# speedup vs baseline: 1.0123x; 1.0042x over previous
; __global__ void __launch_bounds__(NTHR) fwd_megakernel(Params p) {
;     ...
;   run_phase<0>(p); grid.sync();
.LBB0_73:
	s_or_b64 exec, exec, s[2:3]
	v_lshrrev_b32_e32 v1, 20, v0
	v_lshrrev_b32_e32 v0, 10, v0
	v_or_b32_e32 v0, v0, v1
	s_movk_i32 s0, 0x3ff
	v_and_or_b32 v0, v0, s0, v230
	s_waitcnt vmcnt(0) lgkmcnt(0)
	s_barrier
	v_cmp_eq_u32_e64 s[2:3], 0, v0
	s_mov_b64 s[0:1], exec
	s_nop 0
	v_writelane_b32 v255, s2, 1
	s_nop 1
	v_writelane_b32 v255, s3, 2
	s_and_b64 s[2:3], s[0:1], s[2:3]
	s_mov_b64 exec, s[2:3]
	s_cbranch_execz .LBB0_83
	v_readlane_b32 s2, v254, 24
	v_readlane_b32 s3, v254, 25
	s_nop 3
	s_add_u32 s2, s2, 0x10000000
	s_addc_u32 s3, s3, 0
	v_mov_b32_e32 v2, 0
	s_nop 3
	global_store_dword v2, v2, s[2:3] sc0 sc1
	global_store_dword v2, v2, s[2:3] offset:256 sc0 sc1
	global_store_dword v2, v2, s[2:3] offset:512 sc0 sc1
	global_store_dword v2, v2, s[2:3] offset:768 sc0 sc1
	global_store_dword v2, v2, s[2:3] offset:1024 sc0 sc1
	global_store_dword v2, v2, s[2:3] offset:1280 sc0 sc1
	global_store_dword v2, v2, s[2:3] offset:1536 sc0 sc1
	global_store_dword v2, v2, s[2:3] offset:1792 sc0 sc1
	global_store_dword v2, v2, s[2:3] offset:2048 sc0 sc1
	buffer_wbl2 sc1
	s_waitcnt vmcnt(0)
	s_load_dwordx2 s[2:3], s[72:73], 0x58
	v_mov_b32_e32 v2, 0
	s_mov_b64 s[4:5], exec
	v_mbcnt_lo_u32_b32 v1, s4, 0
	v_mbcnt_hi_u32_b32 v1, s5, v1
	s_waitcnt lgkmcnt(0)
	global_load_dword v0, v2, s[2:3] offset:40
	v_cmp_eq_u32_e32 vcc, 0, v1
	s_and_saveexec_b64 s[6:7], vcc
	s_cbranch_execz .LBB0_76
	s_bcnt1_i32_b64 s4, s[4:5]
	v_mov_b32_e32 v3, s4
	global_atomic_add v3, v2, v3, s[2:3] offset:32 sc0

; #define WAIT_V(n) asm volatile("s_waitcnt vmcnt(" #n ")":::"memory")
; #define BAR __builtin_amdgcn_s_barrier()
; #define STAGE_A(b,h,kt) do{ unsigned char* _d = SA(b,h) + wbase; \
;     if constexpr (BLK) { const char* _s = baseA + ((size_t)(h)*(K/64) + (kt)) * 16384; GLDS(_s + voa, _d); GLDS(_s + 8192 + voa, _d + 8192); } \
;     else { const char* _s = baseA + ((size_t)(h)*128*K + (kt)*64) * 2; GLDS(_s + voa, _d); GLDS(_s + (size_t)128*K + voa, _d + 8192); } }while(0)
; #define STAGE_B(b,h,kt) do{ unsigned char* _d = SB(b,h) + wbase; \
;     if constexpr (BLK) { const char* _s = ((h)?baseB1:baseB0) + (size_t)(kt) * 16384; GLDS(_s + voa, _d); GLDS(_s + 8192 + voa, _d + 8192); } \
;     else { const char* _s = ((h)?baseB1:baseB0) + (kt)*128; GLDS(_s + voa, _d); GLDS(_s + (size_t)128*K + voa, _d + 8192); } }while(0)
; template <int K, int EPI, bool MIX = false>
; __device__ __forceinline__ void gemm_phase(const Params& p, const u16* __restrict__ A, const u16* __restrict__ Bt,
;                            const float* __restrict__ rs_in, float* __restrict__ ssq_out, float alpha, bool rev = false) {
;     ...
;   int tid = threadIdx.x;
;   asm volatile("" : "+v"(tid));
;   const int wid = __builtin_amdgcn_readfirstlane(tid >> 6);
;   const int lane = tid & 63, wr = wid >> 2, wc = wid & 3, fr = lane & 15, fq = lane >> 4;
;   const int wbase = wid * 1024;
;   int koff[2];
;   koff[0] = lds_off32(fr, fq); koff[1] = lds_off32(fr, 4 + fq);
;   int it = 0;
;   int id = item_id(0);
;   if (id >= ntiles) return;
;   if (rev) id = ntiles - 1 - id;
;   int pm, pn;
;   const char *baseA, *baseB0, *baseB1;
;   unsigned voa;
;   {
;     const int R = tid >> 3, C = ((tid & 7) ^ ((R >> 1) & 7)) * 8;
;     voa = (unsigned)(R * (BLK ? 64 : K) + C) * 2u;
;   }
;     ...
;   SETUP_TILE();
;   STAGE_B(0,0,0); STAGE_A(0,0,0); STAGE_B(0,1,0); STAGE_A(0,1,0);
;   if (wr == 1) BAR;
;   WAIT_V(4); BAR;
;   STAGE_B(1,0,1); STAGE_A(1,0,1); STAGE_B(1,1,1);
;   WAIT_V(6); BAR;
.LBB0_86:
	s_add_i32 s44, s22, 0x18000
	s_mov_b64 s[14:15], 0x80
	v_lshl_add_u64 v[10:11], v[0:1], 0, s[14:15]
	s_mov_b32 m0, s44
	s_mov_b64 s[16:17], 0x40080
	s_add_i32 s45, s22, 0x1a000
	s_waitcnt vmcnt(4)
	s_barrier
	global_load_lds_dwordx4 v[10:11], off
	v_lshl_add_u64 v[0:1], v[0:1], 0, s[16:17]
	s_mov_b32 m0, s45
	s_add_i32 s46, s22, 0x8000
	global_load_lds_dwordx4 v[0:1], off
	v_lshl_add_u64 v[0:1], v[2:3], 0, s[14:15]
	s_mov_b32 m0, s46
	s_add_i32 s47, s22, 0xa000
	global_load_lds_dwordx4 v[0:1], off
	v_lshl_add_u64 v[0:1], v[2:3], 0, s[16:17]
	s_mov_b32 m0, s47
	s_add_i32 s48, s22, 0x1c000
	global_load_lds_dwordx4 v[0:1], off
	v_lshl_add_u64 v[0:1], v[4:5], 0, s[14:15]
	s_mov_b32 m0, s48
	s_add_i32 s49, s22, 0x1e000
	global_load_lds_dwordx4 v[0:1], off
	v_lshl_add_u64 v[0:1], v[4:5], 0, s[16:17]
	s_mov_b32 m0, s49
	s_and_b32 s20, s18, 3
	global_load_lds_dwordx4 v[0:1], off
	s_lshl_b32 s18, s20, 12
	s_or_b32 s24, s18, 0x10000
	s_lshl_b32 s25, s5, 13
	s_or_b32 s26, s18, 0x14000
	s_or_b32 s28, s18, 0x18000
	s_or_b32 s29, s18, 0x1c000
	s_lshl_b32 s50, s5, 6
	v_and_b32_e32 v221, 15, v8
	v_bfe_u32 v0, v8, 4, 2
	v_bfe_u32 v2, v8, 1, 3
	s_cmpk_lt_u32 s4, 0x100
	v_lshlrev_b32_e32 v1, 7, v221
	v_xor_b32_e32 v3, v0, v2
	v_bitop3_b32 v0, v0, v2, 4 bitop3:0x36
	s_waitcnt vmcnt(6)
	s_cselect_b64 s[18:19], -1, 0
	s_lshl_b32 s51, s20, 5
	v_lshl_or_b32 v3, v3, 4, v1
	v_lshl_or_b32 v0, v0, 4, v1
	s_and_b32 s4, s51, 32
	s_mov_b32 s21, 0
	v_and_b32_e32 v220, 63, v8
	v_add_u32_e32 v212, v7, v6
	v_mov_b32_e32 v213, v211
	v_add_u32_e32 v222, s24, v3
	v_add_u32_e32 v223, s24, v0
	v_add_u32_e32 v224, s25, v3
	v_add_u32_e32 v225, s25, v0
	s_add_i32 s74, s22, 0xc000
	s_add_i32 s75, s22, 0xe000
	v_add_u32_e32 v226, s26, v3
	v_add_u32_e32 v227, s26, v0
	s_mov_b64 s[24:25], 0x100
	s_mov_b64 s[26:27], 0x40100
	v_add_u32_e32 v228, s28, v3
	v_add_u32_e32 v229, s28, v0
	v_add_u32_e32 v232, s29, v3
	v_add_u32_e32 v233, s29, v0
	s_mov_b64 s[28:29], 0x180
	s_mov_b64 s[36:37], 0x40180
	v_mov_b32_e32 v234, 0x358637bd
	s_mov_b32 s78, 0x800000
	s_lshl_b32 s20, s4, 1
	s_mov_b32 s79, s21
	v_readlane_b32 s76, v255, 6
	s_barrier
	s_mov_b64 vcc, exec
	s_branch .LBB0_88

; #define SCHED __builtin_amdgcn_sched_barrier(0)
; template <int K, int EPI, bool MIX = false>
; __device__ __forceinline__ void gemm_phase(const Params& p, const u16* __restrict__ A, const u16* __restrict__ Bt,
;                            const float* __restrict__ rs_in, float* __restrict__ ssq_out, float alpha, bool rev = false) {
;     ...
;     f32x4 acc[2][2][4][2];
; #pragma unroll
;     for (int a = 0; a < 2; ++a)
; #pragma unroll
;       for (int b = 0; b < 2; ++b)
; #pragma unroll
;         for (int m = 0; m < 4; ++m)
; #pragma unroll
;           for (int n = 0; n < 2; ++n) acc[a][b][m][n] = f32x4{0.f, 0.f, 0.f, 0.f};
;     bf16x8 At[4][2], B0[2][2], B1[2][2];
;     asm volatile("" ::: "memory");
;     SCHED;
.LBB0_88:
	s_mov_b32 s80, s40
	v_mov_b32_e32 v0, 0
	s_mov_b32 s81, -2
	s_mov_b64 s[4:5], s[8:9]
	s_mov_b64 s[38:39], s[0:1]
	s_mov_b64 s[40:41], s[6:7]
	v_mov_b32_e32 v1, v0
	v_mov_b32_e32 v2, v0
	v_mov_b32_e32 v3, v0
	v_mov_b32_e32 v4, v0
	v_mov_b32_e32 v5, v0
	v_mov_b32_e32 v6, v0
	v_mov_b32_e32 v7, v0
	v_mov_b32_e32 v8, v0
	v_mov_b32_e32 v9, v0
	v_mov_b32_e32 v10, v0
	v_mov_b32_e32 v11, v0
	v_mov_b32_e32 v12, v0
	v_mov_b32_e32 v13, v0
	v_mov_b32_e32 v14, v0
	v_mov_b32_e32 v15, v0
	v_mov_b32_e32 v16, v0
	v_mov_b32_e32 v17, v0
	v_mov_b32_e32 v18, v0
	v_mov_b32_e32 v19, v0
	v_mov_b32_e32 v20, v0
	v_mov_b32_e32 v21, v0
	v_mov_b32_e32 v22, v0
	v_mov_b32_e32 v23, v0
	v_mov_b32_e32 v24, v0
	v_mov_b32_e32 v25, v0
	v_mov_b32_e32 v26, v0
	v_mov_b32_e32 v27, v0
	v_mov_b32_e32 v28, v0
	v_mov_b32_e32 v29, v0
	v_mov_b32_e32 v30, v0
	v_mov_b32_e32 v31, v0
	v_mov_b32_e32 v56, v0
	v_mov_b32_e32 v57, v0
	v_mov_b32_e32 v58, v0
	v_mov_b32_e32 v59, v0
	v_mov_b32_e32 v68, v0
	v_mov_b32_e32 v69, v0
	v_mov_b32_e32 v70, v0
	v_mov_b32_e32 v71, v0
	v_mov_b32_e32 v72, v0
	v_mov_b32_e32 v73, v0
	v_mov_b32_e32 v74, v0
	v_mov_b32_e32 v75, v0
	v_mov_b32_e32 v76, v0
	v_mov_b32_e32 v77, v0
	v_mov_b32_e32 v78, v0
	v_mov_b32_e32 v79, v0
	v_mov_b32_e32 v80, v0
	v_mov_b32_e32 v81, v0
	v_mov_b32_e32 v82, v0
	v_mov_b32_e32 v83, v0
	v_mov_b32_e32 v84, v0
	v_mov_b32_e32 v85, v0
	v_mov_b32_e32 v86, v0
	v_mov_b32_e32 v87, v0
	v_mov_b32_e32 v88, v0
	v_mov_b32_e32 v89, v0
	v_mov_b32_e32 v90, v0
	v_mov_b32_e32 v91, v0
	v_mov_b32_e32 v92, v0
	v_mov_b32_e32 v93, v0
	v_mov_b32_e32 v94, v0
	v_mov_b32_e32 v95, v0
	v_mov_b32_e32 v96, v0
	v_mov_b32_e32 v97, v0
	v_mov_b32_e32 v98, v0
	v_mov_b32_e32 v99, v0
	v_mov_b32_e32 v100, v0
	v_mov_b32_e32 v101, v0
	v_mov_b32_e32 v102, v0
	v_mov_b32_e32 v103, v0
	v_mov_b32_e32 v104, v0
	v_mov_b32_e32 v105, v0
	v_mov_b32_e32 v106, v0
	v_mov_b32_e32 v107, v0
	v_mov_b32_e32 v108, v0
	v_mov_b32_e32 v109, v0
	v_mov_b32_e32 v110, v0
	v_mov_b32_e32 v111, v0
	v_mov_b32_e32 v112, v0
	v_mov_b32_e32 v113, v0
	v_mov_b32_e32 v114, v0
	v_mov_b32_e32 v115, v0
	v_mov_b32_e32 v116, v0
	v_mov_b32_e32 v117, v0
	v_mov_b32_e32 v118, v0
	v_mov_b32_e32 v119, v0
	v_mov_b32_e32 v120, v0
	v_mov_b32_e32 v121, v0
	v_mov_b32_e32 v122, v0
	v_mov_b32_e32 v123, v0
	v_mov_b32_e32 v124, v0
	v_mov_b32_e32 v125, v0
	v_mov_b32_e32 v126, v0
	v_mov_b32_e32 v127, v0
	v_mov_b32_e32 v32, v0
	v_mov_b32_e32 v33, v0
	v_mov_b32_e32 v34, v0
	v_mov_b32_e32 v35, v0
	v_mov_b32_e32 v36, v0
	v_mov_b32_e32 v37, v0
	v_mov_b32_e32 v38, v0
	v_mov_b32_e32 v39, v0
	v_mov_b32_e32 v40, v0
	v_mov_b32_e32 v41, v0
	v_mov_b32_e32 v42, v0
	v_mov_b32_e32 v43, v0
	v_mov_b32_e32 v44, v0
	v_mov_b32_e32 v45, v0
	v_mov_b32_e32 v46, v0
	v_mov_b32_e32 v47, v0
	v_mov_b32_e32 v48, v0
	v_mov_b32_e32 v49, v0
	v_mov_b32_e32 v50, v0
	v_mov_b32_e32 v51, v0
	v_mov_b32_e32 v52, v0
	v_mov_b32_e32 v53, v0
	v_mov_b32_e32 v54, v0
	v_mov_b32_e32 v55, v0
	v_mov_b32_e32 v60, v0
	v_mov_b32_e32 v61, v0
	v_mov_b32_e32 v62, v0
	v_mov_b32_e32 v63, v0
	v_mov_b32_e32 v64, v0
	v_mov_b32_e32 v65, v0
	v_mov_b32_e32 v66, v0
	v_mov_b32_e32 v67, v0
	s_cbranch_vccnz .Llate_p1_done
	s_barrier
.Llate_p1_done:
.LBB0_89:
	ds_read_b128 v[128:131], v222
	ds_read_b128 v[132:135], v222 offset:2048
	ds_read_b128 v[136:139], v223
	ds_read_b128 v[140:143], v223 offset:2048
	v_lshl_add_u64 v[192:193], s[38:39], 0, v[212:213]
	s_mov_b64 s[82:83], 0x80080
	s_mov_b32 m0, s74
	v_lshl_add_u64 v[176:177], v[192:193], 0, s[82:83]
	s_mov_b64 s[82:83], 0xc0080
	ds_read_b128 v[144:147], v224
	ds_read_b128 v[148:151], v224 offset:2048
	ds_read_b128 v[152:155], v225
	ds_read_b128 v[156:159], v225 offset:2048
	ds_read_b128 v[160:163], v224 offset:4096
	ds_read_b128 v[164:167], v224 offset:6144
	ds_read_b128 v[168:171], v225 offset:4096
	ds_read_b128 v[172:175], v225 offset:6144
	global_load_lds_dwordx4 v[176:177], off
	v_lshl_add_u64 v[176:177], v[192:193], 0, s[82:83]
	s_mov_b32 m0, s75
	s_nop 0
	global_load_lds_dwordx4 v[176:177], off
	s_waitcnt lgkmcnt(8)
	s_barrier
	s_waitcnt lgkmcnt(0)
	s_setprio 1
	s_waitcnt lgkmcnt(0)
	v_mfma_f32_16x16x32_bf16 v[124:127], v[128:131], v[144:147], v[124:127]
	v_mfma_f32_16x16x32_bf16 v[120:123], v[132:135], v[144:147], v[120:123]
	v_mfma_f32_16x16x32_bf16 v[116:119], v[128:131], v[148:151], v[116:119]
	v_mfma_f32_16x16x32_bf16 v[112:115], v[132:135], v[148:151], v[112:115]
	v_mfma_f32_16x16x32_bf16 v[108:111], v[128:131], v[160:163], v[108:111]
	v_mfma_f32_16x16x32_bf16 v[104:107], v[132:135], v[160:163], v[104:107]
	v_mfma_f32_16x16x32_bf16 v[100:103], v[128:131], v[164:167], v[100:103]
	v_mfma_f32_16x16x32_bf16 v[96:99], v[132:135], v[164:167], v[96:99]
	v_mfma_f32_16x16x32_bf16 v[124:127], v[136:139], v[152:155], v[124:127]
	v_mfma_f32_16x16x32_bf16 v[120:123], v[140:143], v[152:155], v[120:123]
	v_mfma_f32_16x16x32_bf16 v[116:119], v[136:139], v[156:159], v[116:119]
	v_mfma_f32_16x16x32_bf16 v[112:115], v[140:143], v[156:159], v[112:115]
	v_mfma_f32_16x16x32_bf16 v[108:111], v[136:139], v[168:171], v[108:111]
	v_mfma_f32_16x16x32_bf16 v[104:107], v[140:143], v[168:171], v[104:107]
	v_mfma_f32_16x16x32_bf16 v[100:103], v[136:139], v[172:175], v[100:103]
	v_mfma_f32_16x16x32_bf16 v[96:99], v[140:143], v[172:175], v[96:99]
	s_setprio 0
	s_barrier
	v_lshl_add_u64 v[194:195], s[40:41], 0, v[212:213]
	s_mov_b32 m0, s30
	v_lshl_add_u64 v[196:197], v[194:195], 0, s[24:25]
	ds_read_b128 v[176:179], v226
	ds_read_b128 v[180:183], v226 offset:2048
	ds_read_b128 v[184:187], v227
	ds_read_b128 v[188:191], v227 offset:2048
	global_load_lds_dwordx4 v[196:197], off
	v_lshl_add_u64 v[196:197], v[194:195], 0, s[26:27]
	s_mov_b32 m0, s31
	s_nop 0
	global_load_lds_dwordx4 v[196:197], off
	s_barrier
	s_waitcnt lgkmcnt(0)
	s_setprio 1
	s_waitcnt lgkmcnt(0)
	v_mfma_f32_16x16x32_bf16 v[92:95], v[176:179], v[144:147], v[92:95]
	v_mfma_f32_16x16x32_bf16 v[88:91], v[180:183], v[144:147], v[88:91]
	v_mfma_f32_16x16x32_bf16 v[84:87], v[176:179], v[148:151], v[84:87]
	v_mfma_f32_16x16x32_bf16 v[80:83], v[180:183], v[148:151], v[80:83]
	v_mfma_f32_16x16x32_bf16 v[76:79], v[176:179], v[160:163], v[76:79]
	v_mfma_f32_16x16x32_bf16 v[72:75], v[180:183], v[160:163], v[72:75]
	v_mfma_f32_16x16x32_bf16 v[68:71], v[176:179], v[164:167], v[68:71]
	v_mfma_f32_16x16x32_bf16 v[56:59], v[180:183], v[164:167], v[56:59]
	v_mfma_f32_16x16x32_bf16 v[92:95], v[184:187], v[152:155], v[92:95]
	v_mfma_f32_16x16x32_bf16 v[88:91], v[188:191], v[152:155], v[88:91]
	v_mfma_f32_16x16x32_bf16 v[84:87], v[184:187], v[156:159], v[84:87]
	v_mfma_f32_16x16x32_bf16 v[80:83], v[188:191], v[156:159], v[80:83]
	v_mfma_f32_16x16x32_bf16 v[76:79], v[184:187], v[168:171], v[76:79]
	v_mfma_f32_16x16x32_bf16 v[72:75], v[188:191], v[168:171], v[72:75]
	v_mfma_f32_16x16x32_bf16 v[68:71], v[184:187], v[172:175], v[68:71]
	v_mfma_f32_16x16x32_bf16 v[56:59], v[188:191], v[172:175], v[56:59]
	s_setprio 0
	s_mov_b32 m0, s22
	v_lshl_add_u64 v[196:197], v[192:193], 0, s[24:25]
	s_barrier
	ds_read_b128 v[144:147], v224 offset:16384
	ds_read_b128 v[148:151], v224 offset:18432
	ds_read_b128 v[152:155], v225 offset:16384
	ds_read_b128 v[156:159], v225 offset:18432
	ds_read_b128 v[160:163], v224 offset:20480
	ds_read_b128 v[164:167], v224 offset:22528
	ds_read_b128 v[168:171], v225 offset:20480
	ds_read_b128 v[172:175], v225 offset:22528
	global_load_lds_dwordx4 v[196:197], off
	v_lshl_add_u64 v[196:197], v[192:193], 0, s[26:27]
	s_mov_b32 m0, s33
	s_nop 0
	global_load_lds_dwordx4 v[196:197], off
	s_barrier
	s_waitcnt lgkmcnt(0)
	s_setprio 1
	s_waitcnt lgkmcnt(0)
	v_mfma_f32_16x16x32_bf16 v[28:31], v[128:131], v[144:147], v[28:31]
	v_mfma_f32_16x16x32_bf16 v[24:27], v[132:135], v[144:147], v[24:27]
	v_mfma_f32_16x16x32_bf16 v[20:23], v[128:131], v[148:151], v[20:23]
	v_mfma_f32_16x16x32_bf16 v[16:19], v[132:135], v[148:151], v[16:19]
	v_mfma_f32_16x16x32_bf16 v[12:15], v[128:131], v[160:163], v[12:15]
	v_mfma_f32_16x16x32_bf16 v[8:11], v[132:135], v[160:163], v[8:11]
	v_mfma_f32_16x16x32_bf16 v[4:7], v[128:131], v[164:167], v[4:7]
	v_mfma_f32_16x16x32_bf16 v[0:3], v[132:135], v[164:167], v[0:3]
	v_mfma_f32_16x16x32_bf16 v[28:31], v[136:139], v[152:155], v[28:31]
	v_mfma_f32_16x16x32_bf16 v[24:27], v[140:143], v[152:155], v[24:27]
	v_mfma_f32_16x16x32_bf16 v[20:23], v[136:139], v[156:159], v[20:23]
	v_mfma_f32_16x16x32_bf16 v[16:19], v[140:143], v[156:159], v[16:19]
	v_mfma_f32_16x16x32_bf16 v[12:15], v[136:139], v[168:171], v[12:15]
	v_mfma_f32_16x16x32_bf16 v[8:11], v[140:143], v[168:171], v[8:11]
	v_mfma_f32_16x16x32_bf16 v[4:7], v[136:139], v[172:175], v[4:7]
	v_mfma_f32_16x16x32_bf16 v[0:3], v[140:143], v[172:175], v[0:3]
	s_setprio 0
	s_barrier
	v_lshl_add_u64 v[196:197], s[4:5], 0, v[212:213]
	s_mov_b32 m0, s34
	v_lshl_add_u64 v[128:129], v[196:197], 0, s[24:25]
	global_load_lds_dwordx4 v[128:129], off
	v_lshl_add_u64 v[128:129], v[196:197], 0, s[26:27]
	s_mov_b32 m0, s35
	s_nop 0
	global_load_lds_dwordx4 v[128:129], off
	s_waitcnt vmcnt(6)
	s_barrier
	s_setprio 1
	v_mfma_f32_16x16x32_bf16 v[32:35], v[176:179], v[144:147], v[32:35]
	v_mfma_f32_16x16x32_bf16 v[36:39], v[180:183], v[144:147], v[36:39]
	v_mfma_f32_16x16x32_bf16 v[40:43], v[176:179], v[148:151], v[40:43]
	v_mfma_f32_16x16x32_bf16 v[44:47], v[180:183], v[148:151], v[44:47]
	v_mfma_f32_16x16x32_bf16 v[48:51], v[176:179], v[160:163], v[48:51]
	v_mfma_f32_16x16x32_bf16 v[52:55], v[180:183], v[160:163], v[52:55]
	v_mfma_f32_16x16x32_bf16 v[60:63], v[176:179], v[164:167], v[60:63]
	v_mfma_f32_16x16x32_bf16 v[64:67], v[180:183], v[164:167], v[64:67]
	v_mfma_f32_16x16x32_bf16 v[32:35], v[184:187], v[152:155], v[32:35]
	v_mfma_f32_16x16x32_bf16 v[36:39], v[188:191], v[152:155], v[36:39]
	v_mfma_f32_16x16x32_bf16 v[40:43], v[184:187], v[156:159], v[40:43]
	v_mfma_f32_16x16x32_bf16 v[44:47], v[188:191], v[156:159], v[44:47]
	v_mfma_f32_16x16x32_bf16 v[48:51], v[184:187], v[168:171], v[48:51]
	v_mfma_f32_16x16x32_bf16 v[52:55], v[188:191], v[168:171], v[52:55]
	v_mfma_f32_16x16x32_bf16 v[60:63], v[184:187], v[172:175], v[60:63]
	v_mfma_f32_16x16x32_bf16 v[64:67], v[188:191], v[172:175], v[64:67]
	s_setprio 0
	s_barrier
	ds_read_b128 v[128:131], v228
	ds_read_b128 v[132:135], v228 offset:2048
	ds_read_b128 v[136:139], v229
	ds_read_b128 v[140:143], v229 offset:2048
	s_mov_b64 s[82:83], 0x80100
	s_mov_b32 m0, s42
	v_lshl_add_u64 v[176:177], v[192:193], 0, s[82:83]
	s_mov_b64 s[82:83], 0xc0100
	ds_read_b128 v[144:147], v224 offset:32768
	ds_read_b128 v[148:151], v224 offset:34816
	ds_read_b128 v[152:155], v225 offset:32768
	ds_read_b128 v[156:159], v225 offset:34816
	ds_read_b128 v[160:163], v224 offset:36864
	ds_read_b128 v[164:167], v224 offset:38912
	ds_read_b128 v[168:171], v225 offset:36864
	ds_read_b128 v[172:175], v225 offset:38912
	global_load_lds_dwordx4 v[176:177], off
	v_lshl_add_u64 v[176:177], v[192:193], 0, s[82:83]
	s_mov_b32 m0, s43
	s_nop 0
	global_load_lds_dwordx4 v[176:177], off
	s_waitcnt lgkmcnt(8)
	s_barrier
	s_waitcnt lgkmcnt(0)
	s_setprio 1
	s_waitcnt lgkmcnt(0)
	v_mfma_f32_16x16x32_bf16 v[124:127], v[128:131], v[144:147], v[124:127]
	v_mfma_f32_16x16x32_bf16 v[120:123], v[132:135], v[144:147], v[120:123]
	v_mfma_f32_16x16x32_bf16 v[116:119], v[128:131], v[148:151], v[116:119]
	v_mfma_f32_16x16x32_bf16 v[112:115], v[132:135], v[148:151], v[112:115]
	v_mfma_f32_16x16x32_bf16 v[108:111], v[128:131], v[160:163], v[108:111]
	v_mfma_f32_16x16x32_bf16 v[104:107], v[132:135], v[160:163], v[104:107]
	v_mfma_f32_16x16x32_bf16 v[100:103], v[128:131], v[164:167], v[100:103]
	v_mfma_f32_16x16x32_bf16 v[96:99], v[132:135], v[164:167], v[96:99]
	v_mfma_f32_16x16x32_bf16 v[124:127], v[136:139], v[152:155], v[124:127]
	v_mfma_f32_16x16x32_bf16 v[120:123], v[140:143], v[152:155], v[120:123]
	v_mfma_f32_16x16x32_bf16 v[116:119], v[136:139], v[156:159], v[116:119]
	v_mfma_f32_16x16x32_bf16 v[112:115], v[140:143], v[156:159], v[112:115]
	v_mfma_f32_16x16x32_bf16 v[108:111], v[136:139], v[168:171], v[108:111]
	v_mfma_f32_16x16x32_bf16 v[104:107], v[140:143], v[168:171], v[104:107]
	v_mfma_f32_16x16x32_bf16 v[100:103], v[136:139], v[172:175], v[100:103]
	v_mfma_f32_16x16x32_bf16 v[96:99], v[140:143], v[172:175], v[96:99]
	s_setprio 0
	s_barrier
	s_mov_b32 m0, s44
	v_lshl_add_u64 v[198:199], v[194:195], 0, s[28:29]
	ds_read_b128 v[176:179], v232
	ds_read_b128 v[180:183], v232 offset:2048
	ds_read_b128 v[184:187], v233
	ds_read_b128 v[188:191], v233 offset:2048
	global_load_lds_dwordx4 v[198:199], off
	v_lshl_add_u64 v[194:195], v[194:195], 0, s[36:37]
	s_mov_b32 m0, s45
	s_nop 0
	global_load_lds_dwordx4 v[194:195], off
	s_barrier
	s_waitcnt lgkmcnt(0)
	s_setprio 1
	s_waitcnt lgkmcnt(0)
	v_mfma_f32_16x16x32_bf16 v[92:95], v[176:179], v[144:147], v[92:95]
	v_mfma_f32_16x16x32_bf16 v[88:91], v[180:183], v[144:147], v[88:91]
	v_mfma_f32_16x16x32_bf16 v[84:87], v[176:179], v[148:151], v[84:87]
	v_mfma_f32_16x16x32_bf16 v[80:83], v[180:183], v[148:151], v[80:83]
	v_mfma_f32_16x16x32_bf16 v[76:79], v[176:179], v[160:163], v[76:79]
	v_mfma_f32_16x16x32_bf16 v[72:75], v[180:183], v[160:163], v[72:75]
	v_mfma_f32_16x16x32_bf16 v[68:71], v[176:179], v[164:167], v[68:71]
	v_mfma_f32_16x16x32_bf16 v[56:59], v[180:183], v[164:167], v[56:59]
	v_mfma_f32_16x16x32_bf16 v[92:95], v[184:187], v[152:155], v[92:95]
	v_mfma_f32_16x16x32_bf16 v[88:91], v[188:191], v[152:155], v[88:91]
	v_mfma_f32_16x16x32_bf16 v[84:87], v[184:187], v[156:159], v[84:87]
	v_mfma_f32_16x16x32_bf16 v[80:83], v[188:191], v[156:159], v[80:83]
	v_mfma_f32_16x16x32_bf16 v[76:79], v[184:187], v[168:171], v[76:79]
	v_mfma_f32_16x16x32_bf16 v[72:75], v[188:191], v[168:171], v[72:75]
	v_mfma_f32_16x16x32_bf16 v[68:71], v[184:187], v[172:175], v[68:71]
	v_mfma_f32_16x16x32_bf16 v[56:59], v[188:191], v[172:175], v[56:59]
	s_setprio 0
	s_mov_b32 m0, s46
	v_lshl_add_u64 v[194:195], v[192:193], 0, s[28:29]
	s_barrier
	ds_read_b128 v[144:147], v224 offset:49152
	ds_read_b128 v[148:151], v224 offset:51200
	ds_read_b128 v[152:155], v225 offset:49152
	ds_read_b128 v[156:159], v225 offset:51200
	ds_read_b128 v[160:163], v224 offset:53248
	ds_read_b128 v[164:167], v224 offset:55296
	ds_read_b128 v[168:171], v225 offset:53248
	ds_read_b128 v[172:175], v225 offset:55296
	global_load_lds_dwordx4 v[194:195], off
	v_lshl_add_u64 v[192:193], v[192:193], 0, s[36:37]
	s_mov_b32 m0, s47
	s_nop 0
	global_load_lds_dwordx4 v[192:193], off
	s_barrier
	s_waitcnt lgkmcnt(0)
	s_setprio 1
	s_waitcnt lgkmcnt(0)
	v_mfma_f32_16x16x32_bf16 v[28:31], v[128:131], v[144:147], v[28:31]
	v_mfma_f32_16x16x32_bf16 v[24:27], v[132:135], v[144:147], v[24:27]
	v_mfma_f32_16x16x32_bf16 v[20:23], v[128:131], v[148:151], v[20:23]
	v_mfma_f32_16x16x32_bf16 v[16:19], v[132:135], v[148:151], v[16:19]
	v_mfma_f32_16x16x32_bf16 v[12:15], v[128:131], v[160:163], v[12:15]
	v_mfma_f32_16x16x32_bf16 v[8:11], v[132:135], v[160:163], v[8:11]
	v_mfma_f32_16x16x32_bf16 v[4:7], v[128:131], v[164:167], v[4:7]
	v_mfma_f32_16x16x32_bf16 v[0:3], v[132:135], v[164:167], v[0:3]
	v_mfma_f32_16x16x32_bf16 v[28:31], v[136:139], v[152:155], v[28:31]
	v_mfma_f32_16x16x32_bf16 v[24:27], v[140:143], v[152:155], v[24:27]
	v_mfma_f32_16x16x32_bf16 v[20:23], v[136:139], v[156:159], v[20:23]
	v_mfma_f32_16x16x32_bf16 v[16:19], v[140:143], v[156:159], v[16:19]
	v_mfma_f32_16x16x32_bf16 v[12:15], v[136:139], v[168:171], v[12:15]
	v_mfma_f32_16x16x32_bf16 v[8:11], v[140:143], v[168:171], v[8:11]
	v_mfma_f32_16x16x32_bf16 v[4:7], v[136:139], v[172:175], v[4:7]
	v_mfma_f32_16x16x32_bf16 v[0:3], v[140:143], v[172:175], v[0:3]
	s_setprio 0
	s_barrier
	s_mov_b32 m0, s48
	v_lshl_add_u64 v[128:129], v[196:197], 0, s[28:29]
	global_load_lds_dwordx4 v[128:129], off
	v_lshl_add_u64 v[128:129], v[196:197], 0, s[36:37]
	s_mov_b32 m0, s49
	s_nop 0
	global_load_lds_dwordx4 v[128:129], off
	s_waitcnt vmcnt(6)
	s_barrier
; #define LDA(dst,b,h) _Pragma("unroll") for(int m=0;m<4;++m) _Pragma("unroll") for(int k=0;k<2;++k) \
;     dst[m][k]=*reinterpret_cast<const bf16x8*>(SA(b,h)+(wr*64+m*16)*128+koff[k])
; #define LDB(dst,b,h) _Pragma("unroll") for(int n=0;n<2;++n) _Pragma("unroll") for(int k=0;k<2;++k) \
;     dst[n][k]=*reinterpret_cast<const bf16x8*>(SB(b,h)+(wc*32+n*16)*128+koff[k])
; #define MMA(ai,bj,Af,Bf) do{__builtin_amdgcn_s_setprio(1); \
;     _Pragma("unroll") for(int m=0;m<4;++m) _Pragma("unroll") for(int n=0;n<2;++n) _Pragma("unroll") for(int k=0;k<2;++k) \
;       acc[ai][bj][m][n]=__builtin_amdgcn_mfma_f32_16x16x32_bf16(Bf[n][k],Af[m][k],acc[ai][bj][m][n],0,0,0); \
;     __builtin_amdgcn_s_setprio(0);}while(0)
; #define WAIT_L(n) asm volatile("s_waitcnt lgkmcnt(" #n ")":::"memory")
; #define BAR __builtin_amdgcn_s_barrier()
; #define SCHED __builtin_amdgcn_sched_barrier(0)
; #define STAGE_A(b,h,kt) do{ unsigned char* _d = SA(b,h) + wbase; \
;     if constexpr (BLK) { const char* _s = baseA + ((size_t)(h)*(K/64) + (kt)) * 16384; GLDS(_s + voa, _d); GLDS(_s + 8192 + voa, _d + 8192); } \
;     else { const char* _s = baseA + ((size_t)(h)*128*K + (kt)*64) * 2; GLDS(_s + voa, _d); GLDS(_s + (size_t)128*K + voa, _d + 8192); } }while(0)
; template <int K, int EPI, bool MIX = false>
; __device__ __forceinline__ void gemm_phase(const Params& p, const u16* __restrict__ A, const u16* __restrict__ Bt,
;                            const float* __restrict__ rs_in, float* __restrict__ ssq_out, float alpha, bool rev = false) {
;     ...
;       for (int t = 0; t < nt - 2; t += 2) KBODY(t);
;     }
;     ...
;     const int cpm = pm, cpn = pn;
;     float rsq[2][4];
;     if constexpr (EPI == EPI_SWIGLU || EPI == EPI_Z || MIX) {
;       const float* rsrc = MIX ? p.ssqb : rs_in;
;       int fr_p = fr;
;       asm volatile("" : "+v"(fr_p));
; #pragma unroll
;       for (int ai = 0; ai < 2; ++ai)
; #pragma unroll
;         for (int m = 0; m < 4; ++m) rsq[ai][m] = rsrc[cpm * 256 + ai * 128 + wr * 64 + m * 16 + fr_p];
;     }
;     ++it;
;     id = item_id(it);
;     const bool more = id < ntiles;
;     if (rev) id = ntiles - 1 - id;
;     {
;       LDB(B0,0,0); SCHED; LDA(At,0,0); STAGE_A(1,1,nt-1);
;       WAIT_L(8); BAR; WAIT_L(0); MMA(0,0,At,B0); BAR; SCHED;
;       if (more) SETUP_TILE();
	s_setprio 1
	v_mfma_f32_16x16x32_bf16 v[32:35], v[176:179], v[144:147], v[32:35]
	v_mfma_f32_16x16x32_bf16 v[36:39], v[180:183], v[144:147], v[36:39]
	v_mfma_f32_16x16x32_bf16 v[40:43], v[176:179], v[148:151], v[40:43]
	v_mfma_f32_16x16x32_bf16 v[44:47], v[180:183], v[148:151], v[44:47]
	v_mfma_f32_16x16x32_bf16 v[48:51], v[176:179], v[160:163], v[48:51]
	v_mfma_f32_16x16x32_bf16 v[52:55], v[180:183], v[160:163], v[52:55]
	v_mfma_f32_16x16x32_bf16 v[60:63], v[176:179], v[164:167], v[60:63]
	v_mfma_f32_16x16x32_bf16 v[64:67], v[180:183], v[164:167], v[64:67]
	v_mfma_f32_16x16x32_bf16 v[32:35], v[184:187], v[152:155], v[32:35]
	v_mfma_f32_16x16x32_bf16 v[36:39], v[188:191], v[152:155], v[36:39]
	v_mfma_f32_16x16x32_bf16 v[40:43], v[184:187], v[156:159], v[40:43]
	v_mfma_f32_16x16x32_bf16 v[44:47], v[188:191], v[156:159], v[44:47]
	v_mfma_f32_16x16x32_bf16 v[48:51], v[184:187], v[168:171], v[48:51]
	v_mfma_f32_16x16x32_bf16 v[52:55], v[188:191], v[168:171], v[52:55]
	v_mfma_f32_16x16x32_bf16 v[60:63], v[184:187], v[172:175], v[60:63]
	v_mfma_f32_16x16x32_bf16 v[64:67], v[188:191], v[172:175], v[64:67]
	s_setprio 0
	s_add_i32 s81, s81, 2
	s_add_u32 s40, s40, 0x100
	s_addc_u32 s41, s41, 0
	s_add_u32 s38, s38, 0x100
	s_addc_u32 s39, s39, 0
	s_add_u32 s4, s4, 0x100
	s_addc_u32 s5, s5, 0
	s_cmp_lt_u32 s81, 28
	s_barrier
	s_cbranch_scc1 .LBB0_89
	v_mov_b32_e32 v128, v221
	s_lshl_b32 s41, s23, 8
	s_add_i32 s41, s41, s50
	v_add_u32_e32 v128, s41, v128
	v_readlane_b32 s52, v254, 32
	v_ashrrev_i32_e32 v129, 31, v128
	v_readlane_b32 s62, v254, 42
	v_readlane_b32 s63, v254, 43
	s_add_i32 s79, s79, 1
	s_mul_i32 s4, s79, s76
	v_lshl_add_u64 v[128:129], v[128:129], 2, s[62:63]
	global_load_dword v210, v[128:129], off
	global_load_dword v241, v[128:129], off offset:64
	global_load_dword v240, v[128:129], off offset:128
	global_load_dword v239, v[128:129], off offset:192
	global_load_dword v238, v[128:129], off offset:512
	global_load_dword v237, v[128:129], off offset:576
	global_load_dword v236, v[128:129], off offset:640
	global_load_dword v235, v[128:129], off offset:704
	ds_read_b128 v[144:147], v222
	ds_read_b128 v[148:151], v222 offset:2048
	ds_read_b128 v[156:159], v223
	ds_read_b128 v[152:155], v223 offset:2048
	s_add_i32 s4, s4, s77
	v_readlane_b32 s53, v254, 33
	v_readlane_b32 s54, v254, 34
	v_readlane_b32 s55, v254, 35
	v_readlane_b32 s56, v254, 36
	v_readlane_b32 s57, v254, 37
	v_readlane_b32 s58, v254, 38
	v_readlane_b32 s59, v254, 39
	v_readlane_b32 s60, v254, 40
	v_readlane_b32 s61, v254, 41
	v_readlane_b32 s64, v254, 44
	v_readlane_b32 s65, v254, 45
	v_readlane_b32 s66, v254, 46
	v_readlane_b32 s67, v254, 47
	v_lshl_add_u64 v[128:129], s[0:1], 0, v[208:209]
	s_mov_b64 s[38:39], 0x80f80
	s_mov_b32 m0, s74
	v_lshl_add_u64 v[130:131], v[128:129], 0, s[38:39]
	s_mov_b64 s[38:39], 0xc0f80
	ds_read_b128 v[160:163], v224
	ds_read_b128 v[164:167], v224 offset:2048
	ds_read_b128 v[188:191], v225
	ds_read_b128 v[180:183], v225 offset:2048
	ds_read_b128 v[168:171], v224 offset:4096
	ds_read_b128 v[172:175], v224 offset:6144
	ds_read_b128 v[184:187], v225 offset:4096
	ds_read_b128 v[176:179], v225 offset:6144
	global_load_lds_dwordx4 v[130:131], off
	v_lshl_add_u64 v[128:129], v[128:129], 0, s[38:39]
	s_mov_b32 m0, s75
	s_nop 0
	global_load_lds_dwordx4 v[128:129], off
	s_waitcnt lgkmcnt(8)
	s_barrier
	s_waitcnt lgkmcnt(0)
	s_setprio 1
	s_waitcnt lgkmcnt(0)
	v_mfma_f32_16x16x32_bf16 v[124:127], v[144:147], v[160:163], v[124:127]
	s_cmpk_lt_i32 s4, 0x2100
	s_cselect_b64 s[38:39], -1, 0
	s_cmpk_gt_i32 s4, 0x20ff
	v_mfma_f32_16x16x32_bf16 v[120:123], v[148:151], v[160:163], v[120:123]
	v_mfma_f32_16x16x32_bf16 v[116:119], v[144:147], v[164:167], v[116:119]
	v_mfma_f32_16x16x32_bf16 v[112:115], v[148:151], v[164:167], v[112:115]
	v_mfma_f32_16x16x32_bf16 v[108:111], v[144:147], v[168:171], v[108:111]
	v_mfma_f32_16x16x32_bf16 v[104:107], v[148:151], v[168:171], v[104:107]
	v_mfma_f32_16x16x32_bf16 v[100:103], v[144:147], v[172:175], v[100:103]
	v_mfma_f32_16x16x32_bf16 v[96:99], v[148:151], v[172:175], v[96:99]
	v_mfma_f32_16x16x32_bf16 v[124:127], v[156:159], v[188:191], v[124:127]
	v_mfma_f32_16x16x32_bf16 v[128:131], v[152:155], v[188:191], v[120:123]
	v_mfma_f32_16x16x32_bf16 v[116:119], v[156:159], v[180:183], v[116:119]
	v_mfma_f32_16x16x32_bf16 v[132:135], v[152:155], v[180:183], v[112:115]
	v_mfma_f32_16x16x32_bf16 v[108:111], v[156:159], v[184:187], v[108:111]
	v_mfma_f32_16x16x32_bf16 v[136:139], v[152:155], v[184:187], v[104:107]
	v_mfma_f32_16x16x32_bf16 v[100:103], v[156:159], v[176:179], v[100:103]
	v_mfma_f32_16x16x32_bf16 v[140:143], v[152:155], v[176:179], v[96:99]
	s_setprio 0
	s_barrier
	s_mov_b32 s40, s80
	s_cbranch_scc1 .LBB0_92
	s_mul_hi_i32 s0, s4, 0x2e8ba2e9
	s_lshr_b32 s1, s0, 31
	s_ashr_i32 s0, s0, 6
	s_add_i32 s0, s0, s1
	s_lshl_b32 s1, s0, 3
	s_mulk_i32 s0, 0xfea0
	s_add_i32 s0, s0, s4
	s_and_b32 s4, s4, 7
	s_or_b32 s23, s1, s4
	s_ashr_i32 s40, s0, 3
	s_lshl_b32 s0, s23, 8
	s_ashr_i32 s1, s0, 31
	s_lshl_b64 s[0:1], s[0:1], 12
	s_add_u32 s0, s90, s0
	s_addc_u32 s1, s91, s1
	s_lshl_b32 s4, s40, 7
	s_ashr_i32 s5, s4, 31
	v_readlane_b32 s52, v254, 16
	s_lshl_b64 s[4:5], s[4:5], 12
	v_readlane_b32 s62, v254, 26
	v_readlane_b32 s63, v254, 27
	s_add_u32 s6, s62, s4
	s_addc_u32 s7, s63, s5
	s_add_u32 s8, s6, 0x1600000
	v_readlane_b32 s76, v255, 6
	s_addc_u32 s9, s7, 0
	v_readlane_b32 s53, v254, 17
	v_readlane_b32 s54, v254, 18
	v_readlane_b32 s55, v254, 19
	v_readlane_b32 s56, v254, 20
	v_readlane_b32 s57, v254, 21
	v_readlane_b32 s58, v254, 22
	v_readlane_b32 s59, v254, 23
	v_readlane_b32 s60, v254, 24
	v_readlane_b32 s61, v254, 25
	v_readlane_b32 s64, v254, 28
	v_readlane_b32 s65, v254, 29
	v_readlane_b32 s66, v254, 30
	v_readlane_b32 s67, v254, 31

; __global__ void __launch_bounds__(NTHR) fwd_megakernel(Params p) {
;     ...
;   run_phase<1>(p); grid.sync();
.LBB0_112:
	s_waitcnt vmcnt(0) lgkmcnt(0)
	s_barrier
	s_mov_b64 s[0:1], exec
	v_readlane_b32 s2, v255, 1
	v_readlane_b32 s3, v255, 2
	s_and_b64 s[2:3], s[0:1], s[2:3]
	s_mov_b64 exec, s[2:3]
	s_cbranch_execz .LBB0_122
	buffer_wbl2 sc1
	s_waitcnt vmcnt(0)
	v_readlane_b32 s2, v254, 24
	v_readlane_b32 s3, v254, 25
	v_readlane_b32 s4, v255, 3
	s_load_dword s5, s[72:73], 0x0
	s_nop 3
	s_add_u32 s2, s2, 0x10000000
	s_addc_u32 s3, s3, 0
	s_and_b32 s4, s4, 7
	s_lshl_b32 s4, s4, 8
	s_add_i32 s4, s4, 0x100
	v_mov_b32_e32 v2, 0
	v_mov_b32_e32 v3, 1
	v_mov_b32_e32 v0, s4
	s_nop 3
	global_atomic_add v3, v2, v3, s[2:3] sc0 sc1
	s_waitcnt lgkmcnt(0)
	s_mul_i32 s5, s5, 1
	s_add_i32 s5, s5, -1
	s_waitcnt vmcnt(0)
	v_readfirstlane_b32 s4, v3
	s_nop 3
	s_cmp_lg_u32 s4, s5
	s_cbranch_scc1 .Lfb1_poll0
	v_mov_b32_e32 v1, 1
	global_atomic_add v2, v1, s[2:3] offset:256 sc1
	global_atomic_add v2, v1, s[2:3] offset:512 sc1
	global_atomic_add v2, v1, s[2:3] offset:768 sc1
	global_atomic_add v2, v1, s[2:3] offset:1024 sc1
	global_atomic_add v2, v1, s[2:3] offset:1280 sc1
	global_atomic_add v2, v1, s[2:3] offset:1536 sc1
	global_atomic_add v2, v1, s[2:3] offset:1792 sc1
	global_atomic_add v2, v1, s[2:3] offset:2048 sc1
	s_branch .Lfb1_done
.Lfb1_poll0:
	s_mov_b32 s6, 0
.Lfb1_poll:
	global_load_dword v1, v0, s[2:3] sc1
	s_waitcnt vmcnt(0)
	v_readfirstlane_b32 s4, v1
	s_nop 3
	s_cmpk_ge_u32 s4, 1
	s_cbranch_scc1 .Lfb1_done
	s_sleep 1
	s_add_u32 s6, s6, 1
	s_cmpk_lt_u32 s6, 0x7fff
	s_cbranch_scc1 .Lfb1_poll

; #define WAIT_V(n) asm volatile("s_waitcnt vmcnt(" #n ")":::"memory")
; #define BAR __builtin_amdgcn_s_barrier()
; #define STAGE_A(b,h,kt) do{ unsigned char* _d = SA(b,h) + wbase; \
;     if constexpr (BLK) { const char* _s = baseA + ((size_t)(h)*(K/64) + (kt)) * 16384; GLDS(_s + voa, _d); GLDS(_s + 8192 + voa, _d + 8192); } \
;     else { const char* _s = baseA + ((size_t)(h)*128*K + (kt)*64) * 2; GLDS(_s + voa, _d); GLDS(_s + (size_t)128*K + voa, _d + 8192); } }while(0)
; #define STAGE_B(b,h,kt) do{ unsigned char* _d = SB(b,h) + wbase; \
;     if constexpr (BLK) { const char* _s = ((h)?baseB1:baseB0) + (size_t)(kt) * 16384; GLDS(_s + voa, _d); GLDS(_s + 8192 + voa, _d + 8192); } \
;     else { const char* _s = ((h)?baseB1:baseB0) + (kt)*128; GLDS(_s + voa, _d); GLDS(_s + (size_t)128*K + voa, _d + 8192); } }while(0)
; template <int K, int EPI, bool MIX = false>
; __device__ __forceinline__ void gemm_phase(const Params& p, const u16* __restrict__ A, const u16* __restrict__ Bt,
;                            const float* __restrict__ rs_in, float* __restrict__ ssq_out, float alpha, bool rev = false) {
;     ...
;   int tid = threadIdx.x;
;   asm volatile("" : "+v"(tid));
;   const int wid = __builtin_amdgcn_readfirstlane(tid >> 6);
;   const int lane = tid & 63, wr = wid >> 2, wc = wid & 3, fr = lane & 15, fq = lane >> 4;
;   const int wbase = wid * 1024;
;   int koff[2];
;   koff[0] = lds_off32(fr, fq); koff[1] = lds_off32(fr, 4 + fq);
;   int it = 0;
;   int id = item_id(0);
;   if (id >= ntiles) return;
;   if (rev) id = ntiles - 1 - id;
;   int pm, pn;
;   const char *baseA, *baseB0, *baseB1;
;   unsigned voa;
;   {
;     const int R = tid >> 3, C = ((tid & 7) ^ ((R >> 1) & 7)) * 8;
;     voa = (unsigned)(R * (BLK ? 64 : K) + C) * 2u;
;   }
;     ...
;   SETUP_TILE();
;   STAGE_B(0,0,0); STAGE_A(0,0,0); STAGE_B(0,1,0); STAGE_A(0,1,0);
;   if (wr == 1) BAR;
;   WAIT_V(4); BAR;
;   STAGE_B(1,0,1); STAGE_A(1,0,1); STAGE_B(1,1,1);
;   WAIT_V(6); BAR;
.LBB0_125:
	s_add_i32 s43, s22, 0x18000
	s_mov_b64 s[14:15], 0x4000
	v_lshl_add_u64 v[8:9], v[0:1], 0, s[14:15]
	s_mov_b32 m0, s43
	s_mov_b64 s[16:17], 0x6000
	s_add_i32 s44, s22, 0x1a000
	s_waitcnt vmcnt(4)
	s_barrier
	global_load_lds_dwordx4 v[8:9], off
	v_lshl_add_u64 v[8:9], v[0:1], 0, s[16:17]
	s_mov_b32 m0, s44
	s_add_i32 s45, s22, 0x8000
	global_load_lds_dwordx4 v[8:9], off
	v_lshl_add_u64 v[8:9], v[2:3], 0, s[14:15]
	s_mov_b32 m0, s45
	s_add_i32 s48, s22, 0xa000
	global_load_lds_dwordx4 v[8:9], off
	v_lshl_add_u64 v[2:3], v[2:3], 0, s[16:17]
	s_mov_b32 m0, s48
	s_add_i32 s49, s22, 0x1c000
	s_mov_b64 s[18:19], 0x164000
	global_load_lds_dwordx4 v[2:3], off
	v_lshl_add_u64 v[2:3], v[0:1], 0, s[18:19]
	s_mov_b32 m0, s49
	s_mov_b64 s[20:21], 0x166000
	s_add_i32 s50, s22, 0x1e000
	global_load_lds_dwordx4 v[2:3], off
	v_lshl_add_u64 v[0:1], v[0:1], 0, s[20:21]
	s_mov_b32 m0, s50
	s_and_b32 s26, s24, 3
	global_load_lds_dwordx4 v[0:1], off
	s_lshl_b32 s24, s26, 12
	v_and_b32_e32 v0, 15, v6
	v_bfe_u32 v1, v6, 4, 2
	v_bfe_u32 v2, v6, 1, 3
	s_or_b32 s28, s24, 0x10000
	s_lshl_b32 s29, s5, 13
	s_or_b32 s36, s24, 0x14000
	s_or_b32 s38, s24, 0x18000
	s_or_b32 s39, s24, 0x1c000
	v_lshlrev_b32_e32 v0, 7, v0
	v_xor_b32_e32 v3, v1, v2
	v_bitop3_b32 v1, v1, v2, 4 bitop3:0x36
	s_waitcnt vmcnt(6)
	s_cmpk_lt_u32 s4, 0x100
	v_lshl_or_b32 v3, v3, 4, v0
	v_lshl_or_b32 v0, v1, 4, v0
	s_cselect_b64 s[24:25], -1, 0
	s_lshl_b32 s4, s26, 5
	s_mov_b32 s27, 0
	v_and_b32_e32 v218, 63, v6
	s_lshl_b32 s51, s5, 6
	v_add_u32_e32 v210, v5, v4
	v_mov_b32_e32 v211, v209
	v_add_u32_e32 v219, s28, v3
	v_add_u32_e32 v220, s28, v0
	v_add_u32_e32 v221, s29, v3
	v_add_u32_e32 v222, s29, v0
	s_add_i32 s74, s22, 0xc000
	s_add_i32 s75, s22, 0xe000
	v_add_u32_e32 v223, s36, v3
	v_add_u32_e32 v224, s36, v0
	s_mov_b64 s[28:29], 0x8000
	s_mov_b64 s[36:37], 0xa000
	v_add_u32_e32 v225, s38, v3
	v_add_u32_e32 v226, s38, v0
	v_add_u32_e32 v227, s39, v3
	v_add_u32_e32 v228, s39, v0
	s_mov_b64 s[38:39], 0xc000
	s_mov_b64 s[40:41], 0xe000
	v_mbcnt_hi_u32_b32 v229, -1, v231
	s_lshl_b32 s26, s4, 1
	s_mov_b32 s78, s27
	s_barrier
	s_mov_b64 vcc, exec
	s_branch .LBB0_127

; #define SCHED __builtin_amdgcn_sched_barrier(0)
; template <int K, int EPI, bool MIX = false>
; __device__ __forceinline__ void gemm_phase(const Params& p, const u16* __restrict__ A, const u16* __restrict__ Bt,
;                            const float* __restrict__ rs_in, float* __restrict__ ssq_out, float alpha, bool rev = false) {
;     ...
;   for (;;) {
;     f32x4 acc[2][2][4][2];
; #pragma unroll
;     for (int a = 0; a < 2; ++a)
; #pragma unroll
;       for (int b = 0; b < 2; ++b)
; #pragma unroll
;         for (int m = 0; m < 4; ++m)
; #pragma unroll
;           for (int n = 0; n < 2; ++n) acc[a][b][m][n] = f32x4{0.f, 0.f, 0.f, 0.f};
;     bf16x8 At[4][2], B0[2][2], B1[2][2];
;     asm volatile("" ::: "memory");
;     SCHED;
.LBB0_127:
	s_mov_b32 s82, s80
	s_mov_b32 s81, s79
	v_mov_b32_e32 v0, 0
	s_mov_b32 s79, -2
	s_mov_b64 s[4:5], s[10:11]
	s_mov_b64 s[46:47], s[2:3]
	s_mov_b64 s[62:63], s[8:9]
	s_waitcnt lgkmcnt(0)
	v_mov_b32_e32 v1, v0
	v_mov_b32_e32 v2, v0
	v_mov_b32_e32 v3, v0
	v_mov_b32_e32 v4, v0
	v_mov_b32_e32 v5, v0
	v_mov_b32_e32 v6, v0
	v_mov_b32_e32 v7, v0
	v_mov_b32_e32 v8, v0
	v_mov_b32_e32 v9, v0
	v_mov_b32_e32 v10, v0
	v_mov_b32_e32 v11, v0
	v_mov_b32_e32 v12, v0
	v_mov_b32_e32 v13, v0
	v_mov_b32_e32 v14, v0
	v_mov_b32_e32 v15, v0
	v_mov_b32_e32 v16, v0
	v_mov_b32_e32 v17, v0
	v_mov_b32_e32 v18, v0
	v_mov_b32_e32 v19, v0
	v_mov_b32_e32 v20, v0
	v_mov_b32_e32 v21, v0
	v_mov_b32_e32 v22, v0
	v_mov_b32_e32 v23, v0
	v_mov_b32_e32 v24, v0
	v_mov_b32_e32 v25, v0
	v_mov_b32_e32 v26, v0
	v_mov_b32_e32 v27, v0
	v_mov_b32_e32 v28, v0
	v_mov_b32_e32 v29, v0
	v_mov_b32_e32 v30, v0
	v_mov_b32_e32 v31, v0
	v_mov_b32_e32 v32, v0
	v_mov_b32_e32 v33, v0
	v_mov_b32_e32 v34, v0
	v_mov_b32_e32 v35, v0
	v_mov_b32_e32 v36, v0
	v_mov_b32_e32 v37, v0
	v_mov_b32_e32 v38, v0
	v_mov_b32_e32 v39, v0
	v_mov_b32_e32 v40, v0
	v_mov_b32_e32 v41, v0
	v_mov_b32_e32 v42, v0
	v_mov_b32_e32 v43, v0
	v_mov_b32_e32 v44, v0
	v_mov_b32_e32 v45, v0
	v_mov_b32_e32 v46, v0
	v_mov_b32_e32 v47, v0
	v_mov_b32_e32 v48, v0
	v_mov_b32_e32 v49, v0
	v_mov_b32_e32 v50, v0
	v_mov_b32_e32 v51, v0
	v_mov_b32_e32 v52, v0
	v_mov_b32_e32 v53, v0
	v_mov_b32_e32 v54, v0
	v_mov_b32_e32 v55, v0
	v_mov_b32_e32 v56, v0
	v_mov_b32_e32 v57, v0
	v_mov_b32_e32 v58, v0
	v_mov_b32_e32 v59, v0
	v_mov_b32_e32 v60, v0
	v_mov_b32_e32 v61, v0
	v_mov_b32_e32 v62, v0
	v_mov_b32_e32 v63, v0
	v_mov_b32_e32 v64, v0
	v_mov_b32_e32 v65, v0
	v_mov_b32_e32 v66, v0
	v_mov_b32_e32 v67, v0
	v_mov_b32_e32 v68, v0
	v_mov_b32_e32 v69, v0
	v_mov_b32_e32 v70, v0
	v_mov_b32_e32 v71, v0
	v_mov_b32_e32 v72, v0
	v_mov_b32_e32 v73, v0
	v_mov_b32_e32 v74, v0
	v_mov_b32_e32 v75, v0
	v_mov_b32_e32 v76, v0
	v_mov_b32_e32 v77, v0
	v_mov_b32_e32 v78, v0
	v_mov_b32_e32 v79, v0
	v_mov_b32_e32 v80, v0
	v_mov_b32_e32 v81, v0
	v_mov_b32_e32 v82, v0
	v_mov_b32_e32 v83, v0
	v_mov_b32_e32 v84, v0
	v_mov_b32_e32 v85, v0
	v_mov_b32_e32 v86, v0
	v_mov_b32_e32 v87, v0
	v_mov_b32_e32 v88, v0
	v_mov_b32_e32 v89, v0
	v_mov_b32_e32 v90, v0
	v_mov_b32_e32 v91, v0
	v_mov_b32_e32 v92, v0
	v_mov_b32_e32 v93, v0
	v_mov_b32_e32 v94, v0
	v_mov_b32_e32 v95, v0
	v_mov_b32_e32 v96, v0
	v_mov_b32_e32 v97, v0
	v_mov_b32_e32 v98, v0
	v_mov_b32_e32 v99, v0
	v_mov_b32_e32 v100, v0
	v_mov_b32_e32 v101, v0
	v_mov_b32_e32 v102, v0
	v_mov_b32_e32 v103, v0
	v_mov_b32_e32 v104, v0
	v_mov_b32_e32 v105, v0
	v_mov_b32_e32 v106, v0
	v_mov_b32_e32 v107, v0
	v_mov_b32_e32 v108, v0
	v_mov_b32_e32 v109, v0
	v_mov_b32_e32 v110, v0
	v_mov_b32_e32 v111, v0
	v_mov_b32_e32 v112, v0
	v_mov_b32_e32 v113, v0
	v_mov_b32_e32 v114, v0
	v_mov_b32_e32 v115, v0
	v_mov_b32_e32 v116, v0
	v_mov_b32_e32 v117, v0
	v_mov_b32_e32 v118, v0
	v_mov_b32_e32 v119, v0
	v_mov_b32_e32 v120, v0
	v_mov_b32_e32 v121, v0
	v_mov_b32_e32 v122, v0
	v_mov_b32_e32 v123, v0
	v_mov_b32_e32 v124, v0
	v_mov_b32_e32 v125, v0
	v_mov_b32_e32 v126, v0
	v_mov_b32_e32 v127, v0
	s_cbranch_vccnz .Llate_p2_done
	s_barrier
.Llate_p2_done:
.LBB0_128:
	ds_read_b128 v[128:131], v219
	ds_read_b128 v[132:135], v219 offset:2048
	ds_read_b128 v[136:139], v220
	ds_read_b128 v[140:143], v220 offset:2048
	v_lshl_add_u64 v[192:193], s[46:47], 0, v[210:211]
	s_mov_b32 m0, s74
	v_lshl_add_u64 v[176:177], v[192:193], 0, s[18:19]
	ds_read_b128 v[144:147], v221
	ds_read_b128 v[148:151], v221 offset:2048
	ds_read_b128 v[152:155], v222
	ds_read_b128 v[156:159], v222 offset:2048
	ds_read_b128 v[160:163], v221 offset:4096
	ds_read_b128 v[164:167], v221 offset:6144
	ds_read_b128 v[168:171], v222 offset:4096
	ds_read_b128 v[172:175], v222 offset:6144
	global_load_lds_dwordx4 v[176:177], off
	v_lshl_add_u64 v[176:177], v[192:193], 0, s[20:21]
	s_mov_b32 m0, s75
	s_nop 0
	global_load_lds_dwordx4 v[176:177], off
	s_waitcnt lgkmcnt(8)
	s_barrier
	s_waitcnt lgkmcnt(0)
	s_setprio 1
	s_waitcnt lgkmcnt(0)
	v_mfma_f32_16x16x32_bf16 v[124:127], v[128:131], v[144:147], v[124:127]
	v_mfma_f32_16x16x32_bf16 v[120:123], v[132:135], v[144:147], v[120:123]
	v_mfma_f32_16x16x32_bf16 v[116:119], v[128:131], v[148:151], v[116:119]
	v_mfma_f32_16x16x32_bf16 v[112:115], v[132:135], v[148:151], v[112:115]
	v_mfma_f32_16x16x32_bf16 v[108:111], v[128:131], v[160:163], v[108:111]
	v_mfma_f32_16x16x32_bf16 v[104:107], v[132:135], v[160:163], v[104:107]
	v_mfma_f32_16x16x32_bf16 v[100:103], v[128:131], v[164:167], v[100:103]
	v_mfma_f32_16x16x32_bf16 v[96:99], v[132:135], v[164:167], v[96:99]
	v_mfma_f32_16x16x32_bf16 v[124:127], v[136:139], v[152:155], v[124:127]
	v_mfma_f32_16x16x32_bf16 v[120:123], v[140:143], v[152:155], v[120:123]
	v_mfma_f32_16x16x32_bf16 v[116:119], v[136:139], v[156:159], v[116:119]
	v_mfma_f32_16x16x32_bf16 v[112:115], v[140:143], v[156:159], v[112:115]
	v_mfma_f32_16x16x32_bf16 v[108:111], v[136:139], v[168:171], v[108:111]
	v_mfma_f32_16x16x32_bf16 v[104:107], v[140:143], v[168:171], v[104:107]
	v_mfma_f32_16x16x32_bf16 v[100:103], v[136:139], v[172:175], v[100:103]
	v_mfma_f32_16x16x32_bf16 v[96:99], v[140:143], v[172:175], v[96:99]
	s_setprio 0
	s_barrier
	v_lshl_add_u64 v[194:195], s[62:63], 0, v[210:211]
	s_mov_b32 m0, s23
	v_lshl_add_u64 v[196:197], v[194:195], 0, s[28:29]
	ds_read_b128 v[176:179], v223
	ds_read_b128 v[180:183], v223 offset:2048
	ds_read_b128 v[184:187], v224
	ds_read_b128 v[188:191], v224 offset:2048
	global_load_lds_dwordx4 v[196:197], off
	v_lshl_add_u64 v[196:197], v[194:195], 0, s[36:37]
	s_mov_b32 m0, s30
	s_nop 0
	global_load_lds_dwordx4 v[196:197], off
	s_barrier
	s_waitcnt lgkmcnt(0)
	s_setprio 1
	s_waitcnt lgkmcnt(0)
	v_mfma_f32_16x16x32_bf16 v[92:95], v[176:179], v[144:147], v[92:95]
	v_mfma_f32_16x16x32_bf16 v[88:91], v[180:183], v[144:147], v[88:91]
	v_mfma_f32_16x16x32_bf16 v[84:87], v[176:179], v[148:151], v[84:87]
	v_mfma_f32_16x16x32_bf16 v[80:83], v[180:183], v[148:151], v[80:83]
	v_mfma_f32_16x16x32_bf16 v[76:79], v[176:179], v[160:163], v[76:79]
	v_mfma_f32_16x16x32_bf16 v[72:75], v[180:183], v[160:163], v[72:75]
	v_mfma_f32_16x16x32_bf16 v[68:71], v[176:179], v[164:167], v[68:71]
	v_mfma_f32_16x16x32_bf16 v[64:67], v[180:183], v[164:167], v[64:67]
	v_mfma_f32_16x16x32_bf16 v[92:95], v[184:187], v[152:155], v[92:95]
	v_mfma_f32_16x16x32_bf16 v[88:91], v[188:191], v[152:155], v[88:91]
	v_mfma_f32_16x16x32_bf16 v[84:87], v[184:187], v[156:159], v[84:87]
	v_mfma_f32_16x16x32_bf16 v[80:83], v[188:191], v[156:159], v[80:83]
	v_mfma_f32_16x16x32_bf16 v[76:79], v[184:187], v[168:171], v[76:79]
	v_mfma_f32_16x16x32_bf16 v[72:75], v[188:191], v[168:171], v[72:75]
	v_mfma_f32_16x16x32_bf16 v[68:71], v[184:187], v[172:175], v[68:71]
	v_mfma_f32_16x16x32_bf16 v[64:67], v[188:191], v[172:175], v[64:67]
	s_setprio 0
	s_mov_b32 m0, s22
	v_lshl_add_u64 v[196:197], v[192:193], 0, s[28:29]
	s_barrier
	ds_read_b128 v[144:147], v221 offset:16384
	ds_read_b128 v[148:151], v221 offset:18432
	ds_read_b128 v[152:155], v222 offset:16384
	ds_read_b128 v[156:159], v222 offset:18432
	ds_read_b128 v[160:163], v221 offset:20480
	ds_read_b128 v[164:167], v221 offset:22528
	ds_read_b128 v[168:171], v222 offset:20480
	ds_read_b128 v[172:175], v222 offset:22528
	global_load_lds_dwordx4 v[196:197], off
	v_lshl_add_u64 v[196:197], v[192:193], 0, s[36:37]
	s_mov_b32 m0, s31
	s_nop 0
	global_load_lds_dwordx4 v[196:197], off
	s_barrier
	s_waitcnt lgkmcnt(0)
	s_setprio 1
	s_waitcnt lgkmcnt(0)
	v_mfma_f32_16x16x32_bf16 v[60:63], v[128:131], v[144:147], v[60:63]
	v_mfma_f32_16x16x32_bf16 v[56:59], v[132:135], v[144:147], v[56:59]
	v_mfma_f32_16x16x32_bf16 v[52:55], v[128:131], v[148:151], v[52:55]
	v_mfma_f32_16x16x32_bf16 v[48:51], v[132:135], v[148:151], v[48:51]
	v_mfma_f32_16x16x32_bf16 v[44:47], v[128:131], v[160:163], v[44:47]
	v_mfma_f32_16x16x32_bf16 v[40:43], v[132:135], v[160:163], v[40:43]
	v_mfma_f32_16x16x32_bf16 v[36:39], v[128:131], v[164:167], v[36:39]
	v_mfma_f32_16x16x32_bf16 v[32:35], v[132:135], v[164:167], v[32:35]
	v_mfma_f32_16x16x32_bf16 v[60:63], v[136:139], v[152:155], v[60:63]
	v_mfma_f32_16x16x32_bf16 v[56:59], v[140:143], v[152:155], v[56:59]
	v_mfma_f32_16x16x32_bf16 v[52:55], v[136:139], v[156:159], v[52:55]
	v_mfma_f32_16x16x32_bf16 v[48:51], v[140:143], v[156:159], v[48:51]
	v_mfma_f32_16x16x32_bf16 v[44:47], v[136:139], v[168:171], v[44:47]
	v_mfma_f32_16x16x32_bf16 v[40:43], v[140:143], v[168:171], v[40:43]
	v_mfma_f32_16x16x32_bf16 v[36:39], v[136:139], v[172:175], v[36:39]
	v_mfma_f32_16x16x32_bf16 v[32:35], v[140:143], v[172:175], v[32:35]
	s_setprio 0
	s_barrier
	v_lshl_add_u64 v[196:197], s[4:5], 0, v[210:211]
	s_mov_b32 m0, s33
	v_lshl_add_u64 v[128:129], v[196:197], 0, s[28:29]
	global_load_lds_dwordx4 v[128:129], off
	v_lshl_add_u64 v[128:129], v[196:197], 0, s[36:37]
	s_mov_b32 m0, s34
	s_nop 0
	global_load_lds_dwordx4 v[128:129], off
	s_waitcnt vmcnt(6)
	s_barrier
	s_setprio 1
	v_mfma_f32_16x16x32_bf16 v[28:31], v[176:179], v[144:147], v[28:31]
	v_mfma_f32_16x16x32_bf16 v[24:27], v[180:183], v[144:147], v[24:27]
	v_mfma_f32_16x16x32_bf16 v[20:23], v[176:179], v[148:151], v[20:23]
	v_mfma_f32_16x16x32_bf16 v[16:19], v[180:183], v[148:151], v[16:19]
	v_mfma_f32_16x16x32_bf16 v[12:15], v[176:179], v[160:163], v[12:15]
	v_mfma_f32_16x16x32_bf16 v[8:11], v[180:183], v[160:163], v[8:11]
	v_mfma_f32_16x16x32_bf16 v[4:7], v[176:179], v[164:167], v[4:7]
	v_mfma_f32_16x16x32_bf16 v[0:3], v[180:183], v[164:167], v[0:3]
	v_mfma_f32_16x16x32_bf16 v[28:31], v[184:187], v[152:155], v[28:31]
	v_mfma_f32_16x16x32_bf16 v[24:27], v[188:191], v[152:155], v[24:27]
	v_mfma_f32_16x16x32_bf16 v[20:23], v[184:187], v[156:159], v[20:23]
	v_mfma_f32_16x16x32_bf16 v[16:19], v[188:191], v[156:159], v[16:19]
	v_mfma_f32_16x16x32_bf16 v[12:15], v[184:187], v[168:171], v[12:15]
	v_mfma_f32_16x16x32_bf16 v[8:11], v[188:191], v[168:171], v[8:11]
	v_mfma_f32_16x16x32_bf16 v[4:7], v[184:187], v[172:175], v[4:7]
	v_mfma_f32_16x16x32_bf16 v[0:3], v[188:191], v[172:175], v[0:3]
	s_setprio 0
	s_barrier
	ds_read_b128 v[128:131], v225
	ds_read_b128 v[132:135], v225 offset:2048
	ds_read_b128 v[136:139], v226
	ds_read_b128 v[140:143], v226 offset:2048
	s_mov_b64 s[96:97], 0x168000
	s_mov_b32 m0, s35
	v_lshl_add_u64 v[176:177], v[192:193], 0, s[96:97]
	s_mov_b64 s[96:97], 0x16a000
	ds_read_b128 v[144:147], v221 offset:32768
	ds_read_b128 v[148:151], v221 offset:34816
	ds_read_b128 v[152:155], v222 offset:32768
	ds_read_b128 v[156:159], v222 offset:34816
	ds_read_b128 v[160:163], v221 offset:36864
	ds_read_b128 v[164:167], v221 offset:38912
	ds_read_b128 v[168:171], v222 offset:36864
	ds_read_b128 v[172:175], v222 offset:38912
	global_load_lds_dwordx4 v[176:177], off
	v_lshl_add_u64 v[176:177], v[192:193], 0, s[96:97]
	s_mov_b32 m0, s42
	s_nop 0
	global_load_lds_dwordx4 v[176:177], off
	s_waitcnt lgkmcnt(8)
	s_barrier
	s_waitcnt lgkmcnt(0)
	s_setprio 1
	s_waitcnt lgkmcnt(0)
	v_mfma_f32_16x16x32_bf16 v[124:127], v[128:131], v[144:147], v[124:127]
	v_mfma_f32_16x16x32_bf16 v[120:123], v[132:135], v[144:147], v[120:123]
	v_mfma_f32_16x16x32_bf16 v[116:119], v[128:131], v[148:151], v[116:119]
	v_mfma_f32_16x16x32_bf16 v[112:115], v[132:135], v[148:151], v[112:115]
	v_mfma_f32_16x16x32_bf16 v[108:111], v[128:131], v[160:163], v[108:111]
	v_mfma_f32_16x16x32_bf16 v[104:107], v[132:135], v[160:163], v[104:107]
	v_mfma_f32_16x16x32_bf16 v[100:103], v[128:131], v[164:167], v[100:103]
	v_mfma_f32_16x16x32_bf16 v[96:99], v[132:135], v[164:167], v[96:99]
	v_mfma_f32_16x16x32_bf16 v[124:127], v[136:139], v[152:155], v[124:127]
	v_mfma_f32_16x16x32_bf16 v[120:123], v[140:143], v[152:155], v[120:123]
	v_mfma_f32_16x16x32_bf16 v[116:119], v[136:139], v[156:159], v[116:119]
	v_mfma_f32_16x16x32_bf16 v[112:115], v[140:143], v[156:159], v[112:115]
	v_mfma_f32_16x16x32_bf16 v[108:111], v[136:139], v[168:171], v[108:111]
	v_mfma_f32_16x16x32_bf16 v[104:107], v[140:143], v[168:171], v[104:107]
	v_mfma_f32_16x16x32_bf16 v[100:103], v[136:139], v[172:175], v[100:103]
	v_mfma_f32_16x16x32_bf16 v[96:99], v[140:143], v[172:175], v[96:99]
	s_setprio 0
	s_barrier
	s_mov_b32 m0, s43
	v_lshl_add_u64 v[198:199], v[194:195], 0, s[38:39]
	ds_read_b128 v[176:179], v227
	ds_read_b128 v[180:183], v227 offset:2048
	ds_read_b128 v[184:187], v228
	ds_read_b128 v[188:191], v228 offset:2048
	global_load_lds_dwordx4 v[198:199], off
	v_lshl_add_u64 v[194:195], v[194:195], 0, s[40:41]
	s_mov_b32 m0, s44
	s_nop 0
	global_load_lds_dwordx4 v[194:195], off
	s_barrier
	s_waitcnt lgkmcnt(0)
	s_setprio 1
	s_waitcnt lgkmcnt(0)
	v_mfma_f32_16x16x32_bf16 v[92:95], v[176:179], v[144:147], v[92:95]
	v_mfma_f32_16x16x32_bf16 v[88:91], v[180:183], v[144:147], v[88:91]
	v_mfma_f32_16x16x32_bf16 v[84:87], v[176:179], v[148:151], v[84:87]
	v_mfma_f32_16x16x32_bf16 v[80:83], v[180:183], v[148:151], v[80:83]
	v_mfma_f32_16x16x32_bf16 v[76:79], v[176:179], v[160:163], v[76:79]
	v_mfma_f32_16x16x32_bf16 v[72:75], v[180:183], v[160:163], v[72:75]
	v_mfma_f32_16x16x32_bf16 v[68:71], v[176:179], v[164:167], v[68:71]
	v_mfma_f32_16x16x32_bf16 v[64:67], v[180:183], v[164:167], v[64:67]
	v_mfma_f32_16x16x32_bf16 v[92:95], v[184:187], v[152:155], v[92:95]
	v_mfma_f32_16x16x32_bf16 v[88:91], v[188:191], v[152:155], v[88:91]
	v_mfma_f32_16x16x32_bf16 v[84:87], v[184:187], v[156:159], v[84:87]
	v_mfma_f32_16x16x32_bf16 v[80:83], v[188:191], v[156:159], v[80:83]
	v_mfma_f32_16x16x32_bf16 v[76:79], v[184:187], v[168:171], v[76:79]
	v_mfma_f32_16x16x32_bf16 v[72:75], v[188:191], v[168:171], v[72:75]
	v_mfma_f32_16x16x32_bf16 v[68:71], v[184:187], v[172:175], v[68:71]
	v_mfma_f32_16x16x32_bf16 v[64:67], v[188:191], v[172:175], v[64:67]
	s_setprio 0
	s_mov_b32 m0, s45
	v_lshl_add_u64 v[194:195], v[192:193], 0, s[38:39]
	s_barrier
	ds_read_b128 v[144:147], v221 offset:49152
	ds_read_b128 v[148:151], v221 offset:51200
	ds_read_b128 v[152:155], v222 offset:49152
	ds_read_b128 v[156:159], v222 offset:51200
	ds_read_b128 v[160:163], v221 offset:53248
	ds_read_b128 v[164:167], v221 offset:55296
	ds_read_b128 v[168:171], v222 offset:53248
	ds_read_b128 v[172:175], v222 offset:55296
	global_load_lds_dwordx4 v[194:195], off
	v_lshl_add_u64 v[192:193], v[192:193], 0, s[40:41]
	s_mov_b32 m0, s48
	s_nop 0
	global_load_lds_dwordx4 v[192:193], off
	s_barrier
	s_waitcnt lgkmcnt(0)
	s_setprio 1
	s_waitcnt lgkmcnt(0)
	v_mfma_f32_16x16x32_bf16 v[60:63], v[128:131], v[144:147], v[60:63]
	v_mfma_f32_16x16x32_bf16 v[56:59], v[132:135], v[144:147], v[56:59]
	v_mfma_f32_16x16x32_bf16 v[52:55], v[128:131], v[148:151], v[52:55]
	v_mfma_f32_16x16x32_bf16 v[48:51], v[132:135], v[148:151], v[48:51]
	v_mfma_f32_16x16x32_bf16 v[44:47], v[128:131], v[160:163], v[44:47]
	v_mfma_f32_16x16x32_bf16 v[40:43], v[132:135], v[160:163], v[40:43]
	v_mfma_f32_16x16x32_bf16 v[36:39], v[128:131], v[164:167], v[36:39]
	v_mfma_f32_16x16x32_bf16 v[32:35], v[132:135], v[164:167], v[32:35]
	v_mfma_f32_16x16x32_bf16 v[60:63], v[136:139], v[152:155], v[60:63]
	v_mfma_f32_16x16x32_bf16 v[56:59], v[140:143], v[152:155], v[56:59]
	v_mfma_f32_16x16x32_bf16 v[52:55], v[136:139], v[156:159], v[52:55]
	v_mfma_f32_16x16x32_bf16 v[48:51], v[140:143], v[156:159], v[48:51]
	v_mfma_f32_16x16x32_bf16 v[44:47], v[136:139], v[168:171], v[44:47]
	v_mfma_f32_16x16x32_bf16 v[40:43], v[140:143], v[168:171], v[40:43]
	v_mfma_f32_16x16x32_bf16 v[36:39], v[136:139], v[172:175], v[36:39]
	v_mfma_f32_16x16x32_bf16 v[32:35], v[140:143], v[172:175], v[32:35]
	s_setprio 0
	s_barrier
	s_mov_b32 m0, s49
	v_lshl_add_u64 v[128:129], v[196:197], 0, s[38:39]
	global_load_lds_dwordx4 v[128:129], off
	v_lshl_add_u64 v[128:129], v[196:197], 0, s[40:41]
	s_mov_b32 m0, s50
	s_nop 0
	global_load_lds_dwordx4 v[128:129], off
	s_waitcnt vmcnt(6)
	s_barrier
; #define LDA(dst,b,h) _Pragma("unroll") for(int m=0;m<4;++m) _Pragma("unroll") for(int k=0;k<2;++k) \
;     dst[m][k]=*reinterpret_cast<const bf16x8*>(SA(b,h)+(wr*64+m*16)*128+koff[k])
; #define LDB(dst,b,h) _Pragma("unroll") for(int n=0;n<2;++n) _Pragma("unroll") for(int k=0;k<2;++k) \
;     dst[n][k]=*reinterpret_cast<const bf16x8*>(SB(b,h)+(wc*32+n*16)*128+koff[k])
; #define MMA(ai,bj,Af,Bf) do{__builtin_amdgcn_s_setprio(1); \
;     _Pragma("unroll") for(int m=0;m<4;++m) _Pragma("unroll") for(int n=0;n<2;++n) _Pragma("unroll") for(int k=0;k<2;++k) \
;       acc[ai][bj][m][n]=__builtin_amdgcn_mfma_f32_16x16x32_bf16(Bf[n][k],Af[m][k],acc[ai][bj][m][n],0,0,0); \
;     __builtin_amdgcn_s_setprio(0);}while(0)
; #define WAIT_L(n) asm volatile("s_waitcnt lgkmcnt(" #n ")":::"memory")
; #define BAR __builtin_amdgcn_s_barrier()
; #define SCHED __builtin_amdgcn_sched_barrier(0)
; #define STAGE_A(b,h,kt) do{ unsigned char* _d = SA(b,h) + wbase; \
;     if constexpr (BLK) { const char* _s = baseA + ((size_t)(h)*(K/64) + (kt)) * 16384; GLDS(_s + voa, _d); GLDS(_s + 8192 + voa, _d + 8192); } \
;     else { const char* _s = baseA + ((size_t)(h)*128*K + (kt)*64) * 2; GLDS(_s + voa, _d); GLDS(_s + (size_t)128*K + voa, _d + 8192); } }while(0)
; template <int K, int EPI, bool MIX = false>
; __device__ __forceinline__ void gemm_phase(const Params& p, const u16* __restrict__ A, const u16* __restrict__ Bt,
;                            const float* __restrict__ rs_in, float* __restrict__ ssq_out, float alpha, bool rev = false) {
;     ...
;       for (int t = 0; t < nt - 2; t += 2) KBODY(t);
;     }
;     ...
;     const int cpm = pm, cpn = pn;
;     float rsq[2][4];
;     if constexpr (EPI == EPI_SWIGLU || EPI == EPI_Z || MIX) {
;       const float* rsrc = MIX ? p.ssqb : rs_in;
;       int fr_p = fr;
;       asm volatile("" : "+v"(fr_p));
; #pragma unroll
;       for (int ai = 0; ai < 2; ++ai)
; #pragma unroll
;         for (int m = 0; m < 4; ++m) rsq[ai][m] = rsrc[cpm * 256 + ai * 128 + wr * 64 + m * 16 + fr_p];
;     }
;     ++it;
;     id = item_id(it);
;     const bool more = id < ntiles;
;     if (rev) id = ntiles - 1 - id;
;     {
;       LDB(B0,0,0); SCHED; LDA(At,0,0); STAGE_A(1,1,nt-1);
;       WAIT_L(8); BAR; WAIT_L(0); MMA(0,0,At,B0); BAR; SCHED;
;       if (more) SETUP_TILE();
	s_setprio 1
	v_mfma_f32_16x16x32_bf16 v[28:31], v[176:179], v[144:147], v[28:31]
	v_mfma_f32_16x16x32_bf16 v[24:27], v[180:183], v[144:147], v[24:27]
	v_mfma_f32_16x16x32_bf16 v[20:23], v[176:179], v[148:151], v[20:23]
	v_mfma_f32_16x16x32_bf16 v[16:19], v[180:183], v[148:151], v[16:19]
	v_mfma_f32_16x16x32_bf16 v[12:15], v[176:179], v[160:163], v[12:15]
	v_mfma_f32_16x16x32_bf16 v[8:11], v[180:183], v[160:163], v[8:11]
	v_mfma_f32_16x16x32_bf16 v[4:7], v[176:179], v[164:167], v[4:7]
	v_mfma_f32_16x16x32_bf16 v[0:3], v[180:183], v[164:167], v[0:3]
	v_mfma_f32_16x16x32_bf16 v[28:31], v[184:187], v[152:155], v[28:31]
	v_mfma_f32_16x16x32_bf16 v[24:27], v[188:191], v[152:155], v[24:27]
	v_mfma_f32_16x16x32_bf16 v[20:23], v[184:187], v[156:159], v[20:23]
	v_mfma_f32_16x16x32_bf16 v[16:19], v[188:191], v[156:159], v[16:19]
	v_mfma_f32_16x16x32_bf16 v[12:15], v[184:187], v[168:171], v[12:15]
	v_mfma_f32_16x16x32_bf16 v[8:11], v[188:191], v[168:171], v[8:11]
	v_mfma_f32_16x16x32_bf16 v[4:7], v[184:187], v[172:175], v[4:7]
	v_mfma_f32_16x16x32_bf16 v[0:3], v[188:191], v[172:175], v[0:3]
	s_setprio 0
	s_add_i32 s79, s79, 2
	s_add_u32 s62, s62, 0x8000
	s_addc_u32 s63, s63, 0
	s_add_u32 s46, s46, 0x8000
	s_addc_u32 s47, s47, 0
	s_add_u32 s4, s4, 0x8000
	s_addc_u32 s5, s5, 0
	s_cmpk_lt_u32 s79, 0x54
	s_barrier
	s_cbranch_scc1 .LBB0_128
	ds_read_b128 v[136:139], v219
	ds_read_b128 v[140:143], v219 offset:2048
	ds_read_b128 v[148:151], v220
	ds_read_b128 v[144:147], v220 offset:2048
	s_add_i32 s78, s78, 1
	s_mul_i32 s4, s78, s76
	s_add_i32 s4, s4, s77
	s_cmpk_lt_i32 s4, 0x600
	s_cselect_b64 s[46:47], -1, 0
	s_cmpk_gt_i32 s4, 0x5ff
	v_lshl_add_u64 v[128:129], s[2:3], 0, v[208:209]
	s_mov_b64 s[62:63], 0x2bc000
	s_mov_b32 m0, s74
	v_lshl_add_u64 v[130:131], v[128:129], 0, s[62:63]
	s_mov_b64 s[62:63], 0x2be000
	ds_read_b128 v[156:159], v221
	ds_read_b128 v[160:163], v221 offset:2048
	ds_read_b128 v[184:187], v222
	ds_read_b128 v[176:179], v222 offset:2048
	ds_read_b128 v[164:167], v221 offset:4096
	ds_read_b128 v[168:171], v221 offset:6144
	ds_read_b128 v[180:183], v222 offset:4096
	ds_read_b128 v[172:175], v222 offset:6144
	global_load_lds_dwordx4 v[130:131], off
	v_lshl_add_u64 v[128:129], v[128:129], 0, s[62:63]
	s_mov_b32 m0, s75
	s_nop 0
	global_load_lds_dwordx4 v[128:129], off
	s_waitcnt lgkmcnt(8)
	s_barrier
	s_waitcnt lgkmcnt(0)
	s_setprio 1
	s_waitcnt lgkmcnt(0)
	v_mfma_f32_16x16x32_bf16 v[124:127], v[136:139], v[156:159], v[124:127]
	v_mfma_f32_16x16x32_bf16 v[120:123], v[140:143], v[156:159], v[120:123]
	v_mfma_f32_16x16x32_bf16 v[116:119], v[136:139], v[160:163], v[116:119]
	v_mfma_f32_16x16x32_bf16 v[112:115], v[140:143], v[160:163], v[112:115]
	v_mfma_f32_16x16x32_bf16 v[108:111], v[136:139], v[164:167], v[108:111]
	v_mfma_f32_16x16x32_bf16 v[104:107], v[140:143], v[164:167], v[104:107]
	v_mfma_f32_16x16x32_bf16 v[100:103], v[136:139], v[168:171], v[100:103]
	v_mfma_f32_16x16x32_bf16 v[96:99], v[140:143], v[168:171], v[96:99]
	v_mfma_f32_16x16x32_bf16 v[124:127], v[148:151], v[184:187], v[124:127]
	v_mfma_f32_16x16x32_bf16 v[120:123], v[144:147], v[184:187], v[120:123]
	v_mfma_f32_16x16x32_bf16 v[116:119], v[148:151], v[176:179], v[116:119]
	v_mfma_f32_16x16x32_bf16 v[112:115], v[144:147], v[176:179], v[112:115]
	v_mfma_f32_16x16x32_bf16 v[128:131], v[148:151], v[180:183], v[108:111]
	v_mfma_f32_16x16x32_bf16 v[132:135], v[144:147], v[180:183], v[104:107]
	v_mfma_f32_16x16x32_bf16 v[100:103], v[148:151], v[172:175], v[100:103]
	v_mfma_f32_16x16x32_bf16 v[96:99], v[144:147], v[172:175], v[96:99]
	s_setprio 0
	s_barrier
	s_mov_b32 s79, s81
	s_mov_b32 s80, s82
	s_cbranch_scc1 .LBB0_131
	s_sub_i32 s2, 0x5ff, s4
	s_lshr_b32 s3, s2, 3
	s_and_b32 s3, s3, 0x1ffffff8
	s_lshl_b32 s4, s3, 3
	s_sub_i32 s4, s2, s4
	s_and_b32 s2, s2, 7
	s_or_b32 s80, s3, s2
	s_ashr_i32 s79, s4, 3
	s_lshl_b32 s2, s80, 1
	s_mul_i32 s3, s80, 0x2c0000
	v_readlane_b32 s52, v254, 16
	s_mul_hi_u32 s4, s2, 0x160000
	s_add_u32 s2, s92, s3
	v_readlane_b32 s60, v254, 24
	v_readlane_b32 s61, v254, 25
	v_readlane_b32 s62, v254, 26
	v_readlane_b32 s63, v254, 27
	v_readlane_b32 s64, v254, 28
	v_readlane_b32 s65, v254, 29
	s_addc_u32 s3, s93, s4
	s_lshl_b32 s4, s79, 1
	s_mul_i32 s5, s79, 0x2c0000
	v_readlane_b32 s66, v254, 30
	v_readlane_b32 s67, v254, 31
	s_mov_b64 s[60:61], s[64:65]
	s_mul_hi_i32 s4, s4, 0x160000
	s_add_u32 s8, s60, s5
	s_addc_u32 s9, s61, s4
	s_add_u32 s10, s8, 0x160000
	v_readlane_b32 s76, v255, 6
	s_addc_u32 s11, s9, 0
	v_readlane_b32 s53, v254, 17
	v_readlane_b32 s54, v254, 18
	v_readlane_b32 s55, v254, 19
	v_readlane_b32 s56, v254, 20
	v_readlane_b32 s57, v254, 21
	v_readlane_b32 s58, v254, 22
	v_readlane_b32 s59, v254, 23
	s_mov_b64 s[62:63], s[66:67]

; __global__ void __launch_bounds__(NTHR) fwd_megakernel(Params p) {
;     ...
;   run_phase<2>(p); grid.sync();
.LBB0_167:
	s_waitcnt vmcnt(0) lgkmcnt(0)
	s_barrier
	s_mov_b64 s[0:1], exec
	v_readlane_b32 s2, v255, 1
	v_readlane_b32 s3, v255, 2
	s_and_b64 s[2:3], s[0:1], s[2:3]
	s_mov_b64 exec, s[2:3]
	s_cbranch_execz .LBB0_177
	buffer_wbl2 sc1
	s_waitcnt vmcnt(0)
	v_readlane_b32 s2, v254, 24
	v_readlane_b32 s3, v254, 25
	v_readlane_b32 s4, v255, 3
	s_load_dword s5, s[72:73], 0x0
	s_nop 3
	s_add_u32 s2, s2, 0x10000000
	s_addc_u32 s3, s3, 0
	s_and_b32 s4, s4, 7
	s_lshl_b32 s4, s4, 8
	s_add_i32 s4, s4, 0x100
	v_mov_b32_e32 v2, 0
	v_mov_b32_e32 v3, 1
	v_mov_b32_e32 v0, s4
	s_nop 3
	global_atomic_add v3, v2, v3, s[2:3] sc0 sc1
	s_waitcnt lgkmcnt(0)
	s_mul_i32 s5, s5, 2
	s_add_i32 s5, s5, -1
	s_waitcnt vmcnt(0)
	v_readfirstlane_b32 s4, v3
	s_nop 3
	s_cmp_lg_u32 s4, s5
	s_cbranch_scc1 .Lfb2_poll0
	v_mov_b32_e32 v1, 1
	global_atomic_add v2, v1, s[2:3] offset:256 sc1
	global_atomic_add v2, v1, s[2:3] offset:512 sc1
	global_atomic_add v2, v1, s[2:3] offset:768 sc1
	global_atomic_add v2, v1, s[2:3] offset:1024 sc1
	global_atomic_add v2, v1, s[2:3] offset:1280 sc1
	global_atomic_add v2, v1, s[2:3] offset:1536 sc1
	global_atomic_add v2, v1, s[2:3] offset:1792 sc1
	global_atomic_add v2, v1, s[2:3] offset:2048 sc1
	s_branch .Lfb2_done

; __global__ void __launch_bounds__(NTHR) fwd_megakernel(Params p) {
;     ...
;   run_phase<2>(p); grid.sync();
.Lfb2_poll:
	global_load_dword v1, v0, s[2:3] sc1
	s_waitcnt vmcnt(0)
	v_readfirstlane_b32 s4, v1
	s_nop 3
	s_cmpk_ge_u32 s4, 2
	s_cbranch_scc1 .Lfb2_done
	s_sleep 1
	s_add_u32 s6, s6, 1
	s_cmpk_lt_u32 s6, 0x7fff
	s_cbranch_scc1 .Lfb2_poll

; #define WAIT_V(n) asm volatile("s_waitcnt vmcnt(" #n ")":::"memory")
; #define BAR __builtin_amdgcn_s_barrier()
; #define STAGE_A(b,h,kt) do{ unsigned char* _d = SA(b,h) + wbase; \
;     if constexpr (BLK) { const char* _s = baseA + ((size_t)(h)*(K/64) + (kt)) * 16384; GLDS(_s + voa, _d); GLDS(_s + 8192 + voa, _d + 8192); } \
;     else { const char* _s = baseA + ((size_t)(h)*128*K + (kt)*64) * 2; GLDS(_s + voa, _d); GLDS(_s + (size_t)128*K + voa, _d + 8192); } }while(0)
; #define STAGE_B(b,h,kt) do{ unsigned char* _d = SB(b,h) + wbase; \
;     if constexpr (BLK) { const char* _s = ((h)?baseB1:baseB0) + (size_t)(kt) * 16384; GLDS(_s + voa, _d); GLDS(_s + 8192 + voa, _d + 8192); } \
;     else { const char* _s = ((h)?baseB1:baseB0) + (kt)*128; GLDS(_s + voa, _d); GLDS(_s + (size_t)128*K + voa, _d + 8192); } }while(0)
; template <int K, int EPI, bool MIX = false>
; __device__ __forceinline__ void gemm_phase(const Params& p, const u16* __restrict__ A, const u16* __restrict__ Bt,
;                            const float* __restrict__ rs_in, float* __restrict__ ssq_out, float alpha, bool rev = false) {
;     ...
;   int tid = threadIdx.x;
;   asm volatile("" : "+v"(tid));
;   const int wid = __builtin_amdgcn_readfirstlane(tid >> 6);
;   const int lane = tid & 63, wr = wid >> 2, wc = wid & 3, fr = lane & 15, fq = lane >> 4;
;   const int wbase = wid * 1024;
;   int koff[2];
;   koff[0] = lds_off32(fr, fq); koff[1] = lds_off32(fr, 4 + fq);
;   int it = 0;
;   int id = item_id(0);
;   if (id >= ntiles) return;
;   if (rev) id = ntiles - 1 - id;
;   int pm, pn;
;   const char *baseA, *baseB0, *baseB1;
;   unsigned voa;
;   {
;     const int R = tid >> 3, C = ((tid & 7) ^ ((R >> 1) & 7)) * 8;
;     voa = (unsigned)(R * (BLK ? 64 : K) + C) * 2u;
;   }
;     ...
;   SETUP_TILE();
;   STAGE_B(0,0,0); STAGE_A(0,0,0); STAGE_B(0,1,0); STAGE_A(0,1,0);
;   if (wr == 1) BAR;
;   WAIT_V(4); BAR;
;   STAGE_B(1,0,1); STAGE_A(1,0,1); STAGE_B(1,1,1);
;   WAIT_V(6); BAR;
.LBB0_180:
	s_add_i32 s27, s76, 0x18000
	s_mov_b64 s[46:47], 0x80
	v_lshl_add_u64 v[8:9], v[0:1], 0, s[46:47]
	s_mov_b32 m0, s27
	s_mov_b64 s[48:49], 0x40080
	s_add_i32 s31, s76, 0x1a000
	s_waitcnt vmcnt(4)
	s_barrier
	global_load_lds_dwordx4 v[8:9], off
	v_lshl_add_u64 v[8:9], v[0:1], 0, s[48:49]
	s_mov_b32 m0, s31
	s_add_i32 s1, s76, 0x8000
	global_load_lds_dwordx4 v[8:9], off
	v_lshl_add_u64 v[8:9], v[2:3], 0, s[46:47]
	s_mov_b32 m0, s1
	s_add_i32 s34, s76, 0xa000
	global_load_lds_dwordx4 v[8:9], off
	v_lshl_add_u64 v[2:3], v[2:3], 0, s[48:49]
	s_mov_b32 m0, s34
	s_add_i32 s19, s76, 0x1c000
	s_mov_b64 s[72:73], 0x80080
	global_load_lds_dwordx4 v[2:3], off
	v_lshl_add_u64 v[2:3], v[0:1], 0, s[72:73]
	s_mov_b32 m0, s19
	s_mov_b64 s[70:71], 0xc0080
	s_add_i32 s18, s76, 0x1e000
	global_load_lds_dwordx4 v[2:3], off
	v_lshl_add_u64 v[0:1], v[0:1], 0, s[70:71]
	s_mov_b32 m0, s18
	s_and_b32 s4, s3, 3
	global_load_lds_dwordx4 v[0:1], off
	s_lshl_b32 s3, s4, 12
	s_or_b32 s5, s3, 0x10000
	s_lshl_b32 s6, s2, 13
	s_or_b32 s7, s3, 0x14000
	s_or_b32 s8, s3, 0x18000
	s_or_b32 s9, s3, 0x1c000
	s_lshl_b32 s13, s2, 6
	s_cmpk_lt_u32 s0, 0x100
	s_cselect_b64 s[2:3], -1, 0
	v_and_b32_e32 v219, 15, v6
	v_bfe_u32 v0, v6, 4, 2
	v_bfe_u32 v2, v6, 1, 3
	v_writelane_b32 v255, s2, 18
	v_lshlrev_b32_e32 v1, 7, v219
	v_xor_b32_e32 v3, v0, v2
	v_bitop3_b32 v0, v0, v2, 4 bitop3:0x36
	s_waitcnt vmcnt(6)
	v_writelane_b32 v255, s3, 19
	s_lshl_b32 s0, s4, 5
	v_lshl_or_b32 v3, v3, 4, v1
	v_lshl_or_b32 v0, v0, 4, v1
	v_writelane_b32 v255, s0, 20
	s_lshl_b32 s2, s4, 6
	v_and_b32_e32 v218, 63, v6
	s_mov_b32 s3, 0
	v_add_u32_e32 v210, v5, v4
	v_mov_b32_e32 v211, v209
	v_add_u32_e32 v220, s5, v3
	v_add_u32_e32 v221, s5, v0
	v_add_u32_e32 v222, s6, v3
	v_add_u32_e32 v223, s6, v0
	s_add_i32 s28, s76, 0xc000
	s_add_i32 s22, s76, 0xe000
	v_add_u32_e32 v224, s7, v3
	v_add_u32_e32 v225, s7, v0
	s_mov_b64 s[78:79], 0x100
	s_mov_b64 s[80:81], 0x40100
	v_add_u32_e32 v226, s8, v3
	v_add_u32_e32 v227, s8, v0
	v_add_u32_e32 v228, s9, v3
	v_add_u32_e32 v229, s9, v0
	s_mov_b64 s[82:83], 0x180
	s_mov_b64 s[96:97], 0x40180
	v_mov_b32_e32 v232, 0x358637bd
	s_mov_b32 s29, 0x800000
	s_mov_b32 s68, 0x3f3504f3
	s_mov_b32 s69, 0x3ea7ba05
	s_mov_b32 s36, 0x3f87dc22
	s_mov_b32 s30, 0x3fb5f0e3
	s_mov_b32 s0, 0xbe91a98e
	s_mov_b32 s14, 0x3e827906
	s_brev_b32 s38, -2
	s_movk_i32 s41, 0x2800
	s_lshl_b32 s24, s2, 1
	v_mbcnt_hi_u32_b32 v233, -1, v231
	v_mov_b32_e32 v234, 0x3e000000
	s_mov_b32 s74, 0
	v_writelane_b32 v255, s13, 21
	s_barrier
	s_mov_b64 vcc, exec
	s_branch .LBB0_182

; #define SCHED __builtin_amdgcn_sched_barrier(0)
; template <int K, int EPI, bool MIX = false>
; __device__ __forceinline__ void gemm_phase(const Params& p, const u16* __restrict__ A, const u16* __restrict__ Bt,
;                            const float* __restrict__ rs_in, float* __restrict__ ssq_out, float alpha, bool rev = false) {
;     ...
;     f32x4 acc[2][2][4][2];
; #pragma unroll
;     for (int a = 0; a < 2; ++a)
; #pragma unroll
;       for (int b = 0; b < 2; ++b)
; #pragma unroll
;         for (int m = 0; m < 4; ++m)
; #pragma unroll
;           for (int n = 0; n < 2; ++n) acc[a][b][m][n] = f32x4{0.f, 0.f, 0.f, 0.f};
;     bf16x8 At[4][2], B0[2][2], B1[2][2];
;     asm volatile("" ::: "memory");
;     SCHED;
.LBB0_182:
	s_mov_b32 s25, s75
	v_mov_b32_e32 v96, 0
	s_mov_b32 s2, -2
	s_mov_b64 s[4:5], s[44:45]
	s_mov_b64 s[6:7], s[16:17]
	s_mov_b64 s[8:9], s[20:21]
	v_mov_b32_e32 v97, v96
	v_mov_b32_e32 v98, v96
	v_mov_b32_e32 v99, v96
	v_mov_b32_e32 v100, v96
	v_mov_b32_e32 v101, v96
	v_mov_b32_e32 v102, v96
	v_mov_b32_e32 v103, v96
	v_mov_b32_e32 v104, v96
	v_mov_b32_e32 v105, v96
	v_mov_b32_e32 v106, v96
	v_mov_b32_e32 v107, v96
	v_mov_b32_e32 v108, v96
	v_mov_b32_e32 v109, v96
	v_mov_b32_e32 v110, v96
	v_mov_b32_e32 v111, v96
	v_mov_b32_e32 v112, v96
	v_mov_b32_e32 v113, v96
	v_mov_b32_e32 v114, v96
	v_mov_b32_e32 v115, v96
	v_mov_b32_e32 v116, v96
	v_mov_b32_e32 v117, v96
	v_mov_b32_e32 v118, v96
	v_mov_b32_e32 v119, v96
	v_mov_b32_e32 v120, v96
	v_mov_b32_e32 v121, v96
	v_mov_b32_e32 v122, v96
	v_mov_b32_e32 v123, v96
	v_mov_b32_e32 v124, v96
	v_mov_b32_e32 v125, v96
	v_mov_b32_e32 v126, v96
	v_mov_b32_e32 v127, v96
	v_mov_b32_e32 v56, v96
	v_mov_b32_e32 v57, v96
	v_mov_b32_e32 v58, v96
	v_mov_b32_e32 v59, v96
	v_mov_b32_e32 v64, v96
	v_mov_b32_e32 v65, v96
	v_mov_b32_e32 v66, v96
	v_mov_b32_e32 v67, v96
	v_mov_b32_e32 v72, v96
	v_mov_b32_e32 v73, v96
	v_mov_b32_e32 v74, v96
	v_mov_b32_e32 v75, v96
	v_mov_b32_e32 v76, v96
	v_mov_b32_e32 v77, v96
	v_mov_b32_e32 v78, v96
	v_mov_b32_e32 v79, v96
	v_mov_b32_e32 v80, v96
	v_mov_b32_e32 v81, v96
	v_mov_b32_e32 v82, v96
	v_mov_b32_e32 v83, v96
	v_mov_b32_e32 v84, v96
	v_mov_b32_e32 v85, v96
	v_mov_b32_e32 v86, v96
	v_mov_b32_e32 v87, v96
	v_mov_b32_e32 v88, v96
	v_mov_b32_e32 v89, v96
	v_mov_b32_e32 v90, v96
	v_mov_b32_e32 v91, v96
	v_mov_b32_e32 v92, v96
	v_mov_b32_e32 v93, v96
	v_mov_b32_e32 v94, v96
	v_mov_b32_e32 v95, v96
	v_mov_b32_e32 v32, v96
	v_mov_b32_e32 v33, v96
	v_mov_b32_e32 v34, v96
	v_mov_b32_e32 v35, v96
	v_mov_b32_e32 v36, v96
	v_mov_b32_e32 v37, v96
	v_mov_b32_e32 v38, v96
	v_mov_b32_e32 v39, v96
	v_mov_b32_e32 v40, v96
	v_mov_b32_e32 v41, v96
	v_mov_b32_e32 v42, v96
	v_mov_b32_e32 v43, v96
	v_mov_b32_e32 v44, v96
	v_mov_b32_e32 v45, v96
	v_mov_b32_e32 v46, v96
	v_mov_b32_e32 v47, v96
	v_mov_b32_e32 v48, v96
	v_mov_b32_e32 v49, v96
	v_mov_b32_e32 v50, v96
	v_mov_b32_e32 v51, v96
	v_mov_b32_e32 v52, v96
	v_mov_b32_e32 v53, v96
	v_mov_b32_e32 v54, v96
	v_mov_b32_e32 v55, v96
	v_mov_b32_e32 v60, v96
	v_mov_b32_e32 v61, v96
	v_mov_b32_e32 v62, v96
	v_mov_b32_e32 v63, v96
	v_mov_b32_e32 v68, v96
	v_mov_b32_e32 v69, v96
	v_mov_b32_e32 v70, v96
	v_mov_b32_e32 v71, v96
	v_mov_b32_e32 v0, v96
	v_mov_b32_e32 v1, v96
	v_mov_b32_e32 v2, v96
	v_mov_b32_e32 v3, v96
	v_mov_b32_e32 v4, v96
	v_mov_b32_e32 v5, v96
	v_mov_b32_e32 v6, v96
	v_mov_b32_e32 v7, v96
	v_mov_b32_e32 v8, v96
	v_mov_b32_e32 v9, v96
	v_mov_b32_e32 v10, v96
	v_mov_b32_e32 v11, v96
	v_mov_b32_e32 v12, v96
	v_mov_b32_e32 v13, v96
	v_mov_b32_e32 v14, v96
	v_mov_b32_e32 v15, v96
	v_mov_b32_e32 v16, v96
	v_mov_b32_e32 v17, v96
	v_mov_b32_e32 v18, v96
	v_mov_b32_e32 v19, v96
	v_mov_b32_e32 v20, v96
	v_mov_b32_e32 v21, v96
	v_mov_b32_e32 v22, v96
	v_mov_b32_e32 v23, v96
	v_mov_b32_e32 v24, v96
	v_mov_b32_e32 v25, v96
	v_mov_b32_e32 v26, v96
	v_mov_b32_e32 v27, v96
	v_mov_b32_e32 v28, v96
	v_mov_b32_e32 v29, v96
	v_mov_b32_e32 v30, v96
	v_mov_b32_e32 v31, v96
	s_cbranch_vccnz .Llate_p3_done
	s_barrier
.Llate_p3_done:
.LBB0_183:
	ds_read_b128 v[128:131], v220
	s_waitcnt lgkmcnt(0)
	ds_read_b128 v[132:135], v220 offset:2048
	ds_read_b128 v[136:139], v221
	ds_read_b128 v[140:143], v221 offset:2048
	v_lshl_add_u64 v[192:193], s[6:7], 0, v[210:211]
	s_mov_b32 m0, s28
	v_lshl_add_u64 v[176:177], v[192:193], 0, s[72:73]
	ds_read_b128 v[144:147], v222
	ds_read_b128 v[148:151], v222 offset:2048
	ds_read_b128 v[152:155], v223
	ds_read_b128 v[156:159], v223 offset:2048
	ds_read_b128 v[160:163], v222 offset:4096
	ds_read_b128 v[164:167], v222 offset:6144
	ds_read_b128 v[168:171], v223 offset:4096
	ds_read_b128 v[172:175], v223 offset:6144
	global_load_lds_dwordx4 v[176:177], off
	v_lshl_add_u64 v[176:177], v[192:193], 0, s[70:71]
	s_mov_b32 m0, s22
	s_nop 0
	global_load_lds_dwordx4 v[176:177], off
	s_waitcnt lgkmcnt(8)
	s_barrier
	s_waitcnt lgkmcnt(0)
	s_setprio 1
	s_waitcnt lgkmcnt(0)
	v_mfma_f32_16x16x32_bf16 v[124:127], v[128:131], v[144:147], v[124:127]
	v_mfma_f32_16x16x32_bf16 v[120:123], v[132:135], v[144:147], v[120:123]
	v_mfma_f32_16x16x32_bf16 v[116:119], v[128:131], v[148:151], v[116:119]
	v_mfma_f32_16x16x32_bf16 v[112:115], v[132:135], v[148:151], v[112:115]
	v_mfma_f32_16x16x32_bf16 v[108:111], v[128:131], v[160:163], v[108:111]
	v_mfma_f32_16x16x32_bf16 v[104:107], v[132:135], v[160:163], v[104:107]
	v_mfma_f32_16x16x32_bf16 v[100:103], v[128:131], v[164:167], v[100:103]
	v_mfma_f32_16x16x32_bf16 v[96:99], v[132:135], v[164:167], v[96:99]
	v_mfma_f32_16x16x32_bf16 v[124:127], v[136:139], v[152:155], v[124:127]
	v_mfma_f32_16x16x32_bf16 v[120:123], v[140:143], v[152:155], v[120:123]
	v_mfma_f32_16x16x32_bf16 v[116:119], v[136:139], v[156:159], v[116:119]
	v_mfma_f32_16x16x32_bf16 v[112:115], v[140:143], v[156:159], v[112:115]
	v_mfma_f32_16x16x32_bf16 v[108:111], v[136:139], v[168:171], v[108:111]
	v_mfma_f32_16x16x32_bf16 v[104:107], v[140:143], v[168:171], v[104:107]
	v_mfma_f32_16x16x32_bf16 v[100:103], v[136:139], v[172:175], v[100:103]
	v_mfma_f32_16x16x32_bf16 v[96:99], v[140:143], v[172:175], v[96:99]
	s_setprio 0
	s_barrier
	v_lshl_add_u64 v[194:195], s[8:9], 0, v[210:211]
	s_mov_b32 m0, s37
	v_lshl_add_u64 v[196:197], v[194:195], 0, s[78:79]
	ds_read_b128 v[176:179], v224
	ds_read_b128 v[180:183], v224 offset:2048
	ds_read_b128 v[184:187], v225
	ds_read_b128 v[188:191], v225 offset:2048
	global_load_lds_dwordx4 v[196:197], off
	v_lshl_add_u64 v[196:197], v[194:195], 0, s[80:81]
	s_mov_b32 m0, s39
	s_nop 0
	global_load_lds_dwordx4 v[196:197], off
	s_barrier
	s_waitcnt lgkmcnt(0)
	s_setprio 1
	s_waitcnt lgkmcnt(0)
	v_mfma_f32_16x16x32_bf16 v[56:59], v[176:179], v[144:147], v[56:59]
	v_mfma_f32_16x16x32_bf16 v[64:67], v[180:183], v[144:147], v[64:67]
	v_mfma_f32_16x16x32_bf16 v[72:75], v[176:179], v[148:151], v[72:75]
	v_mfma_f32_16x16x32_bf16 v[76:79], v[180:183], v[148:151], v[76:79]
	v_mfma_f32_16x16x32_bf16 v[80:83], v[176:179], v[160:163], v[80:83]
	v_mfma_f32_16x16x32_bf16 v[84:87], v[180:183], v[160:163], v[84:87]
	v_mfma_f32_16x16x32_bf16 v[88:91], v[176:179], v[164:167], v[88:91]
	v_mfma_f32_16x16x32_bf16 v[92:95], v[180:183], v[164:167], v[92:95]
	v_mfma_f32_16x16x32_bf16 v[56:59], v[184:187], v[152:155], v[56:59]
	v_mfma_f32_16x16x32_bf16 v[64:67], v[188:191], v[152:155], v[64:67]
	v_mfma_f32_16x16x32_bf16 v[72:75], v[184:187], v[156:159], v[72:75]
	v_mfma_f32_16x16x32_bf16 v[76:79], v[188:191], v[156:159], v[76:79]
	v_mfma_f32_16x16x32_bf16 v[80:83], v[184:187], v[168:171], v[80:83]
	v_mfma_f32_16x16x32_bf16 v[84:87], v[188:191], v[168:171], v[84:87]
	v_mfma_f32_16x16x32_bf16 v[88:91], v[184:187], v[172:175], v[88:91]
	v_mfma_f32_16x16x32_bf16 v[92:95], v[188:191], v[172:175], v[92:95]
	s_setprio 0
	s_mov_b32 m0, s76
	v_lshl_add_u64 v[196:197], v[192:193], 0, s[78:79]
	s_barrier
	ds_read_b128 v[144:147], v222 offset:16384
	ds_read_b128 v[148:151], v222 offset:18432
	ds_read_b128 v[152:155], v223 offset:16384
	ds_read_b128 v[156:159], v223 offset:18432
	ds_read_b128 v[160:163], v222 offset:20480
	ds_read_b128 v[164:167], v222 offset:22528
	ds_read_b128 v[168:171], v223 offset:20480
	ds_read_b128 v[172:175], v223 offset:22528
	global_load_lds_dwordx4 v[196:197], off
	v_lshl_add_u64 v[196:197], v[192:193], 0, s[80:81]
	s_mov_b32 m0, s77
	s_nop 0
	global_load_lds_dwordx4 v[196:197], off
	s_barrier
	s_waitcnt lgkmcnt(0)
	s_setprio 1
	s_waitcnt lgkmcnt(0)
	v_mfma_f32_16x16x32_bf16 v[32:35], v[128:131], v[144:147], v[32:35]
	v_mfma_f32_16x16x32_bf16 v[36:39], v[132:135], v[144:147], v[36:39]
	v_mfma_f32_16x16x32_bf16 v[40:43], v[128:131], v[148:151], v[40:43]
	v_mfma_f32_16x16x32_bf16 v[44:47], v[132:135], v[148:151], v[44:47]
	v_mfma_f32_16x16x32_bf16 v[48:51], v[128:131], v[160:163], v[48:51]
	v_mfma_f32_16x16x32_bf16 v[52:55], v[132:135], v[160:163], v[52:55]
	v_mfma_f32_16x16x32_bf16 v[60:63], v[128:131], v[164:167], v[60:63]
	v_mfma_f32_16x16x32_bf16 v[68:71], v[132:135], v[164:167], v[68:71]
	v_mfma_f32_16x16x32_bf16 v[32:35], v[136:139], v[152:155], v[32:35]
	v_mfma_f32_16x16x32_bf16 v[36:39], v[140:143], v[152:155], v[36:39]
	v_mfma_f32_16x16x32_bf16 v[40:43], v[136:139], v[156:159], v[40:43]
	v_mfma_f32_16x16x32_bf16 v[44:47], v[140:143], v[156:159], v[44:47]
	v_mfma_f32_16x16x32_bf16 v[48:51], v[136:139], v[168:171], v[48:51]
	v_mfma_f32_16x16x32_bf16 v[52:55], v[140:143], v[168:171], v[52:55]
	v_mfma_f32_16x16x32_bf16 v[60:63], v[136:139], v[172:175], v[60:63]
	v_mfma_f32_16x16x32_bf16 v[68:71], v[140:143], v[172:175], v[68:71]
	s_setprio 0
	s_barrier
	v_lshl_add_u64 v[196:197], s[4:5], 0, v[210:211]
	s_mov_b32 m0, s23
	v_lshl_add_u64 v[128:129], v[196:197], 0, s[78:79]
	global_load_lds_dwordx4 v[128:129], off
	v_lshl_add_u64 v[128:129], v[196:197], 0, s[80:81]
	s_mov_b32 m0, s33
	s_nop 0
	global_load_lds_dwordx4 v[128:129], off
	s_waitcnt vmcnt(6)
	s_barrier
	s_setprio 1
	v_mfma_f32_16x16x32_bf16 v[0:3], v[176:179], v[144:147], v[0:3]
	v_mfma_f32_16x16x32_bf16 v[4:7], v[180:183], v[144:147], v[4:7]
	v_mfma_f32_16x16x32_bf16 v[8:11], v[176:179], v[148:151], v[8:11]
	v_mfma_f32_16x16x32_bf16 v[12:15], v[180:183], v[148:151], v[12:15]
	v_mfma_f32_16x16x32_bf16 v[16:19], v[176:179], v[160:163], v[16:19]
	v_mfma_f32_16x16x32_bf16 v[20:23], v[180:183], v[160:163], v[20:23]
	v_mfma_f32_16x16x32_bf16 v[24:27], v[176:179], v[164:167], v[24:27]
	v_mfma_f32_16x16x32_bf16 v[28:31], v[180:183], v[164:167], v[28:31]
	v_mfma_f32_16x16x32_bf16 v[0:3], v[184:187], v[152:155], v[0:3]
	v_mfma_f32_16x16x32_bf16 v[4:7], v[188:191], v[152:155], v[4:7]
	v_mfma_f32_16x16x32_bf16 v[8:11], v[184:187], v[156:159], v[8:11]
	v_mfma_f32_16x16x32_bf16 v[12:15], v[188:191], v[156:159], v[12:15]
	v_mfma_f32_16x16x32_bf16 v[16:19], v[184:187], v[168:171], v[16:19]
	v_mfma_f32_16x16x32_bf16 v[20:23], v[188:191], v[168:171], v[20:23]
	v_mfma_f32_16x16x32_bf16 v[24:27], v[184:187], v[172:175], v[24:27]
	v_mfma_f32_16x16x32_bf16 v[28:31], v[188:191], v[172:175], v[28:31]
	s_setprio 0
	s_barrier
	ds_read_b128 v[128:131], v226
	ds_read_b128 v[132:135], v226 offset:2048
	ds_read_b128 v[136:139], v227
	ds_read_b128 v[140:143], v227 offset:2048
	s_mov_b64 s[10:11], 0x80100
	s_mov_b32 m0, s26
	v_lshl_add_u64 v[176:177], v[192:193], 0, s[10:11]
	s_mov_b64 s[10:11], 0xc0100
	ds_read_b128 v[144:147], v222 offset:32768
	ds_read_b128 v[148:151], v222 offset:34816
	ds_read_b128 v[152:155], v223 offset:32768
	ds_read_b128 v[156:159], v223 offset:34816
	ds_read_b128 v[160:163], v222 offset:36864
	ds_read_b128 v[164:167], v222 offset:38912
	ds_read_b128 v[168:171], v223 offset:36864
	ds_read_b128 v[172:175], v223 offset:38912
	global_load_lds_dwordx4 v[176:177], off
	v_lshl_add_u64 v[176:177], v[192:193], 0, s[10:11]
	s_mov_b32 m0, s35
	s_nop 0
	global_load_lds_dwordx4 v[176:177], off
	s_waitcnt lgkmcnt(8)
	s_barrier
	s_waitcnt lgkmcnt(0)
	s_setprio 1
	s_waitcnt lgkmcnt(0)
	v_mfma_f32_16x16x32_bf16 v[124:127], v[128:131], v[144:147], v[124:127]
	v_mfma_f32_16x16x32_bf16 v[120:123], v[132:135], v[144:147], v[120:123]
	v_mfma_f32_16x16x32_bf16 v[116:119], v[128:131], v[148:151], v[116:119]
	v_mfma_f32_16x16x32_bf16 v[112:115], v[132:135], v[148:151], v[112:115]
	v_mfma_f32_16x16x32_bf16 v[108:111], v[128:131], v[160:163], v[108:111]
	v_mfma_f32_16x16x32_bf16 v[104:107], v[132:135], v[160:163], v[104:107]
	v_mfma_f32_16x16x32_bf16 v[100:103], v[128:131], v[164:167], v[100:103]
	v_mfma_f32_16x16x32_bf16 v[96:99], v[132:135], v[164:167], v[96:99]
	v_mfma_f32_16x16x32_bf16 v[124:127], v[136:139], v[152:155], v[124:127]
	v_mfma_f32_16x16x32_bf16 v[120:123], v[140:143], v[152:155], v[120:123]
	v_mfma_f32_16x16x32_bf16 v[116:119], v[136:139], v[156:159], v[116:119]
	v_mfma_f32_16x16x32_bf16 v[112:115], v[140:143], v[156:159], v[112:115]
	v_mfma_f32_16x16x32_bf16 v[108:111], v[136:139], v[168:171], v[108:111]
	v_mfma_f32_16x16x32_bf16 v[104:107], v[140:143], v[168:171], v[104:107]
	v_mfma_f32_16x16x32_bf16 v[100:103], v[136:139], v[172:175], v[100:103]
	v_mfma_f32_16x16x32_bf16 v[96:99], v[140:143], v[172:175], v[96:99]
	s_setprio 0
	s_barrier
	s_mov_b32 m0, s27
	v_lshl_add_u64 v[198:199], v[194:195], 0, s[82:83]
	ds_read_b128 v[176:179], v228
	ds_read_b128 v[180:183], v228 offset:2048
	ds_read_b128 v[184:187], v229
	ds_read_b128 v[188:191], v229 offset:2048
	global_load_lds_dwordx4 v[198:199], off
	v_lshl_add_u64 v[194:195], v[194:195], 0, s[96:97]
	s_mov_b32 m0, s31
	s_nop 0
	global_load_lds_dwordx4 v[194:195], off
	s_barrier
	s_waitcnt lgkmcnt(0)
	s_setprio 1
	s_waitcnt lgkmcnt(0)
	v_mfma_f32_16x16x32_bf16 v[56:59], v[176:179], v[144:147], v[56:59]
	v_mfma_f32_16x16x32_bf16 v[64:67], v[180:183], v[144:147], v[64:67]
	v_mfma_f32_16x16x32_bf16 v[72:75], v[176:179], v[148:151], v[72:75]
	v_mfma_f32_16x16x32_bf16 v[76:79], v[180:183], v[148:151], v[76:79]
	v_mfma_f32_16x16x32_bf16 v[80:83], v[176:179], v[160:163], v[80:83]
	v_mfma_f32_16x16x32_bf16 v[84:87], v[180:183], v[160:163], v[84:87]
	v_mfma_f32_16x16x32_bf16 v[88:91], v[176:179], v[164:167], v[88:91]
	v_mfma_f32_16x16x32_bf16 v[92:95], v[180:183], v[164:167], v[92:95]
	v_mfma_f32_16x16x32_bf16 v[56:59], v[184:187], v[152:155], v[56:59]
	v_mfma_f32_16x16x32_bf16 v[64:67], v[188:191], v[152:155], v[64:67]
	v_mfma_f32_16x16x32_bf16 v[72:75], v[184:187], v[156:159], v[72:75]
	v_mfma_f32_16x16x32_bf16 v[76:79], v[188:191], v[156:159], v[76:79]
	v_mfma_f32_16x16x32_bf16 v[80:83], v[184:187], v[168:171], v[80:83]
	v_mfma_f32_16x16x32_bf16 v[84:87], v[188:191], v[168:171], v[84:87]
	v_mfma_f32_16x16x32_bf16 v[88:91], v[184:187], v[172:175], v[88:91]
	v_mfma_f32_16x16x32_bf16 v[92:95], v[188:191], v[172:175], v[92:95]
	s_setprio 0
	s_mov_b32 m0, s1
	v_lshl_add_u64 v[194:195], v[192:193], 0, s[82:83]
	s_barrier
	ds_read_b128 v[144:147], v222 offset:49152
	ds_read_b128 v[148:151], v222 offset:51200
	ds_read_b128 v[152:155], v223 offset:49152
	ds_read_b128 v[156:159], v223 offset:51200
	ds_read_b128 v[160:163], v222 offset:53248
	ds_read_b128 v[164:167], v222 offset:55296
	ds_read_b128 v[168:171], v223 offset:53248
	ds_read_b128 v[172:175], v223 offset:55296
	global_load_lds_dwordx4 v[194:195], off
	v_lshl_add_u64 v[192:193], v[192:193], 0, s[96:97]
	s_mov_b32 m0, s34
	s_nop 0
	global_load_lds_dwordx4 v[192:193], off
	s_barrier
	s_waitcnt lgkmcnt(0)
	s_setprio 1
	s_waitcnt lgkmcnt(0)
	v_mfma_f32_16x16x32_bf16 v[32:35], v[128:131], v[144:147], v[32:35]
	v_mfma_f32_16x16x32_bf16 v[36:39], v[132:135], v[144:147], v[36:39]
	v_mfma_f32_16x16x32_bf16 v[40:43], v[128:131], v[148:151], v[40:43]
	v_mfma_f32_16x16x32_bf16 v[44:47], v[132:135], v[148:151], v[44:47]
	v_mfma_f32_16x16x32_bf16 v[48:51], v[128:131], v[160:163], v[48:51]
	v_mfma_f32_16x16x32_bf16 v[52:55], v[132:135], v[160:163], v[52:55]
	v_mfma_f32_16x16x32_bf16 v[60:63], v[128:131], v[164:167], v[60:63]
	v_mfma_f32_16x16x32_bf16 v[68:71], v[132:135], v[164:167], v[68:71]
	v_mfma_f32_16x16x32_bf16 v[32:35], v[136:139], v[152:155], v[32:35]
	v_mfma_f32_16x16x32_bf16 v[36:39], v[140:143], v[152:155], v[36:39]
	v_mfma_f32_16x16x32_bf16 v[40:43], v[136:139], v[156:159], v[40:43]
	v_mfma_f32_16x16x32_bf16 v[44:47], v[140:143], v[156:159], v[44:47]
	v_mfma_f32_16x16x32_bf16 v[48:51], v[136:139], v[168:171], v[48:51]
	v_mfma_f32_16x16x32_bf16 v[52:55], v[140:143], v[168:171], v[52:55]
	v_mfma_f32_16x16x32_bf16 v[60:63], v[136:139], v[172:175], v[60:63]
	v_mfma_f32_16x16x32_bf16 v[68:71], v[140:143], v[172:175], v[68:71]
	s_setprio 0
	s_barrier
	s_mov_b32 m0, s19
	v_lshl_add_u64 v[128:129], v[196:197], 0, s[82:83]
	global_load_lds_dwordx4 v[128:129], off
	v_lshl_add_u64 v[128:129], v[196:197], 0, s[96:97]
	s_mov_b32 m0, s18
	s_nop 0
	global_load_lds_dwordx4 v[128:129], off
	s_waitcnt vmcnt(6)
	s_barrier
; #define LDA(dst,b,h) _Pragma("unroll") for(int m=0;m<4;++m) _Pragma("unroll") for(int k=0;k<2;++k) \
;     dst[m][k]=*reinterpret_cast<const bf16x8*>(SA(b,h)+(wr*64+m*16)*128+koff[k])
; #define LDB(dst,b,h) _Pragma("unroll") for(int n=0;n<2;++n) _Pragma("unroll") for(int k=0;k<2;++k) \
;     dst[n][k]=*reinterpret_cast<const bf16x8*>(SB(b,h)+(wc*32+n*16)*128+koff[k])
; #define MMA(ai,bj,Af,Bf) do{__builtin_amdgcn_s_setprio(1); \
;     _Pragma("unroll") for(int m=0;m<4;++m) _Pragma("unroll") for(int n=0;n<2;++n) _Pragma("unroll") for(int k=0;k<2;++k) \
;       acc[ai][bj][m][n]=__builtin_amdgcn_mfma_f32_16x16x32_bf16(Bf[n][k],Af[m][k],acc[ai][bj][m][n],0,0,0); \
;     __builtin_amdgcn_s_setprio(0);}while(0)
; #define WAIT_L(n) asm volatile("s_waitcnt lgkmcnt(" #n ")":::"memory")
; #define BAR __builtin_amdgcn_s_barrier()
; #define SCHED __builtin_amdgcn_sched_barrier(0)
; #define STAGE_A(b,h,kt) do{ unsigned char* _d = SA(b,h) + wbase; \
;     if constexpr (BLK) { const char* _s = baseA + ((size_t)(h)*(K/64) + (kt)) * 16384; GLDS(_s + voa, _d); GLDS(_s + 8192 + voa, _d + 8192); } \
;     else { const char* _s = baseA + ((size_t)(h)*128*K + (kt)*64) * 2; GLDS(_s + voa, _d); GLDS(_s + (size_t)128*K + voa, _d + 8192); } }while(0)
; template <int K, int EPI, bool MIX = false>
; __device__ __forceinline__ void gemm_phase(const Params& p, const u16* __restrict__ A, const u16* __restrict__ Bt,
;                            const float* __restrict__ rs_in, float* __restrict__ ssq_out, float alpha, bool rev = false) {
;     ...
;       for (int t = 0; t < nt - 2; t += 2) KBODY(t);
;     }
;     ...
;     const int cpm = pm, cpn = pn;
;     float rsq[2][4];
;     if constexpr (EPI == EPI_SWIGLU || EPI == EPI_Z || MIX) {
;       const float* rsrc = MIX ? p.ssqb : rs_in;
;       int fr_p = fr;
;       asm volatile("" : "+v"(fr_p));
; #pragma unroll
;       for (int ai = 0; ai < 2; ++ai)
; #pragma unroll
;         for (int m = 0; m < 4; ++m) rsq[ai][m] = rsrc[cpm * 256 + ai * 128 + wr * 64 + m * 16 + fr_p];
;     }
;     ++it;
;     id = item_id(it);
;     const bool more = id < ntiles;
;     if (rev) id = ntiles - 1 - id;
;     {
;       LDB(B0,0,0); SCHED; LDA(At,0,0); STAGE_A(1,1,nt-1);
;       WAIT_L(8); BAR; WAIT_L(0); MMA(0,0,At,B0); BAR; SCHED;
;       if (more) SETUP_TILE();
	s_setprio 1
	v_mfma_f32_16x16x32_bf16 v[0:3], v[176:179], v[144:147], v[0:3]
	v_mfma_f32_16x16x32_bf16 v[4:7], v[180:183], v[144:147], v[4:7]
	v_mfma_f32_16x16x32_bf16 v[8:11], v[176:179], v[148:151], v[8:11]
	v_mfma_f32_16x16x32_bf16 v[12:15], v[180:183], v[148:151], v[12:15]
	v_mfma_f32_16x16x32_bf16 v[16:19], v[176:179], v[160:163], v[16:19]
	v_mfma_f32_16x16x32_bf16 v[20:23], v[180:183], v[160:163], v[20:23]
	v_mfma_f32_16x16x32_bf16 v[24:27], v[176:179], v[164:167], v[24:27]
	v_mfma_f32_16x16x32_bf16 v[28:31], v[180:183], v[164:167], v[28:31]
	v_mfma_f32_16x16x32_bf16 v[0:3], v[184:187], v[152:155], v[0:3]
	v_mfma_f32_16x16x32_bf16 v[4:7], v[188:191], v[152:155], v[4:7]
	v_mfma_f32_16x16x32_bf16 v[8:11], v[184:187], v[156:159], v[8:11]
	v_mfma_f32_16x16x32_bf16 v[12:15], v[188:191], v[156:159], v[12:15]
	v_mfma_f32_16x16x32_bf16 v[16:19], v[184:187], v[168:171], v[16:19]
	v_mfma_f32_16x16x32_bf16 v[20:23], v[188:191], v[168:171], v[20:23]
	v_mfma_f32_16x16x32_bf16 v[24:27], v[184:187], v[172:175], v[24:27]
	v_mfma_f32_16x16x32_bf16 v[28:31], v[188:191], v[172:175], v[28:31]
	s_setprio 0
	s_add_i32 s2, s2, 2
	s_add_u32 s8, s8, 0x100
	s_addc_u32 s9, s9, 0
	s_add_u32 s6, s6, 0x100
	s_addc_u32 s7, s7, 0
	s_add_u32 s4, s4, 0x100
	s_addc_u32 s5, s5, 0
	s_cmp_lt_u32 s2, 28
	s_barrier
	s_cbranch_scc1 .LBB0_183
	v_mov_b32_e32 v128, v219
	s_lshl_b32 s15, s12, 8
	s_add_i32 s15, s15, s13
	v_add_u32_e32 v128, s15, v128
	v_readlane_b32 s52, v254, 32
	v_ashrrev_i32_e32 v129, 31, v128
	v_readlane_b32 s64, v254, 44
	v_readlane_b32 s65, v254, 45
	s_add_i32 s74, s74, 1
	v_readlane_b32 s2, v255, 6
	v_lshl_add_u64 v[128:129], v[128:129], 2, s[64:65]
	global_load_dword v242, v[128:129], off
	global_load_dword v241, v[128:129], off offset:64
	global_load_dword v240, v[128:129], off offset:128
	global_load_dword v239, v[128:129], off offset:192
	global_load_dword v238, v[128:129], off offset:512
	global_load_dword v237, v[128:129], off offset:576
	global_load_dword v236, v[128:129], off offset:640
	global_load_dword v235, v[128:129], off offset:704
	ds_read_b128 v[136:139], v220
	ds_read_b128 v[140:143], v220 offset:2048
	ds_read_b128 v[148:151], v221
	ds_read_b128 v[144:147], v221 offset:2048
	s_mul_i32 s2, s74, s2
	v_readlane_b32 s4, v255, 17
	s_add_i32 s2, s2, s4
	v_readlane_b32 s53, v254, 33
	v_readlane_b32 s54, v254, 34
	v_readlane_b32 s55, v254, 35
	v_readlane_b32 s56, v254, 36
	v_readlane_b32 s57, v254, 37
	v_readlane_b32 s58, v254, 38
	v_readlane_b32 s59, v254, 39
	v_readlane_b32 s60, v254, 40
	v_readlane_b32 s61, v254, 41
	v_readlane_b32 s62, v254, 42
	v_readlane_b32 s63, v254, 43
	v_readlane_b32 s66, v254, 46
	v_readlane_b32 s67, v254, 47
	v_lshl_add_u64 v[128:129], s[16:17], 0, v[208:209]
	s_mov_b64 s[4:5], 0x80f80
	s_mov_b32 m0, s28
	v_lshl_add_u64 v[130:131], v[128:129], 0, s[4:5]
	s_mov_b64 s[4:5], 0xc0f80
	ds_read_b128 v[152:155], v222
	ds_read_b128 v[156:159], v222 offset:2048
	ds_read_b128 v[180:183], v223
	ds_read_b128 v[164:167], v223 offset:2048
	ds_read_b128 v[160:163], v222 offset:4096
	ds_read_b128 v[168:171], v222 offset:6144
	ds_read_b128 v[176:179], v223 offset:4096
	ds_read_b128 v[172:175], v223 offset:6144
	global_load_lds_dwordx4 v[130:131], off
	v_lshl_add_u64 v[128:129], v[128:129], 0, s[4:5]
	s_mov_b32 m0, s22
	s_nop 0
	global_load_lds_dwordx4 v[128:129], off
	s_waitcnt lgkmcnt(8)
	s_barrier
	s_waitcnt lgkmcnt(0)
	s_setprio 1
	s_waitcnt lgkmcnt(0)
	v_mfma_f32_16x16x32_bf16 v[124:127], v[136:139], v[152:155], v[124:127]
	s_cmpk_lt_i32 s2, 0xf00
	s_cselect_b64 s[4:5], -1, 0
	s_cmpk_gt_i32 s2, 0xeff
	v_mfma_f32_16x16x32_bf16 v[120:123], v[140:143], v[152:155], v[120:123]
	v_mfma_f32_16x16x32_bf16 v[116:119], v[136:139], v[156:159], v[116:119]
	v_mfma_f32_16x16x32_bf16 v[112:115], v[140:143], v[156:159], v[112:115]
	v_mfma_f32_16x16x32_bf16 v[108:111], v[136:139], v[160:163], v[108:111]
	v_mfma_f32_16x16x32_bf16 v[104:107], v[140:143], v[160:163], v[104:107]
	v_mfma_f32_16x16x32_bf16 v[100:103], v[136:139], v[168:171], v[100:103]
	v_mfma_f32_16x16x32_bf16 v[96:99], v[140:143], v[168:171], v[96:99]
	v_mfma_f32_16x16x32_bf16 v[124:127], v[148:151], v[180:183], v[124:127]
	v_mfma_f32_16x16x32_bf16 v[120:123], v[144:147], v[180:183], v[120:123]
	v_mfma_f32_16x16x32_bf16 v[116:119], v[148:151], v[164:167], v[116:119]
	v_mfma_f32_16x16x32_bf16 v[112:115], v[144:147], v[164:167], v[112:115]
	v_mfma_f32_16x16x32_bf16 v[108:111], v[148:151], v[176:179], v[108:111]
	v_mfma_f32_16x16x32_bf16 v[104:107], v[144:147], v[176:179], v[104:107]
	v_mfma_f32_16x16x32_bf16 v[128:131], v[148:151], v[172:175], v[100:103]
	v_mfma_f32_16x16x32_bf16 v[132:135], v[144:147], v[172:175], v[96:99]
	s_setprio 0
	s_barrier
	s_mov_b32 s75, s25
	s_cbranch_scc1 .LBB0_186
	s_mul_hi_i32 s6, s2, 0x66666667
	s_lshr_b32 s7, s6, 31
	s_ashr_i32 s6, s6, 6
	s_add_i32 s6, s6, s7
	s_lshl_b32 s7, s6, 3
	s_mulk_i32 s6, 0xff60
	s_add_i32 s6, s6, s2
	s_and_b32 s2, s2, 7
	s_or_b32 s12, s7, s2
	s_ashr_i32 s75, s6, 3
	s_lshl_b32 s6, s12, 8
	s_ashr_i32 s7, s6, 31
	s_lshl_b64 s[6:7], s[6:7], 12
	s_add_u32 s16, s90, s6
	s_addc_u32 s17, s91, s7
	s_lshl_b32 s6, s75, 8
	s_ashr_i32 s7, s6, 31
	v_readlane_b32 s52, v254, 16
	s_lshl_b64 s[6:7], s[6:7], 12
	v_readlane_b32 s66, v254, 30
	v_readlane_b32 s67, v254, 31
	s_add_u32 s20, s66, s6
	s_addc_u32 s21, s67, s7
	s_add_u32 s44, s20, 0x80000
	s_addc_u32 s45, s21, 0
	v_readlane_b32 s53, v254, 17
	v_readlane_b32 s54, v254, 18
	v_readlane_b32 s55, v254, 19
	v_readlane_b32 s56, v254, 20
	v_readlane_b32 s57, v254, 21
	v_readlane_b32 s58, v254, 22
	v_readlane_b32 s59, v254, 23
	v_readlane_b32 s60, v254, 24
	v_readlane_b32 s61, v254, 25
	v_readlane_b32 s62, v254, 26
	v_readlane_b32 s63, v254, 27
	v_readlane_b32 s64, v254, 28
	v_readlane_b32 s65, v254, 29

; __global__ void __launch_bounds__(NTHR) fwd_megakernel(Params p) {
;     ...
;   run_phase<3>(p); grid.sync();
.LBB0_307:
	s_waitcnt vmcnt(0) lgkmcnt(0)
	s_barrier
	s_mov_b64 s[0:1], exec
	v_readlane_b32 s2, v255, 1
	v_readlane_b32 s3, v255, 2
	s_and_b64 s[2:3], s[0:1], s[2:3]
	v_readlane_b32 s69, v255, 3
	s_mov_b64 exec, s[2:3]
	s_cbranch_execz .LBB0_317
	buffer_wbl2 sc1
	s_waitcnt vmcnt(0)
	v_readlane_b32 s2, v254, 24
	v_readlane_b32 s3, v254, 25
	v_readlane_b32 s4, v255, 3
	s_load_dword s5, s[72:73], 0x0
	s_nop 3
	s_add_u32 s2, s2, 0x10000000
	s_addc_u32 s3, s3, 0
	s_and_b32 s4, s4, 7
	s_lshl_b32 s4, s4, 8
	s_add_i32 s4, s4, 0x100
	v_mov_b32_e32 v2, 0
	v_mov_b32_e32 v3, 1
	v_mov_b32_e32 v0, s4
	s_nop 3
	global_atomic_add v3, v2, v3, s[2:3] sc0 sc1
	s_waitcnt lgkmcnt(0)
	s_mul_i32 s5, s5, 3
	s_add_i32 s5, s5, -1
	s_waitcnt vmcnt(0)
	v_readfirstlane_b32 s4, v3
	s_nop 3
	s_cmp_lg_u32 s4, s5
	s_cbranch_scc1 .Lfb3_poll0
	v_mov_b32_e32 v1, 1
	global_atomic_add v2, v1, s[2:3] offset:256 sc1
	global_atomic_add v2, v1, s[2:3] offset:512 sc1
	global_atomic_add v2, v1, s[2:3] offset:768 sc1
	global_atomic_add v2, v1, s[2:3] offset:1024 sc1
	global_atomic_add v2, v1, s[2:3] offset:1280 sc1
	global_atomic_add v2, v1, s[2:3] offset:1536 sc1
	global_atomic_add v2, v1, s[2:3] offset:1792 sc1
	global_atomic_add v2, v1, s[2:3] offset:2048 sc1
	s_branch .Lfb3_done

; __global__ void __launch_bounds__(NTHR) fwd_megakernel(Params p) {
;     ...
;   run_phase<3>(p); grid.sync();
.Lfb3_poll:
	global_load_dword v1, v0, s[2:3] sc1
	s_waitcnt vmcnt(0)
	v_readfirstlane_b32 s4, v1
	s_nop 3
	s_cmpk_ge_u32 s4, 3
	s_cbranch_scc1 .Lfb3_done
	s_sleep 1
	s_add_u32 s6, s6, 1
	s_cmpk_lt_u32 s6, 0x7fff
	s_cbranch_scc1 .Lfb3_poll

; __device__ __forceinline__ void phase_mixer(const Params& p) {
;     ...
;   phase_gate(p);
;   __syncthreads();
; }
; __global__ void __launch_bounds__(NTHR) fwd_megakernel(Params p) {
;     ...
;   run_phase<4>(p); grid.sync();
.LBB0_349:
	s_waitcnt vmcnt(0) lgkmcnt(0)
	s_barrier
	s_barrier
	s_mov_b64 s[0:1], exec
	v_readlane_b32 s2, v255, 1
	v_readlane_b32 s3, v255, 2
	s_and_b64 s[2:3], s[0:1], s[2:3]
	s_mov_b64 exec, s[2:3]
	s_cbranch_execz .LBB0_359
	buffer_wbl2 sc1
	s_waitcnt vmcnt(0)
	v_readlane_b32 s2, v254, 24
	v_readlane_b32 s3, v254, 25
	v_readlane_b32 s4, v255, 3
	s_load_dword s5, s[72:73], 0x0
	s_nop 3
	s_add_u32 s2, s2, 0x10000000
	s_addc_u32 s3, s3, 0
	s_and_b32 s4, s4, 7
	s_lshl_b32 s4, s4, 8
	s_add_i32 s4, s4, 0x100
	v_mov_b32_e32 v2, 0
	v_mov_b32_e32 v3, 1
	v_mov_b32_e32 v0, s4
	s_nop 3
	global_atomic_add v3, v2, v3, s[2:3] sc0 sc1
	s_waitcnt lgkmcnt(0)
	s_mul_i32 s5, s5, 4
	s_add_i32 s5, s5, -1
	s_waitcnt vmcnt(0)
	v_readfirstlane_b32 s4, v3
	s_nop 3
	s_cmp_lg_u32 s4, s5
	s_cbranch_scc1 .Lfb4_poll0
	v_mov_b32_e32 v1, 1
	global_atomic_add v2, v1, s[2:3] offset:256 sc1
	global_atomic_add v2, v1, s[2:3] offset:512 sc1
	global_atomic_add v2, v1, s[2:3] offset:768 sc1
	global_atomic_add v2, v1, s[2:3] offset:1024 sc1
	global_atomic_add v2, v1, s[2:3] offset:1280 sc1
	global_atomic_add v2, v1, s[2:3] offset:1536 sc1
	global_atomic_add v2, v1, s[2:3] offset:1792 sc1
	global_atomic_add v2, v1, s[2:3] offset:2048 sc1
	s_branch .Lfb4_done

; __global__ void __launch_bounds__(NTHR) fwd_megakernel(Params p) {
;     ...
;   run_phase<4>(p); grid.sync();
.Lfb4_poll:
	global_load_dword v1, v0, s[2:3] sc1
	s_waitcnt vmcnt(0)
	v_readfirstlane_b32 s4, v1
	s_nop 3
	s_cmpk_ge_u32 s4, 4
	s_cbranch_scc1 .Lfb4_done
	s_sleep 1
	s_add_u32 s6, s6, 1
	s_cmpk_lt_u32 s6, 0x7fff
	s_cbranch_scc1 .Lfb4_poll

; #define WAIT_V(n) asm volatile("s_waitcnt vmcnt(" #n ")":::"memory")
; #define BAR __builtin_amdgcn_s_barrier()
; #define STAGE_A(b,h,kt) do{ unsigned char* _d = SA(b,h) + wbase; \
;     if constexpr (BLK) { const char* _s = baseA + ((size_t)(h)*(K/64) + (kt)) * 16384; GLDS(_s + voa, _d); GLDS(_s + 8192 + voa, _d + 8192); } \
;     else { const char* _s = baseA + ((size_t)(h)*128*K + (kt)*64) * 2; GLDS(_s + voa, _d); GLDS(_s + (size_t)128*K + voa, _d + 8192); } }while(0)
; #define STAGE_B(b,h,kt) do{ unsigned char* _d = SB(b,h) + wbase; \
;     if constexpr (BLK) { const char* _s = ((h)?baseB1:baseB0) + (size_t)(kt) * 16384; GLDS(_s + voa, _d); GLDS(_s + 8192 + voa, _d + 8192); } \
;     else { const char* _s = ((h)?baseB1:baseB0) + (kt)*128; GLDS(_s + voa, _d); GLDS(_s + (size_t)128*K + voa, _d + 8192); } }while(0)
; template <int K, int EPI, bool MIX = false>
; __device__ __forceinline__ void gemm_phase(const Params& p, const u16* __restrict__ A, const u16* __restrict__ Bt,
;                            const float* __restrict__ rs_in, float* __restrict__ ssq_out, float alpha, bool rev = false) {
;     ...
;   int tid = threadIdx.x;
;   asm volatile("" : "+v"(tid));
;   const int wid = __builtin_amdgcn_readfirstlane(tid >> 6);
;   const int lane = tid & 63, wr = wid >> 2, wc = wid & 3, fr = lane & 15, fq = lane >> 4;
;   const int wbase = wid * 1024;
;   int koff[2];
;   koff[0] = lds_off32(fr, fq); koff[1] = lds_off32(fr, 4 + fq);
;   int it = 0;
;   int id = item_id(0);
;   if (id >= ntiles) return;
;   if (rev) id = ntiles - 1 - id;
;   int pm, pn;
;   const char *baseA, *baseB0, *baseB1;
;   unsigned voa;
;   {
;     const int R = tid >> 3, C = ((tid & 7) ^ ((R >> 1) & 7)) * 8;
;     voa = (unsigned)(R * (BLK ? 64 : K) + C) * 2u;
;   }
;     ...
;   SETUP_TILE();
;   STAGE_B(0,0,0); STAGE_A(0,0,0); STAGE_B(0,1,0); STAGE_A(0,1,0);
;   if (wr == 1) BAR;
;   WAIT_V(4); BAR;
;   STAGE_B(1,0,1); STAGE_A(1,0,1); STAGE_B(1,1,1);
;   WAIT_V(6); BAR;
;   for (;;) {
.LBB0_362:
	s_add_i32 s65, s34, 0x18000
	s_mov_b64 s[18:19], 0x80
	v_lshl_add_u64 v[8:9], v[0:1], 0, s[18:19]
	s_mov_b32 m0, s65
	s_mov_b64 s[20:21], 0x40080
	s_add_i32 s68, s34, 0x1a000
	s_waitcnt vmcnt(4)
	s_barrier
	global_load_lds_dwordx4 v[8:9], off
	v_lshl_add_u64 v[8:9], v[0:1], 0, s[20:21]
	s_mov_b32 m0, s68
	s_add_i32 s69, s34, 0x8000
	global_load_lds_dwordx4 v[8:9], off
	v_lshl_add_u64 v[8:9], v[2:3], 0, s[18:19]
	s_mov_b32 m0, s69
	s_add_i32 s70, s34, 0xa000
	global_load_lds_dwordx4 v[8:9], off
	v_lshl_add_u64 v[2:3], v[2:3], 0, s[20:21]
	s_mov_b32 m0, s70
	s_add_i32 s71, s34, 0x1c000
	s_mov_b64 s[22:23], 0x80080
	global_load_lds_dwordx4 v[2:3], off
	v_lshl_add_u64 v[2:3], v[0:1], 0, s[22:23]
	s_mov_b32 m0, s71
	s_mov_b64 s[24:25], 0xc0080
	s_add_i32 s72, s34, 0x1e000
	global_load_lds_dwordx4 v[2:3], off
	v_lshl_add_u64 v[0:1], v[0:1], 0, s[24:25]
	s_mov_b32 m0, s72
	s_and_b32 s6, s6, 3
	global_load_lds_dwordx4 v[0:1], off
	s_lshl_b32 s7, s6, 12
	v_and_b32_e32 v233, 15, v4
	v_bfe_u32 v0, v4, 4, 2
	v_bfe_u32 v2, v4, 1, 3
	s_or_b32 s28, s7, 0x10000
	s_lshl_b32 s30, s5, 13
	s_or_b32 s31, s7, 0x14000
	s_or_b32 s38, s7, 0x18000
	s_or_b32 s7, s7, 0x1c000
	s_lshl_b32 s73, s5, 6
	v_lshlrev_b32_e32 v1, 7, v233
	v_xor_b32_e32 v3, v0, v2
	v_bitop3_b32 v0, v0, v2, 4 bitop3:0x36
	s_waitcnt vmcnt(6)
	s_cmpk_lt_u32 s4, 0x100
	v_lshl_or_b32 v3, v3, 4, v1
	v_lshl_or_b32 v0, v0, 4, v1
	s_cselect_b64 s[26:27], -1, 0
	s_lshl_b32 s4, s6, 5
	s_mov_b32 s29, 0
	v_and_b32_e32 v232, 63, v4
	v_add_u32_e32 v222, v6, v5
	v_mov_b32_e32 v223, v221
	v_add_u32_e32 v234, s28, v3
	v_add_u32_e32 v235, s28, v0
	v_add_u32_e32 v236, s30, v3
	v_add_u32_e32 v237, s30, v0
	s_add_i32 s74, s34, 0xc000
	s_add_i32 s75, s34, 0xe000
	v_add_u32_e32 v238, s31, v3
	v_add_u32_e32 v239, s31, v0
	s_mov_b64 s[30:31], 0x100
	s_mov_b64 s[36:37], 0x40100
	v_add_u32_e32 v240, s38, v3
	v_add_u32_e32 v241, s38, v0
	v_add_u32_e32 v242, s7, v3
	v_add_u32_e32 v243, s7, v0
	s_mov_b64 s[38:39], 0x180
	s_mov_b64 s[40:41], 0x40180
	v_mov_b32_e32 v244, 0x358637bd
	s_mov_b32 s76, 0x800000
	s_mov_b64 s[46:47], 0x900
	s_mov_b64 s[48:49], 0x40900
	s_mov_b64 s[50:51], 0x980
	s_mov_b64 s[58:59], 0x40980
	v_mbcnt_hi_u32_b32 v245, -1, v231
	s_lshl_b32 s28, s4, 1
	s_mov_b32 s77, s29
	s_barrier
	s_mov_b64 vcc, exec
	s_branch .LBB0_364

; #define SCHED __builtin_amdgcn_sched_barrier(0)
; template <int K, int EPI, bool MIX = false>
; __device__ __forceinline__ void gemm_phase(const Params& p, const u16* __restrict__ A, const u16* __restrict__ Bt,
;                            const float* __restrict__ rs_in, float* __restrict__ ssq_out, float alpha, bool rev = false) {
;     ...
;     f32x4 acc[2][2][4][2];
; #pragma unroll
;     for (int a = 0; a < 2; ++a)
; #pragma unroll
;       for (int b = 0; b < 2; ++b)
; #pragma unroll
;         for (int m = 0; m < 4; ++m)
; #pragma unroll
;           for (int n = 0; n < 2; ++n) acc[a][b][m][n] = f32x4{0.f, 0.f, 0.f, 0.f};
;     bf16x8 At[4][2], B0[2][2], B1[2][2];
;     asm volatile("" ::: "memory");
;     SCHED;
.LBB0_364:
	s_mov_b32 s78, s33
	v_mov_b32_e32 v0, 0
	s_mov_b32 s33, -2
	s_mov_b64 s[4:5], s[16:17]
	s_mov_b64 s[6:7], s[8:9]
	s_mov_b64 s[60:61], s[12:13]
	s_waitcnt lgkmcnt(0)
	v_mov_b32_e32 v1, v0
	v_mov_b32_e32 v2, v0
	v_mov_b32_e32 v3, v0
	v_mov_b32_e32 v4, v0
	v_mov_b32_e32 v5, v0
	v_mov_b32_e32 v6, v0
	v_mov_b32_e32 v7, v0
	v_mov_b32_e32 v56, v0
	v_mov_b32_e32 v57, v0
	v_mov_b32_e32 v58, v0
	v_mov_b32_e32 v59, v0
	v_mov_b32_e32 v60, v0
	v_mov_b32_e32 v61, v0
	v_mov_b32_e32 v62, v0
	v_mov_b32_e32 v63, v0
	v_mov_b32_e32 v104, v0
	v_mov_b32_e32 v105, v0
	v_mov_b32_e32 v106, v0
	v_mov_b32_e32 v107, v0
	v_mov_b32_e32 v108, v0
	v_mov_b32_e32 v109, v0
	v_mov_b32_e32 v110, v0
	v_mov_b32_e32 v111, v0
	v_mov_b32_e32 v80, v0
	v_mov_b32_e32 v81, v0
	v_mov_b32_e32 v82, v0
	v_mov_b32_e32 v83, v0
	v_mov_b32_e32 v84, v0
	v_mov_b32_e32 v85, v0
	v_mov_b32_e32 v86, v0
	v_mov_b32_e32 v87, v0
	v_mov_b32_e32 v72, v0
	v_mov_b32_e32 v73, v0
	v_mov_b32_e32 v74, v0
	v_mov_b32_e32 v75, v0
	v_mov_b32_e32 v76, v0
	v_mov_b32_e32 v77, v0
	v_mov_b32_e32 v78, v0
	v_mov_b32_e32 v79, v0
	v_mov_b32_e32 v48, v0
	v_mov_b32_e32 v49, v0
	v_mov_b32_e32 v50, v0
	v_mov_b32_e32 v51, v0
	v_mov_b32_e32 v52, v0
	v_mov_b32_e32 v53, v0
	v_mov_b32_e32 v54, v0
	v_mov_b32_e32 v55, v0
	v_mov_b32_e32 v32, v0
	v_mov_b32_e32 v33, v0
	v_mov_b32_e32 v34, v0
	v_mov_b32_e32 v35, v0
	v_mov_b32_e32 v36, v0
	v_mov_b32_e32 v37, v0
	v_mov_b32_e32 v38, v0
	v_mov_b32_e32 v39, v0
	v_mov_b32_e32 v16, v0
	v_mov_b32_e32 v17, v0
	v_mov_b32_e32 v18, v0
	v_mov_b32_e32 v19, v0
	v_mov_b32_e32 v20, v0
	v_mov_b32_e32 v21, v0
	v_mov_b32_e32 v22, v0
	v_mov_b32_e32 v23, v0
	v_mov_b32_e32 v96, v0
	v_mov_b32_e32 v97, v0
	v_mov_b32_e32 v98, v0
	v_mov_b32_e32 v99, v0
	v_mov_b32_e32 v100, v0
	v_mov_b32_e32 v101, v0
	v_mov_b32_e32 v102, v0
	v_mov_b32_e32 v103, v0
	v_mov_b32_e32 v64, v0
	v_mov_b32_e32 v65, v0
	v_mov_b32_e32 v66, v0
	v_mov_b32_e32 v67, v0
	v_mov_b32_e32 v68, v0
	v_mov_b32_e32 v69, v0
	v_mov_b32_e32 v70, v0
	v_mov_b32_e32 v71, v0
	v_mov_b32_e32 v40, v0
	v_mov_b32_e32 v41, v0
	v_mov_b32_e32 v42, v0
	v_mov_b32_e32 v43, v0
	v_mov_b32_e32 v44, v0
	v_mov_b32_e32 v45, v0
	v_mov_b32_e32 v46, v0
	v_mov_b32_e32 v47, v0
	v_mov_b32_e32 v24, v0
	v_mov_b32_e32 v25, v0
	v_mov_b32_e32 v26, v0
	v_mov_b32_e32 v27, v0
	v_mov_b32_e32 v28, v0
	v_mov_b32_e32 v29, v0
	v_mov_b32_e32 v30, v0
	v_mov_b32_e32 v31, v0
	v_mov_b32_e32 v128, v0
	v_mov_b32_e32 v129, v0
	v_mov_b32_e32 v130, v0
	v_mov_b32_e32 v131, v0
	v_mov_b32_e32 v132, v0
	v_mov_b32_e32 v133, v0
	v_mov_b32_e32 v134, v0
	v_mov_b32_e32 v135, v0
	v_mov_b32_e32 v120, v0
	v_mov_b32_e32 v121, v0
	v_mov_b32_e32 v122, v0
	v_mov_b32_e32 v123, v0
	v_mov_b32_e32 v124, v0
	v_mov_b32_e32 v125, v0
	v_mov_b32_e32 v126, v0
	v_mov_b32_e32 v127, v0
	v_mov_b32_e32 v88, v0
	v_mov_b32_e32 v89, v0
	v_mov_b32_e32 v90, v0
	v_mov_b32_e32 v91, v0
	v_mov_b32_e32 v92, v0
	v_mov_b32_e32 v93, v0
	v_mov_b32_e32 v94, v0
	v_mov_b32_e32 v95, v0
	v_mov_b32_e32 v12, v0
	v_mov_b32_e32 v13, v0
	v_mov_b32_e32 v14, v0
	v_mov_b32_e32 v15, v0
	v_mov_b32_e32 v8, v0
	v_mov_b32_e32 v9, v0
	v_mov_b32_e32 v10, v0
	v_mov_b32_e32 v11, v0
	s_cbranch_vccnz .Llate_p5_done
	s_barrier
.Llate_p5_done:
.LBB0_365:
	ds_read_b128 v[112:115], v234
	ds_read_b128 v[116:119], v234 offset:2048
	ds_read_b128 v[136:139], v235
	ds_read_b128 v[140:143], v235 offset:2048
	v_lshl_add_u64 v[192:193], s[6:7], 0, v[222:223]
	s_mov_b32 m0, s74
	v_lshl_add_u64 v[176:177], v[192:193], 0, s[22:23]
	ds_read_b128 v[144:147], v236
	ds_read_b128 v[148:151], v236 offset:2048
	ds_read_b128 v[152:155], v237
	ds_read_b128 v[156:159], v237 offset:2048
	ds_read_b128 v[160:163], v236 offset:4096
	ds_read_b128 v[164:167], v236 offset:6144
	ds_read_b128 v[168:171], v237 offset:4096
	ds_read_b128 v[172:175], v237 offset:6144
	global_load_lds_dwordx4 v[176:177], off
	v_lshl_add_u64 v[176:177], v[192:193], 0, s[24:25]
	s_mov_b32 m0, s75
	s_nop 0
	global_load_lds_dwordx4 v[176:177], off
	s_waitcnt lgkmcnt(8)
	s_barrier
	s_waitcnt lgkmcnt(0)
	s_setprio 1
	s_waitcnt lgkmcnt(0)
	v_mfma_f32_16x16x32_bf16 v[28:31], v[112:115], v[144:147], v[28:31]
	v_mfma_f32_16x16x32_bf16 v[24:27], v[116:119], v[144:147], v[24:27]
	v_mfma_f32_16x16x32_bf16 v[44:47], v[112:115], v[148:151], v[44:47]
	v_mfma_f32_16x16x32_bf16 v[40:43], v[116:119], v[148:151], v[40:43]
	v_mfma_f32_16x16x32_bf16 v[68:71], v[112:115], v[160:163], v[68:71]
	v_mfma_f32_16x16x32_bf16 v[64:67], v[116:119], v[160:163], v[64:67]
	v_mfma_f32_16x16x32_bf16 v[100:103], v[112:115], v[164:167], v[100:103]
	v_mfma_f32_16x16x32_bf16 v[96:99], v[116:119], v[164:167], v[96:99]
	v_mfma_f32_16x16x32_bf16 v[28:31], v[136:139], v[152:155], v[28:31]
	v_mfma_f32_16x16x32_bf16 v[24:27], v[140:143], v[152:155], v[24:27]
	v_mfma_f32_16x16x32_bf16 v[44:47], v[136:139], v[156:159], v[44:47]
	v_mfma_f32_16x16x32_bf16 v[40:43], v[140:143], v[156:159], v[40:43]
	v_mfma_f32_16x16x32_bf16 v[68:71], v[136:139], v[168:171], v[68:71]
	v_mfma_f32_16x16x32_bf16 v[64:67], v[140:143], v[168:171], v[64:67]
	v_mfma_f32_16x16x32_bf16 v[100:103], v[136:139], v[172:175], v[100:103]
	v_mfma_f32_16x16x32_bf16 v[96:99], v[140:143], v[172:175], v[96:99]
	s_setprio 0
	s_barrier
	v_lshl_add_u64 v[194:195], s[60:61], 0, v[222:223]
	s_mov_b32 m0, s42
	v_lshl_add_u64 v[196:197], v[194:195], 0, s[30:31]
	ds_read_b128 v[176:179], v238
	ds_read_b128 v[180:183], v238 offset:2048
	ds_read_b128 v[184:187], v239
	ds_read_b128 v[188:191], v239 offset:2048
	global_load_lds_dwordx4 v[196:197], off
	v_lshl_add_u64 v[196:197], v[194:195], 0, s[36:37]
	s_mov_b32 m0, s43
	s_nop 0
	global_load_lds_dwordx4 v[196:197], off
	s_barrier
	s_waitcnt lgkmcnt(0)
	s_setprio 1
	s_waitcnt lgkmcnt(0)
	v_mfma_f32_16x16x32_bf16 v[20:23], v[176:179], v[144:147], v[20:23]
	v_mfma_f32_16x16x32_bf16 v[16:19], v[180:183], v[144:147], v[16:19]
	v_mfma_f32_16x16x32_bf16 v[36:39], v[176:179], v[148:151], v[36:39]
	v_mfma_f32_16x16x32_bf16 v[32:35], v[180:183], v[148:151], v[32:35]
	v_mfma_f32_16x16x32_bf16 v[52:55], v[176:179], v[160:163], v[52:55]
	v_mfma_f32_16x16x32_bf16 v[48:51], v[180:183], v[160:163], v[48:51]
	v_mfma_f32_16x16x32_bf16 v[76:79], v[176:179], v[164:167], v[76:79]
	v_mfma_f32_16x16x32_bf16 v[72:75], v[180:183], v[164:167], v[72:75]
	v_mfma_f32_16x16x32_bf16 v[20:23], v[184:187], v[152:155], v[20:23]
	v_mfma_f32_16x16x32_bf16 v[16:19], v[188:191], v[152:155], v[16:19]
	v_mfma_f32_16x16x32_bf16 v[36:39], v[184:187], v[156:159], v[36:39]
	v_mfma_f32_16x16x32_bf16 v[32:35], v[188:191], v[156:159], v[32:35]
	v_mfma_f32_16x16x32_bf16 v[52:55], v[184:187], v[168:171], v[52:55]
	v_mfma_f32_16x16x32_bf16 v[48:51], v[188:191], v[168:171], v[48:51]
	v_mfma_f32_16x16x32_bf16 v[76:79], v[184:187], v[172:175], v[76:79]
	v_mfma_f32_16x16x32_bf16 v[72:75], v[188:191], v[172:175], v[72:75]
	s_setprio 0
	s_mov_b32 m0, s34
	v_lshl_add_u64 v[196:197], v[192:193], 0, s[30:31]
	s_barrier
	ds_read_b128 v[144:147], v236 offset:16384
	ds_read_b128 v[148:151], v236 offset:18432
	ds_read_b128 v[152:155], v237 offset:16384
	ds_read_b128 v[156:159], v237 offset:18432
	ds_read_b128 v[160:163], v236 offset:20480
	ds_read_b128 v[164:167], v236 offset:22528
	ds_read_b128 v[168:171], v237 offset:20480
	ds_read_b128 v[172:175], v237 offset:22528
	global_load_lds_dwordx4 v[196:197], off
	v_lshl_add_u64 v[196:197], v[192:193], 0, s[36:37]
	s_mov_b32 m0, s44
	s_nop 0
	global_load_lds_dwordx4 v[196:197], off
	s_barrier
	s_waitcnt lgkmcnt(0)
	s_setprio 1
	s_waitcnt lgkmcnt(0)
	v_mfma_f32_16x16x32_bf16 v[84:87], v[112:115], v[144:147], v[84:87]
	v_mfma_f32_16x16x32_bf16 v[80:83], v[116:119], v[144:147], v[80:83]
	v_mfma_f32_16x16x32_bf16 v[108:111], v[112:115], v[148:151], v[108:111]
	v_mfma_f32_16x16x32_bf16 v[104:107], v[116:119], v[148:151], v[104:107]
	v_mfma_f32_16x16x32_bf16 v[60:63], v[112:115], v[160:163], v[60:63]
	v_mfma_f32_16x16x32_bf16 v[56:59], v[116:119], v[160:163], v[56:59]
	v_mfma_f32_16x16x32_bf16 v[4:7], v[112:115], v[164:167], v[4:7]
	v_mfma_f32_16x16x32_bf16 v[0:3], v[116:119], v[164:167], v[0:3]
	v_mfma_f32_16x16x32_bf16 v[84:87], v[136:139], v[152:155], v[84:87]
	v_mfma_f32_16x16x32_bf16 v[80:83], v[140:143], v[152:155], v[80:83]
	v_mfma_f32_16x16x32_bf16 v[108:111], v[136:139], v[156:159], v[108:111]
	v_mfma_f32_16x16x32_bf16 v[104:107], v[140:143], v[156:159], v[104:107]
	v_mfma_f32_16x16x32_bf16 v[60:63], v[136:139], v[168:171], v[60:63]
	v_mfma_f32_16x16x32_bf16 v[56:59], v[140:143], v[168:171], v[56:59]
	v_mfma_f32_16x16x32_bf16 v[4:7], v[136:139], v[172:175], v[4:7]
	v_mfma_f32_16x16x32_bf16 v[0:3], v[140:143], v[172:175], v[0:3]
	s_setprio 0
	s_barrier
	v_lshl_add_u64 v[196:197], s[4:5], 0, v[222:223]
	s_mov_b32 m0, s45
	v_lshl_add_u64 v[112:113], v[196:197], 0, s[30:31]
	global_load_lds_dwordx4 v[112:113], off
	v_lshl_add_u64 v[112:113], v[196:197], 0, s[36:37]
	s_mov_b32 m0, s62
	s_nop 0
	global_load_lds_dwordx4 v[112:113], off
	s_waitcnt vmcnt(6)
	s_barrier
	s_setprio 1
	v_mfma_f32_16x16x32_bf16 v[120:123], v[176:179], v[148:151], v[120:123]
	v_mfma_f32_16x16x32_bf16 v[124:127], v[180:183], v[148:151], v[124:127]
	v_mfma_f32_16x16x32_bf16 v[88:91], v[176:179], v[160:163], v[88:91]
	v_mfma_f32_16x16x32_bf16 v[92:95], v[180:183], v[160:163], v[92:95]
	v_mfma_f32_16x16x32_bf16 v[12:15], v[176:179], v[164:167], v[12:15]
	v_mfma_f32_16x16x32_bf16 v[8:11], v[180:183], v[164:167], v[8:11]
	v_mfma_f32_16x16x32_bf16 v[112:115], v[176:179], v[144:147], v[128:131]
	v_mfma_f32_16x16x32_bf16 v[116:119], v[180:183], v[144:147], v[132:135]
	v_mfma_f32_16x16x32_bf16 v[120:123], v[184:187], v[156:159], v[120:123]
	v_mfma_f32_16x16x32_bf16 v[124:127], v[188:191], v[156:159], v[124:127]
	v_mfma_f32_16x16x32_bf16 v[88:91], v[184:187], v[168:171], v[88:91]
	v_mfma_f32_16x16x32_bf16 v[92:95], v[188:191], v[168:171], v[92:95]
	v_mfma_f32_16x16x32_bf16 v[12:15], v[184:187], v[172:175], v[12:15]
	v_mfma_f32_16x16x32_bf16 v[8:11], v[188:191], v[172:175], v[8:11]
	v_mfma_f32_16x16x32_bf16 v[112:115], v[184:187], v[152:155], v[112:115]
	v_mfma_f32_16x16x32_bf16 v[116:119], v[188:191], v[152:155], v[116:119]
	s_setprio 0
	s_barrier
	ds_read_b128 v[128:131], v240
	ds_read_b128 v[132:135], v240 offset:2048
	ds_read_b128 v[136:139], v241
	ds_read_b128 v[140:143], v241 offset:2048
	s_mov_b64 s[80:81], 0x80100
	s_mov_b32 m0, s63
	v_lshl_add_u64 v[176:177], v[192:193], 0, s[80:81]
	s_mov_b64 s[80:81], 0xc0100
	ds_read_b128 v[144:147], v236 offset:32768
	ds_read_b128 v[148:151], v236 offset:34816
	ds_read_b128 v[152:155], v237 offset:32768
	ds_read_b128 v[156:159], v237 offset:34816
	ds_read_b128 v[160:163], v236 offset:36864
	ds_read_b128 v[164:167], v236 offset:38912
	ds_read_b128 v[168:171], v237 offset:36864
	ds_read_b128 v[172:175], v237 offset:38912
	global_load_lds_dwordx4 v[176:177], off
	v_lshl_add_u64 v[176:177], v[192:193], 0, s[80:81]
	s_mov_b32 m0, s64
	s_nop 0
	global_load_lds_dwordx4 v[176:177], off
	s_waitcnt lgkmcnt(8)
	s_barrier
	s_waitcnt lgkmcnt(0)
	s_setprio 1
	s_waitcnt lgkmcnt(0)
	v_mfma_f32_16x16x32_bf16 v[28:31], v[128:131], v[144:147], v[28:31]
	v_mfma_f32_16x16x32_bf16 v[24:27], v[132:135], v[144:147], v[24:27]
	v_mfma_f32_16x16x32_bf16 v[44:47], v[128:131], v[148:151], v[44:47]
	v_mfma_f32_16x16x32_bf16 v[40:43], v[132:135], v[148:151], v[40:43]
	v_mfma_f32_16x16x32_bf16 v[68:71], v[128:131], v[160:163], v[68:71]
	v_mfma_f32_16x16x32_bf16 v[64:67], v[132:135], v[160:163], v[64:67]
	v_mfma_f32_16x16x32_bf16 v[100:103], v[128:131], v[164:167], v[100:103]
	v_mfma_f32_16x16x32_bf16 v[96:99], v[132:135], v[164:167], v[96:99]
	v_mfma_f32_16x16x32_bf16 v[28:31], v[136:139], v[152:155], v[28:31]
	v_mfma_f32_16x16x32_bf16 v[24:27], v[140:143], v[152:155], v[24:27]
	v_mfma_f32_16x16x32_bf16 v[44:47], v[136:139], v[156:159], v[44:47]
	v_mfma_f32_16x16x32_bf16 v[40:43], v[140:143], v[156:159], v[40:43]
	v_mfma_f32_16x16x32_bf16 v[68:71], v[136:139], v[168:171], v[68:71]
	v_mfma_f32_16x16x32_bf16 v[64:67], v[140:143], v[168:171], v[64:67]
	v_mfma_f32_16x16x32_bf16 v[100:103], v[136:139], v[172:175], v[100:103]
	v_mfma_f32_16x16x32_bf16 v[96:99], v[140:143], v[172:175], v[96:99]
	s_setprio 0
	s_barrier
	s_mov_b32 m0, s65
	v_lshl_add_u64 v[198:199], v[194:195], 0, s[38:39]
	ds_read_b128 v[176:179], v242
	ds_read_b128 v[180:183], v242 offset:2048
	ds_read_b128 v[184:187], v243
	ds_read_b128 v[188:191], v243 offset:2048
	global_load_lds_dwordx4 v[198:199], off
	v_lshl_add_u64 v[194:195], v[194:195], 0, s[40:41]
	s_mov_b32 m0, s68
	s_nop 0
	global_load_lds_dwordx4 v[194:195], off
	s_barrier
	s_waitcnt lgkmcnt(0)
	s_setprio 1
	s_waitcnt lgkmcnt(0)
	v_mfma_f32_16x16x32_bf16 v[20:23], v[176:179], v[144:147], v[20:23]
	v_mfma_f32_16x16x32_bf16 v[16:19], v[180:183], v[144:147], v[16:19]
	v_mfma_f32_16x16x32_bf16 v[36:39], v[176:179], v[148:151], v[36:39]
	v_mfma_f32_16x16x32_bf16 v[32:35], v[180:183], v[148:151], v[32:35]
	v_mfma_f32_16x16x32_bf16 v[52:55], v[176:179], v[160:163], v[52:55]
	v_mfma_f32_16x16x32_bf16 v[48:51], v[180:183], v[160:163], v[48:51]
	v_mfma_f32_16x16x32_bf16 v[76:79], v[176:179], v[164:167], v[76:79]
	v_mfma_f32_16x16x32_bf16 v[72:75], v[180:183], v[164:167], v[72:75]
	v_mfma_f32_16x16x32_bf16 v[20:23], v[184:187], v[152:155], v[20:23]
	v_mfma_f32_16x16x32_bf16 v[16:19], v[188:191], v[152:155], v[16:19]
	v_mfma_f32_16x16x32_bf16 v[36:39], v[184:187], v[156:159], v[36:39]
	v_mfma_f32_16x16x32_bf16 v[32:35], v[188:191], v[156:159], v[32:35]
	v_mfma_f32_16x16x32_bf16 v[52:55], v[184:187], v[168:171], v[52:55]
	v_mfma_f32_16x16x32_bf16 v[48:51], v[188:191], v[168:171], v[48:51]
	v_mfma_f32_16x16x32_bf16 v[76:79], v[184:187], v[172:175], v[76:79]
	v_mfma_f32_16x16x32_bf16 v[72:75], v[188:191], v[172:175], v[72:75]
	s_setprio 0
	s_mov_b32 m0, s69
	v_lshl_add_u64 v[194:195], v[192:193], 0, s[38:39]
	s_barrier
	ds_read_b128 v[144:147], v236 offset:49152
	ds_read_b128 v[148:151], v236 offset:51200
	ds_read_b128 v[152:155], v237 offset:49152
	ds_read_b128 v[156:159], v237 offset:51200
	ds_read_b128 v[160:163], v236 offset:53248
	ds_read_b128 v[164:167], v236 offset:55296
	ds_read_b128 v[168:171], v237 offset:53248
	ds_read_b128 v[172:175], v237 offset:55296
	global_load_lds_dwordx4 v[194:195], off
	v_lshl_add_u64 v[192:193], v[192:193], 0, s[40:41]
	s_mov_b32 m0, s70
	s_nop 0
	global_load_lds_dwordx4 v[192:193], off
	s_barrier
	s_waitcnt lgkmcnt(0)
	s_setprio 1
	s_waitcnt lgkmcnt(0)
	v_mfma_f32_16x16x32_bf16 v[84:87], v[128:131], v[144:147], v[84:87]
	v_mfma_f32_16x16x32_bf16 v[80:83], v[132:135], v[144:147], v[80:83]
	v_mfma_f32_16x16x32_bf16 v[108:111], v[128:131], v[148:151], v[108:111]
	v_mfma_f32_16x16x32_bf16 v[104:107], v[132:135], v[148:151], v[104:107]
	v_mfma_f32_16x16x32_bf16 v[60:63], v[128:131], v[160:163], v[60:63]
	v_mfma_f32_16x16x32_bf16 v[56:59], v[132:135], v[160:163], v[56:59]
	v_mfma_f32_16x16x32_bf16 v[4:7], v[128:131], v[164:167], v[4:7]
	v_mfma_f32_16x16x32_bf16 v[0:3], v[132:135], v[164:167], v[0:3]
	v_mfma_f32_16x16x32_bf16 v[84:87], v[136:139], v[152:155], v[84:87]
	v_mfma_f32_16x16x32_bf16 v[80:83], v[140:143], v[152:155], v[80:83]
	v_mfma_f32_16x16x32_bf16 v[108:111], v[136:139], v[156:159], v[108:111]
	v_mfma_f32_16x16x32_bf16 v[104:107], v[140:143], v[156:159], v[104:107]
	v_mfma_f32_16x16x32_bf16 v[60:63], v[136:139], v[168:171], v[60:63]
	v_mfma_f32_16x16x32_bf16 v[56:59], v[140:143], v[168:171], v[56:59]
	v_mfma_f32_16x16x32_bf16 v[4:7], v[136:139], v[172:175], v[4:7]
	v_mfma_f32_16x16x32_bf16 v[0:3], v[140:143], v[172:175], v[0:3]
	s_setprio 0
	s_barrier
	s_mov_b32 m0, s71
	v_lshl_add_u64 v[128:129], v[196:197], 0, s[38:39]
	global_load_lds_dwordx4 v[128:129], off
	v_lshl_add_u64 v[128:129], v[196:197], 0, s[40:41]
	s_mov_b32 m0, s72
	s_nop 0
	global_load_lds_dwordx4 v[128:129], off
	s_waitcnt vmcnt(6)
	s_barrier
	s_setprio 1
	v_mfma_f32_16x16x32_bf16 v[112:115], v[176:179], v[144:147], v[112:115]
	v_mfma_f32_16x16x32_bf16 v[128:131], v[184:187], v[152:155], v[112:115]
	v_mfma_f32_16x16x32_bf16 v[112:115], v[180:183], v[144:147], v[116:119]
	v_mfma_f32_16x16x32_bf16 v[132:135], v[188:191], v[152:155], v[112:115]
	v_mfma_f32_16x16x32_bf16 v[112:115], v[176:179], v[148:151], v[120:123]
	v_mfma_f32_16x16x32_bf16 v[120:123], v[184:187], v[156:159], v[112:115]
	v_mfma_f32_16x16x32_bf16 v[112:115], v[180:183], v[148:151], v[124:127]
	v_mfma_f32_16x16x32_bf16 v[88:91], v[176:179], v[160:163], v[88:91]
	v_mfma_f32_16x16x32_bf16 v[92:95], v[180:183], v[160:163], v[92:95]
	v_mfma_f32_16x16x32_bf16 v[12:15], v[176:179], v[164:167], v[12:15]
	v_mfma_f32_16x16x32_bf16 v[8:11], v[180:183], v[164:167], v[8:11]
	v_mfma_f32_16x16x32_bf16 v[124:127], v[188:191], v[156:159], v[112:115]
	v_mfma_f32_16x16x32_bf16 v[88:91], v[184:187], v[168:171], v[88:91]
	v_mfma_f32_16x16x32_bf16 v[92:95], v[188:191], v[168:171], v[92:95]
	v_mfma_f32_16x16x32_bf16 v[12:15], v[184:187], v[172:175], v[12:15]
	v_mfma_f32_16x16x32_bf16 v[8:11], v[188:191], v[172:175], v[8:11]
	s_setprio 0
	s_add_i32 s33, s33, 2
	s_add_u32 s60, s60, 0x100
	s_addc_u32 s61, s61, 0
	s_add_u32 s6, s6, 0x100
	s_addc_u32 s7, s7, 0
	s_add_u32 s4, s4, 0x100
	s_addc_u32 s5, s5, 0
	s_cmp_lt_u32 s33, 14
	s_barrier
; template <int K, int EPI, bool MIX = false>
; __device__ __forceinline__ void gemm_phase(const Params& p, const u16* __restrict__ A, const u16* __restrict__ Bt,
;                            const float* __restrict__ rs_in, float* __restrict__ ssq_out, float alpha, bool rev = false) {
;     ...
;       for (int t = 0; t < nt / 2; t += 2) KBODY(t);
;       {
;           int fr_m = fr;
;           asm volatile("" : "+v"(fr_m));
; #pragma unroll
;           for (int ai = 0; ai < 2; ++ai)
; #pragma unroll
;             for (int m = 0; m < 4; ++m) {
;               const int row = pm * 256 + ai * 128 + wr * 64 + m * 16 + fr_m;
;               const float ra = rsqrtf(p.ssqa[row] * (1.f / 1024.f) + 1e-6f);
;               const float rb = rsqrtf(p.ssqb[row] * (1.f / 1024.f) + 1e-6f);
;               const float f = ra * __builtin_amdgcn_rcpf(rb);
; #pragma unroll
;               for (int bj = 0; bj < 2; ++bj)
; #pragma unroll
;                 for (int n = 0; n < 2; ++n) acc[ai][bj][m][n] *= f;
;             }
;       }
	s_cbranch_scc1 .LBB0_365
	v_mov_b32_e32 v112, v233
	s_lshl_b32 s79, s35, 8
	s_add_i32 s79, s79, s73
	v_add_u32_e32 v112, s79, v112
	v_ashrrev_i32_e32 v113, 31, v112
	v_lshlrev_b64 v[112:113], 2, v[112:113]
	v_lshl_add_u64 v[138:139], s[86:87], 0, v[112:113]
	global_load_dword v114, v[138:139], off
	v_lshl_add_u64 v[136:137], s[88:89], 0, v[112:113]
	global_load_dword v112, v[136:137], off
	s_mov_b32 s33, 14
	s_mov_b64 s[4:5], s[16:17]
	s_mov_b64 s[6:7], s[8:9]
	s_mov_b64 s[60:61], s[12:13]
	s_waitcnt vmcnt(0)
	v_fmamk_f32 v114, v114, 0x3a800000, v244
	v_cmp_gt_f32_e32 vcc, s76, v114
	v_mul_f32_e32 v115, 0x4b800000, v114
	v_fmamk_f32 v112, v112, 0x3a800000, v244
	v_cndmask_b32_e32 v114, v114, v115, vcc
	v_rsq_f32_e32 v114, v114
	v_mul_f32_e32 v113, 0x4b800000, v112
	v_mul_f32_e32 v115, 0x45800000, v114
	v_cndmask_b32_e32 v114, v114, v115, vcc
	v_cmp_gt_f32_e32 vcc, s76, v112
	s_nop 1
	v_cndmask_b32_e32 v112, v112, v113, vcc
	v_rsq_f32_e32 v112, v112
	s_nop 0
	v_mul_f32_e32 v113, 0x45800000, v112
	v_cndmask_b32_e32 v112, v112, v113, vcc
	v_rcp_f32_e32 v112, v112
	s_nop 0
	v_mul_f32_e32 v112, v114, v112
	v_pk_mul_f32 v[30:31], v[30:31], v[112:113] op_sel_hi:[1,0]
	v_pk_mul_f32 v[28:29], v[28:29], v[112:113] op_sel_hi:[1,0]
	v_pk_mul_f32 v[26:27], v[26:27], v[112:113] op_sel_hi:[1,0]
	v_pk_mul_f32 v[24:25], v[24:25], v[112:113] op_sel_hi:[1,0]
	v_pk_mul_f32 v[22:23], v[22:23], v[112:113] op_sel_hi:[1,0]
	v_pk_mul_f32 v[20:21], v[20:21], v[112:113] op_sel_hi:[1,0]
	v_pk_mul_f32 v[18:19], v[18:19], v[112:113] op_sel_hi:[1,0]
	v_pk_mul_f32 v[16:17], v[16:17], v[112:113] op_sel_hi:[1,0]
	global_load_dword v112, v[138:139], off offset:64
	s_waitcnt vmcnt(0)
	v_fmamk_f32 v112, v112, 0x3a800000, v244
	v_cmp_gt_f32_e32 vcc, s76, v112
	v_mul_f32_e32 v113, 0x4b800000, v112
	s_nop 0
	v_cndmask_b32_e32 v112, v112, v113, vcc
	v_rsq_f32_e32 v112, v112
	s_nop 0
	v_mul_f32_e32 v113, 0x45800000, v112
	v_cndmask_b32_e32 v112, v112, v113, vcc
	global_load_dword v113, v[136:137], off offset:64
	s_waitcnt vmcnt(0)
	v_fmamk_f32 v113, v113, 0x3a800000, v244
	v_cmp_gt_f32_e32 vcc, s76, v113
	v_mul_f32_e32 v114, 0x4b800000, v113
	s_nop 0
	v_cndmask_b32_e32 v113, v113, v114, vcc
	v_rsq_f32_e32 v113, v113
	s_nop 0
	v_mul_f32_e32 v114, 0x45800000, v113
	v_cndmask_b32_e32 v113, v113, v114, vcc
	v_rcp_f32_e32 v113, v113
	s_nop 0
	v_mul_f32_e32 v112, v112, v113
	v_pk_mul_f32 v[46:47], v[46:47], v[112:113] op_sel_hi:[1,0]
	v_pk_mul_f32 v[44:45], v[44:45], v[112:113] op_sel_hi:[1,0]
	v_pk_mul_f32 v[42:43], v[42:43], v[112:113] op_sel_hi:[1,0]
	v_pk_mul_f32 v[40:41], v[40:41], v[112:113] op_sel_hi:[1,0]
	v_pk_mul_f32 v[38:39], v[38:39], v[112:113] op_sel_hi:[1,0]
	v_pk_mul_f32 v[36:37], v[36:37], v[112:113] op_sel_hi:[1,0]
	v_pk_mul_f32 v[34:35], v[34:35], v[112:113] op_sel_hi:[1,0]
	v_pk_mul_f32 v[32:33], v[32:33], v[112:113] op_sel_hi:[1,0]
	global_load_dword v112, v[138:139], off offset:128
	s_waitcnt vmcnt(0)
	v_fmamk_f32 v112, v112, 0x3a800000, v244
	v_cmp_gt_f32_e32 vcc, s76, v112
	v_mul_f32_e32 v113, 0x4b800000, v112
	s_nop 0
	v_cndmask_b32_e32 v112, v112, v113, vcc
	v_rsq_f32_e32 v112, v112
	s_nop 0
	v_mul_f32_e32 v113, 0x45800000, v112
	v_cndmask_b32_e32 v112, v112, v113, vcc
	global_load_dword v113, v[136:137], off offset:128
	s_waitcnt vmcnt(0)
	v_fmamk_f32 v113, v113, 0x3a800000, v244
	v_cmp_gt_f32_e32 vcc, s76, v113
	v_mul_f32_e32 v114, 0x4b800000, v113
	s_nop 0
	v_cndmask_b32_e32 v113, v113, v114, vcc
	v_rsq_f32_e32 v113, v113
	s_nop 0
	v_mul_f32_e32 v114, 0x45800000, v113
	v_cndmask_b32_e32 v113, v113, v114, vcc
	v_rcp_f32_e32 v113, v113
	s_nop 0
	v_mul_f32_e32 v112, v112, v113
	v_pk_mul_f32 v[70:71], v[70:71], v[112:113] op_sel_hi:[1,0]
	v_pk_mul_f32 v[68:69], v[68:69], v[112:113] op_sel_hi:[1,0]
	v_pk_mul_f32 v[66:67], v[66:67], v[112:113] op_sel_hi:[1,0]
	v_pk_mul_f32 v[64:65], v[64:65], v[112:113] op_sel_hi:[1,0]
	v_pk_mul_f32 v[54:55], v[54:55], v[112:113] op_sel_hi:[1,0]
	v_pk_mul_f32 v[52:53], v[52:53], v[112:113] op_sel_hi:[1,0]
	v_pk_mul_f32 v[50:51], v[50:51], v[112:113] op_sel_hi:[1,0]
	v_pk_mul_f32 v[48:49], v[48:49], v[112:113] op_sel_hi:[1,0]
	global_load_dword v112, v[138:139], off offset:192
	s_waitcnt vmcnt(0)
	v_fmamk_f32 v112, v112, 0x3a800000, v244
	v_cmp_gt_f32_e32 vcc, s76, v112
	v_mul_f32_e32 v113, 0x4b800000, v112
	s_nop 0
	v_cndmask_b32_e32 v112, v112, v113, vcc
	v_rsq_f32_e32 v112, v112
	s_nop 0
	v_mul_f32_e32 v113, 0x45800000, v112
	v_cndmask_b32_e32 v112, v112, v113, vcc
	global_load_dword v113, v[136:137], off offset:192
	s_waitcnt vmcnt(0)
	v_fmamk_f32 v113, v113, 0x3a800000, v244
	v_cmp_gt_f32_e32 vcc, s76, v113
	v_mul_f32_e32 v114, 0x4b800000, v113
	s_nop 0
	v_cndmask_b32_e32 v113, v113, v114, vcc
	v_rsq_f32_e32 v113, v113
	s_nop 0
	v_mul_f32_e32 v114, 0x45800000, v113
	v_cndmask_b32_e32 v113, v113, v114, vcc
	v_rcp_f32_e32 v113, v113
	s_nop 0
	v_mul_f32_e32 v140, v112, v113
	v_pk_mul_f32 v[112:113], v[96:97], v[140:141] op_sel_hi:[1,0]
	global_load_dword v96, v[138:139], off offset:512
	v_pk_mul_f32 v[114:115], v[98:99], v[140:141] op_sel_hi:[1,0]
	v_pk_mul_f32 v[118:119], v[102:103], v[140:141] op_sel_hi:[1,0]
	v_pk_mul_f32 v[116:117], v[100:101], v[140:141] op_sel_hi:[1,0]
	v_pk_mul_f32 v[78:79], v[78:79], v[140:141] op_sel_hi:[1,0]
	v_pk_mul_f32 v[76:77], v[76:77], v[140:141] op_sel_hi:[1,0]
	v_pk_mul_f32 v[74:75], v[74:75], v[140:141] op_sel_hi:[1,0]
	v_pk_mul_f32 v[72:73], v[72:73], v[140:141] op_sel_hi:[1,0]
	s_waitcnt vmcnt(0)
; template <int K, int EPI, bool MIX = false>
; __device__ __forceinline__ void gemm_phase(const Params& p, const u16* __restrict__ A, const u16* __restrict__ Bt,
;                            const float* __restrict__ rs_in, float* __restrict__ ssq_out, float alpha, bool rev = false) {
;     ...
;       {
;           int fr_m = fr;
;           asm volatile("" : "+v"(fr_m));
; #pragma unroll
;           for (int ai = 0; ai < 2; ++ai)
; #pragma unroll
;             for (int m = 0; m < 4; ++m) {
;               const int row = pm * 256 + ai * 128 + wr * 64 + m * 16 + fr_m;
;               const float ra = rsqrtf(p.ssqa[row] * (1.f / 1024.f) + 1e-6f);
;               const float rb = rsqrtf(p.ssqb[row] * (1.f / 1024.f) + 1e-6f);
;               const float f = ra * __builtin_amdgcn_rcpf(rb);
; #pragma unroll
;               for (int bj = 0; bj < 2; ++bj)
; #pragma unroll
;                 for (int n = 0; n < 2; ++n) acc[ai][bj][m][n] *= f;
;             }
;       }
	v_fmamk_f32 v96, v96, 0x3a800000, v244
	v_cmp_gt_f32_e32 vcc, s76, v96
	v_mul_f32_e32 v97, 0x4b800000, v96
	s_nop 0
	v_cndmask_b32_e32 v96, v96, v97, vcc
	v_rsq_f32_e32 v96, v96
	s_nop 0
	v_mul_f32_e32 v97, 0x45800000, v96
	v_cndmask_b32_e32 v96, v96, v97, vcc
	global_load_dword v97, v[136:137], off offset:512
	s_waitcnt vmcnt(0)
	v_fmamk_f32 v97, v97, 0x3a800000, v244
	v_cmp_gt_f32_e32 vcc, s76, v97
	v_mul_f32_e32 v98, 0x4b800000, v97
	s_nop 0
	v_cndmask_b32_e32 v97, v97, v98, vcc
	v_rsq_f32_e32 v97, v97
	s_nop 0
	v_mul_f32_e32 v98, 0x45800000, v97
	v_cndmask_b32_e32 v97, v97, v98, vcc
	v_rcp_f32_e32 v97, v97
	s_nop 0
	v_mul_f32_e32 v140, v96, v97
	v_pk_mul_f32 v[96:97], v[80:81], v[140:141] op_sel_hi:[1,0]
	v_pk_mul_f32 v[80:81], v[128:129], v[140:141] op_sel_hi:[1,0]
	global_load_dword v128, v[138:139], off offset:576
	v_pk_mul_f32 v[98:99], v[82:83], v[140:141] op_sel_hi:[1,0]
	v_pk_mul_f32 v[82:83], v[130:131], v[140:141] op_sel_hi:[1,0]
	v_pk_mul_f32 v[102:103], v[86:87], v[140:141] op_sel_hi:[1,0]
	v_pk_mul_f32 v[100:101], v[84:85], v[140:141] op_sel_hi:[1,0]
	v_pk_mul_f32 v[86:87], v[134:135], v[140:141] op_sel_hi:[1,0]
	v_pk_mul_f32 v[84:85], v[132:133], v[140:141] op_sel_hi:[1,0]
	s_waitcnt vmcnt(0)
	v_fmamk_f32 v128, v128, 0x3a800000, v244
	v_cmp_gt_f32_e32 vcc, s76, v128
	v_mul_f32_e32 v129, 0x4b800000, v128
	s_nop 0
	v_cndmask_b32_e32 v128, v128, v129, vcc
	v_rsq_f32_e32 v128, v128
	s_nop 0
	v_mul_f32_e32 v129, 0x45800000, v128
	v_cndmask_b32_e32 v128, v128, v129, vcc
	global_load_dword v129, v[136:137], off offset:576
	s_waitcnt vmcnt(0)
	v_fmamk_f32 v129, v129, 0x3a800000, v244
	v_cmp_gt_f32_e32 vcc, s76, v129
	v_mul_f32_e32 v130, 0x4b800000, v129
	s_nop 0
	v_cndmask_b32_e32 v129, v129, v130, vcc
	v_rsq_f32_e32 v129, v129
	s_nop 0
	v_mul_f32_e32 v130, 0x45800000, v129
	v_cndmask_b32_e32 v129, v129, v130, vcc
	v_rcp_f32_e32 v129, v129
	s_nop 0
	v_mul_f32_e32 v140, v128, v129
	v_pk_mul_f32 v[128:129], v[104:105], v[140:141] op_sel_hi:[1,0]
	v_pk_mul_f32 v[104:105], v[120:121], v[140:141] op_sel_hi:[1,0]
	global_load_dword v120, v[138:139], off offset:640
	v_pk_mul_f32 v[130:131], v[106:107], v[140:141] op_sel_hi:[1,0]
	v_pk_mul_f32 v[106:107], v[122:123], v[140:141] op_sel_hi:[1,0]
	v_pk_mul_f32 v[134:135], v[110:111], v[140:141] op_sel_hi:[1,0]
	v_pk_mul_f32 v[132:133], v[108:109], v[140:141] op_sel_hi:[1,0]
	v_pk_mul_f32 v[110:111], v[126:127], v[140:141] op_sel_hi:[1,0]
	v_pk_mul_f32 v[108:109], v[124:125], v[140:141] op_sel_hi:[1,0]
	s_waitcnt vmcnt(0)
	v_fmamk_f32 v120, v120, 0x3a800000, v244
	v_cmp_gt_f32_e32 vcc, s76, v120
	v_mul_f32_e32 v121, 0x4b800000, v120
	s_nop 0
	v_cndmask_b32_e32 v120, v120, v121, vcc
	v_rsq_f32_e32 v120, v120
	s_nop 0
	v_mul_f32_e32 v121, 0x45800000, v120
	v_cndmask_b32_e32 v120, v120, v121, vcc
	global_load_dword v121, v[136:137], off offset:640
	s_waitcnt vmcnt(0)
	v_fmamk_f32 v121, v121, 0x3a800000, v244
	v_cmp_gt_f32_e32 vcc, s76, v121
	v_mul_f32_e32 v122, 0x4b800000, v121
	s_nop 0
	v_cndmask_b32_e32 v121, v121, v122, vcc
	v_rsq_f32_e32 v121, v121
	s_nop 0
	v_mul_f32_e32 v122, 0x45800000, v121
	v_cndmask_b32_e32 v121, v121, v122, vcc
	v_rcp_f32_e32 v121, v121
	s_nop 0
	v_mul_f32_e32 v140, v120, v121
	v_pk_mul_f32 v[120:121], v[56:57], v[140:141] op_sel_hi:[1,0]
	v_pk_mul_f32 v[56:57], v[88:89], v[140:141] op_sel_hi:[1,0]
	global_load_dword v88, v[138:139], off offset:704
	v_pk_mul_f32 v[122:123], v[58:59], v[140:141] op_sel_hi:[1,0]
	v_pk_mul_f32 v[58:59], v[90:91], v[140:141] op_sel_hi:[1,0]
	v_pk_mul_f32 v[126:127], v[62:63], v[140:141] op_sel_hi:[1,0]
	v_pk_mul_f32 v[124:125], v[60:61], v[140:141] op_sel_hi:[1,0]
	v_pk_mul_f32 v[62:63], v[94:95], v[140:141] op_sel_hi:[1,0]
	v_pk_mul_f32 v[60:61], v[92:93], v[140:141] op_sel_hi:[1,0]
	s_waitcnt vmcnt(0)
	v_fmamk_f32 v88, v88, 0x3a800000, v244
	v_cmp_gt_f32_e32 vcc, s76, v88
	v_mul_f32_e32 v89, 0x4b800000, v88
	s_nop 0
	v_cndmask_b32_e32 v88, v88, v89, vcc
	v_rsq_f32_e32 v88, v88
	s_nop 0
	v_mul_f32_e32 v89, 0x45800000, v88
	v_cndmask_b32_e32 v88, v88, v89, vcc
	global_load_dword v89, v[136:137], off offset:704
	s_waitcnt vmcnt(0)
	v_fmamk_f32 v89, v89, 0x3a800000, v244
	v_cmp_gt_f32_e32 vcc, s76, v89
	v_mul_f32_e32 v90, 0x4b800000, v89
	s_nop 0
	v_cndmask_b32_e32 v89, v89, v90, vcc
	v_rsq_f32_e32 v89, v89
	s_nop 0
	v_mul_f32_e32 v90, 0x45800000, v89
	v_cndmask_b32_e32 v89, v89, v90, vcc
	v_rcp_f32_e32 v89, v89
	s_nop 0
	v_mul_f32_e32 v136, v88, v89
	v_pk_mul_f32 v[90:91], v[6:7], v[136:137] op_sel_hi:[1,0]
	v_pk_mul_f32 v[88:89], v[4:5], v[136:137] op_sel_hi:[1,0]
	v_pk_mul_f32 v[94:95], v[2:3], v[136:137] op_sel_hi:[1,0]
	v_pk_mul_f32 v[92:93], v[0:1], v[136:137] op_sel_hi:[1,0]
	v_pk_mul_f32 v[2:3], v[14:15], v[136:137] op_sel_hi:[1,0]
	v_pk_mul_f32 v[0:1], v[12:13], v[136:137] op_sel_hi:[1,0]
	v_pk_mul_f32 v[6:7], v[10:11], v[136:137] op_sel_hi:[1,0]
	v_pk_mul_f32 v[4:5], v[8:9], v[136:137] op_sel_hi:[1,0]

; __global__ void __launch_bounds__(NTHR) fwd_megakernel(Params p) {
;     ...
;   run_phase<5>(p); grid.sync();
.LBB0_407:
	s_waitcnt vmcnt(0) lgkmcnt(0)
	s_barrier
	s_mov_b64 s[0:1], exec
	v_readlane_b32 s4, v255, 1
	v_readlane_b32 s5, v255, 2
	s_and_b64 s[4:5], s[0:1], s[4:5]
	s_mov_b64 exec, s[4:5]
	s_cbranch_execz .LBB0_417
	buffer_wbl2 sc1
	s_waitcnt vmcnt(0)
	v_readlane_b32 s4, v254, 24
	v_readlane_b32 s5, v254, 25
	v_readlane_b32 s6, v255, 3
	s_load_dword s7, s[72:73], 0x0
	s_nop 3
	s_add_u32 s4, s4, 0x10000000
	s_addc_u32 s5, s5, 0
	s_and_b32 s6, s6, 7
	s_lshl_b32 s6, s6, 8
	s_add_i32 s6, s6, 0x100
	v_mov_b32_e32 v2, 0
	v_mov_b32_e32 v3, 1
	v_mov_b32_e32 v0, s6
	s_nop 3
	global_atomic_add v3, v2, v3, s[4:5] sc0 sc1
	s_waitcnt lgkmcnt(0)
	s_mul_i32 s7, s7, 5
	s_add_i32 s7, s7, -1
	s_waitcnt vmcnt(0)
	v_readfirstlane_b32 s6, v3
	s_nop 3
	s_cmp_lg_u32 s6, s7
	s_cbranch_scc1 .Lfb5_poll0
	v_mov_b32_e32 v1, 1
	global_atomic_add v2, v1, s[4:5] offset:256 sc1
	global_atomic_add v2, v1, s[4:5] offset:512 sc1
	global_atomic_add v2, v1, s[4:5] offset:768 sc1
	global_atomic_add v2, v1, s[4:5] offset:1024 sc1
	global_atomic_add v2, v1, s[4:5] offset:1280 sc1
	global_atomic_add v2, v1, s[4:5] offset:1536 sc1
	global_atomic_add v2, v1, s[4:5] offset:1792 sc1
	global_atomic_add v2, v1, s[4:5] offset:2048 sc1
	s_branch .Lfb5_done
.Lfb5_poll0:
	s_mov_b32 s8, 0
.Lfb5_poll:
	global_load_dword v1, v0, s[4:5] sc1
	s_waitcnt vmcnt(0)
	v_readfirstlane_b32 s6, v1
	s_nop 3
	s_cmpk_ge_u32 s6, 5
	s_cbranch_scc1 .Lfb5_done
	s_sleep 1
	s_add_u32 s8, s8, 1
	s_cmpk_lt_u32 s8, 0x7fff
	s_cbranch_scc1 .Lfb5_poll

; #define WAIT_V(n) asm volatile("s_waitcnt vmcnt(" #n ")":::"memory")
; #define BAR __builtin_amdgcn_s_barrier()
; #define STAGE_A(b,h,kt) do{ unsigned char* _d = SA(b,h) + wbase; \
;     if constexpr (BLK) { const char* _s = baseA + ((size_t)(h)*(K/64) + (kt)) * 16384; GLDS(_s + voa, _d); GLDS(_s + 8192 + voa, _d + 8192); } \
;     else { const char* _s = baseA + ((size_t)(h)*128*K + (kt)*64) * 2; GLDS(_s + voa, _d); GLDS(_s + (size_t)128*K + voa, _d + 8192); } }while(0)
; #define STAGE_B(b,h,kt) do{ unsigned char* _d = SB(b,h) + wbase; \
;     if constexpr (BLK) { const char* _s = ((h)?baseB1:baseB0) + (size_t)(kt) * 16384; GLDS(_s + voa, _d); GLDS(_s + 8192 + voa, _d + 8192); } \
;     else { const char* _s = ((h)?baseB1:baseB0) + (kt)*128; GLDS(_s + voa, _d); GLDS(_s + (size_t)128*K + voa, _d + 8192); } }while(0)
; template <int K, int EPI, bool MIX = false>
; __device__ __forceinline__ void gemm_phase(const Params& p, const u16* __restrict__ A, const u16* __restrict__ Bt,
;                            const float* __restrict__ rs_in, float* __restrict__ ssq_out, float alpha, bool rev = false) {
;     ...
;   int tid = threadIdx.x;
;   asm volatile("" : "+v"(tid));
;   const int wid = __builtin_amdgcn_readfirstlane(tid >> 6);
;   const int lane = tid & 63, wr = wid >> 2, wc = wid & 3, fr = lane & 15, fq = lane >> 4;
;   const int wbase = wid * 1024;
;   int koff[2];
;   koff[0] = lds_off32(fr, fq); koff[1] = lds_off32(fr, 4 + fq);
;   int it = 0;
;   int id = item_id(0);
;   if (id >= ntiles) return;
;   if (rev) id = ntiles - 1 - id;
;   int pm, pn;
;   const char *baseA, *baseB0, *baseB1;
;   unsigned voa;
;   {
;     const int R = tid >> 3, C = ((tid & 7) ^ ((R >> 1) & 7)) * 8;
;     voa = (unsigned)(R * (BLK ? 64 : K) + C) * 2u;
;   }
;     ...
;   SETUP_TILE();
;   STAGE_B(0,0,0); STAGE_A(0,0,0); STAGE_B(0,1,0); STAGE_A(0,1,0);
;   if (wr == 1) BAR;
;   WAIT_V(4); BAR;
;   STAGE_B(1,0,1); STAGE_A(1,0,1); STAGE_B(1,1,1);
;   WAIT_V(6); BAR;
;   for (;;) {
.LBB0_420:
	s_add_i32 s62, s33, 0x18000
	s_mov_b64 s[16:17], 0x80
	v_lshl_add_u64 v[10:11], v[0:1], 0, s[16:17]
	s_mov_b32 m0, s62
	s_mov_b64 s[18:19], 0x40080
	s_add_i32 s63, s33, 0x1a000
	s_waitcnt vmcnt(4)
	s_barrier
	global_load_lds_dwordx4 v[10:11], off
	v_lshl_add_u64 v[0:1], v[0:1], 0, s[18:19]
	s_mov_b32 m0, s63
	s_add_i32 s64, s33, 0x8000
	global_load_lds_dwordx4 v[0:1], off
	v_lshl_add_u64 v[0:1], v[2:3], 0, s[16:17]
	s_mov_b32 m0, s64
	s_add_i32 s65, s33, 0xa000
	global_load_lds_dwordx4 v[0:1], off
	v_lshl_add_u64 v[0:1], v[2:3], 0, s[18:19]
	s_mov_b32 m0, s65
	s_add_i32 s68, s33, 0x1c000
	global_load_lds_dwordx4 v[0:1], off
	v_lshl_add_u64 v[0:1], v[4:5], 0, s[16:17]
	s_mov_b32 m0, s68
	s_add_i32 s69, s33, 0x1e000
	global_load_lds_dwordx4 v[0:1], off
	v_lshl_add_u64 v[0:1], v[4:5], 0, s[18:19]
	s_mov_b32 m0, s69
	s_and_b32 s22, s20, 3
	global_load_lds_dwordx4 v[0:1], off
	s_lshl_b32 s20, s22, 12
	s_or_b32 s24, s20, 0x10000
	s_lshl_b32 s25, s5, 13
	s_or_b32 s28, s20, 0x14000
	s_or_b32 s36, s20, 0x18000
	s_or_b32 s40, s20, 0x1c000
	s_lshl_b32 s70, s5, 6
	v_and_b32_e32 v223, 15, v8
	v_bfe_u32 v0, v8, 4, 2
	v_bfe_u32 v2, v8, 1, 3
	s_cmpk_lt_u32 s4, 0x100
	v_lshlrev_b32_e32 v1, 7, v223
	v_xor_b32_e32 v3, v0, v2
	v_bitop3_b32 v0, v0, v2, 4 bitop3:0x36
	s_waitcnt vmcnt(6)
	s_cselect_b64 s[20:21], -1, 0
	s_lshl_b32 s71, s22, 5
	v_lshl_or_b32 v3, v3, 4, v1
	v_lshl_or_b32 v0, v0, 4, v1
	s_and_b32 s4, s71, 32
	s_mov_b32 s23, 0
	v_and_b32_e32 v222, 63, v8
	v_add_u32_e32 v216, v7, v6
	v_mov_b32_e32 v217, v215
	v_add_u32_e32 v224, s24, v3
	v_add_u32_e32 v225, s24, v0
	v_add_u32_e32 v226, s25, v3
	v_add_u32_e32 v227, s25, v0
	s_mov_b64 s[24:25], 0x80080
	s_add_i32 s72, s33, 0xc000
	s_mov_b64 s[26:27], 0xc0080
	s_add_i32 s73, s33, 0xe000
	v_add_u32_e32 v228, s28, v3
	v_add_u32_e32 v229, s28, v0
	s_mov_b64 s[28:29], 0x100
	s_mov_b64 s[30:31], 0x40100
	v_add_u32_e32 v232, s36, v3
	v_add_u32_e32 v233, s36, v0
	s_mov_b64 s[36:37], 0x80100
	s_mov_b64 s[38:39], 0xc0100
	v_add_u32_e32 v234, s40, v3
	v_add_u32_e32 v235, s40, v0
	s_mov_b64 s[40:41], 0x180
	s_mov_b64 s[46:47], 0x40180
	s_mov_b64 s[48:49], 0x80f80
	s_mov_b64 s[50:51], 0xc0f80
	v_mov_b32_e32 v236, 0x358637bd
	s_mov_b32 s74, 0x800000
	s_lshl_b32 s22, s4, 1
	s_mov_b32 s75, s23
	s_barrier
	s_mov_b64 vcc, exec
	s_branch .LBB0_422

; #define SCHED __builtin_amdgcn_sched_barrier(0)
; template <int K, int EPI, bool MIX = false>
; __device__ __forceinline__ void gemm_phase(const Params& p, const u16* __restrict__ A, const u16* __restrict__ Bt,
;                            const float* __restrict__ rs_in, float* __restrict__ ssq_out, float alpha, bool rev = false) {
;     ...
;     f32x4 acc[2][2][4][2];
; #pragma unroll
;     for (int a = 0; a < 2; ++a)
; #pragma unroll
;       for (int b = 0; b < 2; ++b)
; #pragma unroll
;         for (int m = 0; m < 4; ++m)
; #pragma unroll
;           for (int n = 0; n < 2; ++n) acc[a][b][m][n] = f32x4{0.f, 0.f, 0.f, 0.f};
;     bf16x8 At[4][2], B0[2][2], B1[2][2];
;     asm volatile("" ::: "memory");
;     SCHED;
.LBB0_422:
	s_mov_b32 s76, s58
	v_mov_b32_e32 v0, 0
	s_mov_b32 s77, -2
	s_mov_b64 s[4:5], s[10:11]
	s_mov_b64 s[52:53], s[0:1]
	s_mov_b64 s[58:59], s[8:9]
	v_mov_b32_e32 v1, v0
	v_mov_b32_e32 v2, v0
	v_mov_b32_e32 v3, v0
	v_mov_b32_e32 v4, v0
	v_mov_b32_e32 v5, v0
	v_mov_b32_e32 v6, v0
	v_mov_b32_e32 v7, v0
	v_mov_b32_e32 v8, v0
	v_mov_b32_e32 v9, v0
	v_mov_b32_e32 v10, v0
	v_mov_b32_e32 v11, v0
	v_mov_b32_e32 v12, v0
	v_mov_b32_e32 v13, v0
	v_mov_b32_e32 v14, v0
	v_mov_b32_e32 v15, v0
	v_mov_b32_e32 v16, v0
	v_mov_b32_e32 v17, v0
	v_mov_b32_e32 v18, v0
	v_mov_b32_e32 v19, v0
	v_mov_b32_e32 v20, v0
	v_mov_b32_e32 v21, v0
	v_mov_b32_e32 v22, v0
	v_mov_b32_e32 v23, v0
	v_mov_b32_e32 v24, v0
	v_mov_b32_e32 v25, v0
	v_mov_b32_e32 v26, v0
	v_mov_b32_e32 v27, v0
	v_mov_b32_e32 v28, v0
	v_mov_b32_e32 v29, v0
	v_mov_b32_e32 v30, v0
	v_mov_b32_e32 v31, v0
	v_mov_b32_e32 v64, v0
	v_mov_b32_e32 v65, v0
	v_mov_b32_e32 v66, v0
	v_mov_b32_e32 v67, v0
	v_mov_b32_e32 v68, v0
	v_mov_b32_e32 v69, v0
	v_mov_b32_e32 v70, v0
	v_mov_b32_e32 v71, v0
	v_mov_b32_e32 v72, v0
	v_mov_b32_e32 v73, v0
	v_mov_b32_e32 v74, v0
	v_mov_b32_e32 v75, v0
	v_mov_b32_e32 v76, v0
	v_mov_b32_e32 v77, v0
	v_mov_b32_e32 v78, v0
	v_mov_b32_e32 v79, v0
	v_mov_b32_e32 v80, v0
	v_mov_b32_e32 v81, v0
	v_mov_b32_e32 v82, v0
	v_mov_b32_e32 v83, v0
	v_mov_b32_e32 v84, v0
	v_mov_b32_e32 v85, v0
	v_mov_b32_e32 v86, v0
	v_mov_b32_e32 v87, v0
	v_mov_b32_e32 v88, v0
	v_mov_b32_e32 v89, v0
	v_mov_b32_e32 v90, v0
	v_mov_b32_e32 v91, v0
	v_mov_b32_e32 v92, v0
	v_mov_b32_e32 v93, v0
	v_mov_b32_e32 v94, v0
	v_mov_b32_e32 v95, v0
	v_mov_b32_e32 v96, v0
	v_mov_b32_e32 v97, v0
	v_mov_b32_e32 v98, v0
	v_mov_b32_e32 v99, v0
	v_mov_b32_e32 v100, v0
	v_mov_b32_e32 v101, v0
	v_mov_b32_e32 v102, v0
	v_mov_b32_e32 v103, v0
	v_mov_b32_e32 v104, v0
	v_mov_b32_e32 v105, v0
	v_mov_b32_e32 v106, v0
	v_mov_b32_e32 v107, v0
	v_mov_b32_e32 v108, v0
	v_mov_b32_e32 v109, v0
	v_mov_b32_e32 v110, v0
	v_mov_b32_e32 v111, v0
	v_mov_b32_e32 v112, v0
	v_mov_b32_e32 v113, v0
	v_mov_b32_e32 v114, v0
	v_mov_b32_e32 v115, v0
	v_mov_b32_e32 v116, v0
	v_mov_b32_e32 v117, v0
	v_mov_b32_e32 v118, v0
	v_mov_b32_e32 v119, v0
	v_mov_b32_e32 v120, v0
	v_mov_b32_e32 v121, v0
	v_mov_b32_e32 v122, v0
	v_mov_b32_e32 v123, v0
	v_mov_b32_e32 v124, v0
	v_mov_b32_e32 v125, v0
	v_mov_b32_e32 v126, v0
	v_mov_b32_e32 v127, v0
	v_mov_b32_e32 v32, v0
	v_mov_b32_e32 v33, v0
	v_mov_b32_e32 v34, v0
	v_mov_b32_e32 v35, v0
	v_mov_b32_e32 v36, v0
	v_mov_b32_e32 v37, v0
	v_mov_b32_e32 v38, v0
	v_mov_b32_e32 v39, v0
	v_mov_b32_e32 v40, v0
	v_mov_b32_e32 v41, v0
	v_mov_b32_e32 v42, v0
	v_mov_b32_e32 v43, v0
	v_mov_b32_e32 v44, v0
	v_mov_b32_e32 v45, v0
	v_mov_b32_e32 v46, v0
	v_mov_b32_e32 v47, v0
	v_mov_b32_e32 v48, v0
	v_mov_b32_e32 v49, v0
	v_mov_b32_e32 v50, v0
	v_mov_b32_e32 v51, v0
	v_mov_b32_e32 v52, v0
	v_mov_b32_e32 v53, v0
	v_mov_b32_e32 v54, v0
	v_mov_b32_e32 v55, v0
	v_mov_b32_e32 v56, v0
	v_mov_b32_e32 v57, v0
	v_mov_b32_e32 v58, v0
	v_mov_b32_e32 v59, v0
	v_mov_b32_e32 v60, v0
	v_mov_b32_e32 v61, v0
	v_mov_b32_e32 v62, v0
	v_mov_b32_e32 v63, v0
	s_cbranch_vccnz .Llate_p6_done
	s_barrier
.Llate_p6_done:
.LBB0_423:
	ds_read_b128 v[128:131], v224
	ds_read_b128 v[132:135], v224 offset:2048
	ds_read_b128 v[136:139], v225
	ds_read_b128 v[140:143], v225 offset:2048
	v_lshl_add_u64 v[192:193], s[52:53], 0, v[216:217]
	s_mov_b32 m0, s72
	v_lshl_add_u64 v[176:177], v[192:193], 0, s[24:25]
	ds_read_b128 v[144:147], v226
	ds_read_b128 v[148:151], v226 offset:2048
	ds_read_b128 v[152:155], v227
	ds_read_b128 v[156:159], v227 offset:2048
	ds_read_b128 v[160:163], v226 offset:4096
	ds_read_b128 v[164:167], v226 offset:6144
	ds_read_b128 v[168:171], v227 offset:4096
	ds_read_b128 v[172:175], v227 offset:6144
	global_load_lds_dwordx4 v[176:177], off
	v_lshl_add_u64 v[176:177], v[192:193], 0, s[26:27]
	s_mov_b32 m0, s73
	s_nop 0
	global_load_lds_dwordx4 v[176:177], off
	s_waitcnt lgkmcnt(8)
	s_barrier
	s_waitcnt lgkmcnt(0)
	s_setprio 1
	s_waitcnt lgkmcnt(0)
	v_mfma_f32_16x16x32_bf16 v[124:127], v[128:131], v[144:147], v[124:127]
	v_mfma_f32_16x16x32_bf16 v[120:123], v[132:135], v[144:147], v[120:123]
	v_mfma_f32_16x16x32_bf16 v[116:119], v[128:131], v[148:151], v[116:119]
	v_mfma_f32_16x16x32_bf16 v[112:115], v[132:135], v[148:151], v[112:115]
	v_mfma_f32_16x16x32_bf16 v[108:111], v[128:131], v[160:163], v[108:111]
	v_mfma_f32_16x16x32_bf16 v[104:107], v[132:135], v[160:163], v[104:107]
	v_mfma_f32_16x16x32_bf16 v[100:103], v[128:131], v[164:167], v[100:103]
	v_mfma_f32_16x16x32_bf16 v[96:99], v[132:135], v[164:167], v[96:99]
	v_mfma_f32_16x16x32_bf16 v[124:127], v[136:139], v[152:155], v[124:127]
	v_mfma_f32_16x16x32_bf16 v[120:123], v[140:143], v[152:155], v[120:123]
	v_mfma_f32_16x16x32_bf16 v[116:119], v[136:139], v[156:159], v[116:119]
	v_mfma_f32_16x16x32_bf16 v[112:115], v[140:143], v[156:159], v[112:115]
	v_mfma_f32_16x16x32_bf16 v[108:111], v[136:139], v[168:171], v[108:111]
	v_mfma_f32_16x16x32_bf16 v[104:107], v[140:143], v[168:171], v[104:107]
	v_mfma_f32_16x16x32_bf16 v[100:103], v[136:139], v[172:175], v[100:103]
	v_mfma_f32_16x16x32_bf16 v[96:99], v[140:143], v[172:175], v[96:99]
	s_setprio 0
	s_barrier
	v_lshl_add_u64 v[194:195], s[58:59], 0, v[216:217]
	s_mov_b32 m0, s35
	v_lshl_add_u64 v[196:197], v[194:195], 0, s[28:29]
	ds_read_b128 v[176:179], v228
	ds_read_b128 v[180:183], v228 offset:2048
	ds_read_b128 v[184:187], v229
	ds_read_b128 v[188:191], v229 offset:2048
	global_load_lds_dwordx4 v[196:197], off
	v_lshl_add_u64 v[196:197], v[194:195], 0, s[30:31]
	s_mov_b32 m0, s42
	s_nop 0
	global_load_lds_dwordx4 v[196:197], off
	s_barrier
	s_waitcnt lgkmcnt(0)
	s_setprio 1
	s_waitcnt lgkmcnt(0)
	v_mfma_f32_16x16x32_bf16 v[92:95], v[176:179], v[144:147], v[92:95]
	v_mfma_f32_16x16x32_bf16 v[88:91], v[180:183], v[144:147], v[88:91]
	v_mfma_f32_16x16x32_bf16 v[84:87], v[176:179], v[148:151], v[84:87]
	v_mfma_f32_16x16x32_bf16 v[80:83], v[180:183], v[148:151], v[80:83]
	v_mfma_f32_16x16x32_bf16 v[76:79], v[176:179], v[160:163], v[76:79]
	v_mfma_f32_16x16x32_bf16 v[72:75], v[180:183], v[160:163], v[72:75]
	v_mfma_f32_16x16x32_bf16 v[68:71], v[176:179], v[164:167], v[68:71]
	v_mfma_f32_16x16x32_bf16 v[64:67], v[180:183], v[164:167], v[64:67]
	v_mfma_f32_16x16x32_bf16 v[92:95], v[184:187], v[152:155], v[92:95]
	v_mfma_f32_16x16x32_bf16 v[88:91], v[188:191], v[152:155], v[88:91]
	v_mfma_f32_16x16x32_bf16 v[84:87], v[184:187], v[156:159], v[84:87]
	v_mfma_f32_16x16x32_bf16 v[80:83], v[188:191], v[156:159], v[80:83]
	v_mfma_f32_16x16x32_bf16 v[76:79], v[184:187], v[168:171], v[76:79]
	v_mfma_f32_16x16x32_bf16 v[72:75], v[188:191], v[168:171], v[72:75]
	v_mfma_f32_16x16x32_bf16 v[68:71], v[184:187], v[172:175], v[68:71]
	v_mfma_f32_16x16x32_bf16 v[64:67], v[188:191], v[172:175], v[64:67]
	s_setprio 0
	s_mov_b32 m0, s33
	v_lshl_add_u64 v[196:197], v[192:193], 0, s[28:29]
	s_barrier
	ds_read_b128 v[144:147], v226 offset:16384
	ds_read_b128 v[148:151], v226 offset:18432
	ds_read_b128 v[152:155], v227 offset:16384
	ds_read_b128 v[156:159], v227 offset:18432
	ds_read_b128 v[160:163], v226 offset:20480
	ds_read_b128 v[164:167], v226 offset:22528
	ds_read_b128 v[168:171], v227 offset:20480
	ds_read_b128 v[172:175], v227 offset:22528
	global_load_lds_dwordx4 v[196:197], off
	v_lshl_add_u64 v[196:197], v[192:193], 0, s[30:31]
	s_mov_b32 m0, s43
	s_nop 0
	global_load_lds_dwordx4 v[196:197], off
	s_barrier
	s_waitcnt lgkmcnt(0)
	s_setprio 1
	s_waitcnt lgkmcnt(0)
	v_mfma_f32_16x16x32_bf16 v[28:31], v[128:131], v[144:147], v[28:31]
	v_mfma_f32_16x16x32_bf16 v[24:27], v[132:135], v[144:147], v[24:27]
	v_mfma_f32_16x16x32_bf16 v[20:23], v[128:131], v[148:151], v[20:23]
	v_mfma_f32_16x16x32_bf16 v[16:19], v[132:135], v[148:151], v[16:19]
	v_mfma_f32_16x16x32_bf16 v[12:15], v[128:131], v[160:163], v[12:15]
	v_mfma_f32_16x16x32_bf16 v[8:11], v[132:135], v[160:163], v[8:11]
	v_mfma_f32_16x16x32_bf16 v[4:7], v[128:131], v[164:167], v[4:7]
	v_mfma_f32_16x16x32_bf16 v[0:3], v[132:135], v[164:167], v[0:3]
	v_mfma_f32_16x16x32_bf16 v[28:31], v[136:139], v[152:155], v[28:31]
	v_mfma_f32_16x16x32_bf16 v[24:27], v[140:143], v[152:155], v[24:27]
	v_mfma_f32_16x16x32_bf16 v[20:23], v[136:139], v[156:159], v[20:23]
	v_mfma_f32_16x16x32_bf16 v[16:19], v[140:143], v[156:159], v[16:19]
	v_mfma_f32_16x16x32_bf16 v[12:15], v[136:139], v[168:171], v[12:15]
	v_mfma_f32_16x16x32_bf16 v[8:11], v[140:143], v[168:171], v[8:11]
	v_mfma_f32_16x16x32_bf16 v[4:7], v[136:139], v[172:175], v[4:7]
	v_mfma_f32_16x16x32_bf16 v[0:3], v[140:143], v[172:175], v[0:3]
	s_setprio 0
	s_barrier
	v_lshl_add_u64 v[196:197], s[4:5], 0, v[216:217]
	s_mov_b32 m0, s44
	v_lshl_add_u64 v[128:129], v[196:197], 0, s[28:29]
	global_load_lds_dwordx4 v[128:129], off
	v_lshl_add_u64 v[128:129], v[196:197], 0, s[30:31]
	s_mov_b32 m0, s45
	s_nop 0
	global_load_lds_dwordx4 v[128:129], off
	s_waitcnt vmcnt(6)
	s_barrier
	s_setprio 1
	v_mfma_f32_16x16x32_bf16 v[32:35], v[176:179], v[144:147], v[32:35]
	v_mfma_f32_16x16x32_bf16 v[36:39], v[180:183], v[144:147], v[36:39]
	v_mfma_f32_16x16x32_bf16 v[40:43], v[176:179], v[148:151], v[40:43]
	v_mfma_f32_16x16x32_bf16 v[44:47], v[180:183], v[148:151], v[44:47]
	v_mfma_f32_16x16x32_bf16 v[48:51], v[176:179], v[160:163], v[48:51]
	v_mfma_f32_16x16x32_bf16 v[52:55], v[180:183], v[160:163], v[52:55]
	v_mfma_f32_16x16x32_bf16 v[56:59], v[176:179], v[164:167], v[56:59]
	v_mfma_f32_16x16x32_bf16 v[60:63], v[180:183], v[164:167], v[60:63]
	v_mfma_f32_16x16x32_bf16 v[32:35], v[184:187], v[152:155], v[32:35]
	v_mfma_f32_16x16x32_bf16 v[36:39], v[188:191], v[152:155], v[36:39]
	v_mfma_f32_16x16x32_bf16 v[40:43], v[184:187], v[156:159], v[40:43]
	v_mfma_f32_16x16x32_bf16 v[44:47], v[188:191], v[156:159], v[44:47]
	v_mfma_f32_16x16x32_bf16 v[48:51], v[184:187], v[168:171], v[48:51]
	v_mfma_f32_16x16x32_bf16 v[52:55], v[188:191], v[168:171], v[52:55]
	v_mfma_f32_16x16x32_bf16 v[56:59], v[184:187], v[172:175], v[56:59]
	v_mfma_f32_16x16x32_bf16 v[60:63], v[188:191], v[172:175], v[60:63]
	s_setprio 0
	s_barrier
	ds_read_b128 v[128:131], v232
	ds_read_b128 v[132:135], v232 offset:2048
	ds_read_b128 v[136:139], v233
	ds_read_b128 v[140:143], v233 offset:2048
	s_mov_b32 m0, s60
	v_lshl_add_u64 v[176:177], v[192:193], 0, s[36:37]
	ds_read_b128 v[144:147], v226 offset:32768
	ds_read_b128 v[148:151], v226 offset:34816
	ds_read_b128 v[152:155], v227 offset:32768
	ds_read_b128 v[156:159], v227 offset:34816
	ds_read_b128 v[160:163], v226 offset:36864
	ds_read_b128 v[164:167], v226 offset:38912
	ds_read_b128 v[168:171], v227 offset:36864
	ds_read_b128 v[172:175], v227 offset:38912
	global_load_lds_dwordx4 v[176:177], off
	v_lshl_add_u64 v[176:177], v[192:193], 0, s[38:39]
	s_mov_b32 m0, s61
	s_nop 0
	global_load_lds_dwordx4 v[176:177], off
	s_waitcnt lgkmcnt(8)
	s_barrier
	s_waitcnt lgkmcnt(0)
	s_setprio 1
	s_waitcnt lgkmcnt(0)
	v_mfma_f32_16x16x32_bf16 v[124:127], v[128:131], v[144:147], v[124:127]
	v_mfma_f32_16x16x32_bf16 v[120:123], v[132:135], v[144:147], v[120:123]
	v_mfma_f32_16x16x32_bf16 v[116:119], v[128:131], v[148:151], v[116:119]
	v_mfma_f32_16x16x32_bf16 v[112:115], v[132:135], v[148:151], v[112:115]
	v_mfma_f32_16x16x32_bf16 v[108:111], v[128:131], v[160:163], v[108:111]
	v_mfma_f32_16x16x32_bf16 v[104:107], v[132:135], v[160:163], v[104:107]
	v_mfma_f32_16x16x32_bf16 v[100:103], v[128:131], v[164:167], v[100:103]
	v_mfma_f32_16x16x32_bf16 v[96:99], v[132:135], v[164:167], v[96:99]
	v_mfma_f32_16x16x32_bf16 v[124:127], v[136:139], v[152:155], v[124:127]
	v_mfma_f32_16x16x32_bf16 v[120:123], v[140:143], v[152:155], v[120:123]
	v_mfma_f32_16x16x32_bf16 v[116:119], v[136:139], v[156:159], v[116:119]
	v_mfma_f32_16x16x32_bf16 v[112:115], v[140:143], v[156:159], v[112:115]
	v_mfma_f32_16x16x32_bf16 v[108:111], v[136:139], v[168:171], v[108:111]
	v_mfma_f32_16x16x32_bf16 v[104:107], v[140:143], v[168:171], v[104:107]
	v_mfma_f32_16x16x32_bf16 v[100:103], v[136:139], v[172:175], v[100:103]
	v_mfma_f32_16x16x32_bf16 v[96:99], v[140:143], v[172:175], v[96:99]
	s_setprio 0
	s_barrier
	s_mov_b32 m0, s62
	v_lshl_add_u64 v[198:199], v[194:195], 0, s[40:41]
	ds_read_b128 v[176:179], v234
	ds_read_b128 v[180:183], v234 offset:2048
	ds_read_b128 v[184:187], v235
	ds_read_b128 v[188:191], v235 offset:2048
	global_load_lds_dwordx4 v[198:199], off
	v_lshl_add_u64 v[194:195], v[194:195], 0, s[46:47]
	s_mov_b32 m0, s63
	s_nop 0
	global_load_lds_dwordx4 v[194:195], off
	s_barrier
	s_waitcnt lgkmcnt(0)
	s_setprio 1
	s_waitcnt lgkmcnt(0)
	v_mfma_f32_16x16x32_bf16 v[92:95], v[176:179], v[144:147], v[92:95]
	v_mfma_f32_16x16x32_bf16 v[88:91], v[180:183], v[144:147], v[88:91]
	v_mfma_f32_16x16x32_bf16 v[84:87], v[176:179], v[148:151], v[84:87]
	v_mfma_f32_16x16x32_bf16 v[80:83], v[180:183], v[148:151], v[80:83]
	v_mfma_f32_16x16x32_bf16 v[76:79], v[176:179], v[160:163], v[76:79]
	v_mfma_f32_16x16x32_bf16 v[72:75], v[180:183], v[160:163], v[72:75]
	v_mfma_f32_16x16x32_bf16 v[68:71], v[176:179], v[164:167], v[68:71]
	v_mfma_f32_16x16x32_bf16 v[64:67], v[180:183], v[164:167], v[64:67]
	v_mfma_f32_16x16x32_bf16 v[92:95], v[184:187], v[152:155], v[92:95]
	v_mfma_f32_16x16x32_bf16 v[88:91], v[188:191], v[152:155], v[88:91]
	v_mfma_f32_16x16x32_bf16 v[84:87], v[184:187], v[156:159], v[84:87]
	v_mfma_f32_16x16x32_bf16 v[80:83], v[188:191], v[156:159], v[80:83]
	v_mfma_f32_16x16x32_bf16 v[76:79], v[184:187], v[168:171], v[76:79]
	v_mfma_f32_16x16x32_bf16 v[72:75], v[188:191], v[168:171], v[72:75]
	v_mfma_f32_16x16x32_bf16 v[68:71], v[184:187], v[172:175], v[68:71]
	v_mfma_f32_16x16x32_bf16 v[64:67], v[188:191], v[172:175], v[64:67]
	s_setprio 0
	s_mov_b32 m0, s64
	v_lshl_add_u64 v[194:195], v[192:193], 0, s[40:41]
	s_barrier
	ds_read_b128 v[144:147], v226 offset:49152
	ds_read_b128 v[148:151], v226 offset:51200
	ds_read_b128 v[152:155], v227 offset:49152
	ds_read_b128 v[156:159], v227 offset:51200
	ds_read_b128 v[160:163], v226 offset:53248
	ds_read_b128 v[164:167], v226 offset:55296
	ds_read_b128 v[168:171], v227 offset:53248
	ds_read_b128 v[172:175], v227 offset:55296
	global_load_lds_dwordx4 v[194:195], off
	v_lshl_add_u64 v[192:193], v[192:193], 0, s[46:47]
	s_mov_b32 m0, s65
	s_nop 0
	global_load_lds_dwordx4 v[192:193], off
	s_barrier
	s_waitcnt lgkmcnt(0)
	s_setprio 1
	s_waitcnt lgkmcnt(0)
	v_mfma_f32_16x16x32_bf16 v[28:31], v[128:131], v[144:147], v[28:31]
	v_mfma_f32_16x16x32_bf16 v[24:27], v[132:135], v[144:147], v[24:27]
	v_mfma_f32_16x16x32_bf16 v[20:23], v[128:131], v[148:151], v[20:23]
	v_mfma_f32_16x16x32_bf16 v[16:19], v[132:135], v[148:151], v[16:19]
	v_mfma_f32_16x16x32_bf16 v[12:15], v[128:131], v[160:163], v[12:15]
	v_mfma_f32_16x16x32_bf16 v[8:11], v[132:135], v[160:163], v[8:11]
	v_mfma_f32_16x16x32_bf16 v[4:7], v[128:131], v[164:167], v[4:7]
	v_mfma_f32_16x16x32_bf16 v[0:3], v[132:135], v[164:167], v[0:3]
	v_mfma_f32_16x16x32_bf16 v[28:31], v[136:139], v[152:155], v[28:31]
	v_mfma_f32_16x16x32_bf16 v[24:27], v[140:143], v[152:155], v[24:27]
	v_mfma_f32_16x16x32_bf16 v[20:23], v[136:139], v[156:159], v[20:23]
	v_mfma_f32_16x16x32_bf16 v[16:19], v[140:143], v[156:159], v[16:19]
	v_mfma_f32_16x16x32_bf16 v[12:15], v[136:139], v[168:171], v[12:15]
	v_mfma_f32_16x16x32_bf16 v[8:11], v[140:143], v[168:171], v[8:11]
	v_mfma_f32_16x16x32_bf16 v[4:7], v[136:139], v[172:175], v[4:7]
	v_mfma_f32_16x16x32_bf16 v[0:3], v[140:143], v[172:175], v[0:3]
	s_setprio 0
	s_barrier
	s_mov_b32 m0, s68
	v_lshl_add_u64 v[128:129], v[196:197], 0, s[40:41]
	global_load_lds_dwordx4 v[128:129], off
	v_lshl_add_u64 v[128:129], v[196:197], 0, s[46:47]
	s_mov_b32 m0, s69
	s_nop 0
	global_load_lds_dwordx4 v[128:129], off
	s_waitcnt vmcnt(6)
	s_barrier
; #define LDA(dst,b,h) _Pragma("unroll") for(int m=0;m<4;++m) _Pragma("unroll") for(int k=0;k<2;++k) \
;     dst[m][k]=*reinterpret_cast<const bf16x8*>(SA(b,h)+(wr*64+m*16)*128+koff[k])
; #define LDB(dst,b,h) _Pragma("unroll") for(int n=0;n<2;++n) _Pragma("unroll") for(int k=0;k<2;++k) \
;     dst[n][k]=*reinterpret_cast<const bf16x8*>(SB(b,h)+(wc*32+n*16)*128+koff[k])
; #define MMA(ai,bj,Af,Bf) do{__builtin_amdgcn_s_setprio(1); \
;     _Pragma("unroll") for(int m=0;m<4;++m) _Pragma("unroll") for(int n=0;n<2;++n) _Pragma("unroll") for(int k=0;k<2;++k) \
;       acc[ai][bj][m][n]=__builtin_amdgcn_mfma_f32_16x16x32_bf16(Bf[n][k],Af[m][k],acc[ai][bj][m][n],0,0,0); \
;     __builtin_amdgcn_s_setprio(0);}while(0)
; #define WAIT_L(n) asm volatile("s_waitcnt lgkmcnt(" #n ")":::"memory")
; #define BAR __builtin_amdgcn_s_barrier()
; #define SCHED __builtin_amdgcn_sched_barrier(0)
; #define STAGE_A(b,h,kt) do{ unsigned char* _d = SA(b,h) + wbase; \
;     if constexpr (BLK) { const char* _s = baseA + ((size_t)(h)*(K/64) + (kt)) * 16384; GLDS(_s + voa, _d); GLDS(_s + 8192 + voa, _d + 8192); } \
;     else { const char* _s = baseA + ((size_t)(h)*128*K + (kt)*64) * 2; GLDS(_s + voa, _d); GLDS(_s + (size_t)128*K + voa, _d + 8192); } }while(0)
; template <int K, int EPI, bool MIX = false>
; __device__ __forceinline__ void gemm_phase(const Params& p, const u16* __restrict__ A, const u16* __restrict__ Bt,
;                            const float* __restrict__ rs_in, float* __restrict__ ssq_out, float alpha, bool rev = false) {
;     ...
;       for (int t = 0; t < nt - 2; t += 2) KBODY(t);
;     }
;     ...
;     const int cpm = pm, cpn = pn;
;     float rsq[2][4];
;     if constexpr (EPI == EPI_SWIGLU || EPI == EPI_Z || MIX) {
;       const float* rsrc = MIX ? p.ssqb : rs_in;
;       int fr_p = fr;
;       asm volatile("" : "+v"(fr_p));
; #pragma unroll
;       for (int ai = 0; ai < 2; ++ai)
; #pragma unroll
;         for (int m = 0; m < 4; ++m) rsq[ai][m] = rsrc[cpm * 256 + ai * 128 + wr * 64 + m * 16 + fr_p];
;     }
;     ++it;
;     id = item_id(it);
;     const bool more = id < ntiles;
;     if (rev) id = ntiles - 1 - id;
;     {
;       LDB(B0,0,0); SCHED; LDA(At,0,0); STAGE_A(1,1,nt-1);
;       WAIT_L(8); BAR; WAIT_L(0); MMA(0,0,At,B0); BAR; SCHED;
;       if (more) SETUP_TILE();
	s_setprio 1
	v_mfma_f32_16x16x32_bf16 v[32:35], v[176:179], v[144:147], v[32:35]
	v_mfma_f32_16x16x32_bf16 v[36:39], v[180:183], v[144:147], v[36:39]
	v_mfma_f32_16x16x32_bf16 v[40:43], v[176:179], v[148:151], v[40:43]
	v_mfma_f32_16x16x32_bf16 v[44:47], v[180:183], v[148:151], v[44:47]
	v_mfma_f32_16x16x32_bf16 v[48:51], v[176:179], v[160:163], v[48:51]
	v_mfma_f32_16x16x32_bf16 v[52:55], v[180:183], v[160:163], v[52:55]
	v_mfma_f32_16x16x32_bf16 v[56:59], v[176:179], v[164:167], v[56:59]
	v_mfma_f32_16x16x32_bf16 v[60:63], v[180:183], v[164:167], v[60:63]
	v_mfma_f32_16x16x32_bf16 v[32:35], v[184:187], v[152:155], v[32:35]
	v_mfma_f32_16x16x32_bf16 v[36:39], v[188:191], v[152:155], v[36:39]
	v_mfma_f32_16x16x32_bf16 v[40:43], v[184:187], v[156:159], v[40:43]
	v_mfma_f32_16x16x32_bf16 v[44:47], v[188:191], v[156:159], v[44:47]
	v_mfma_f32_16x16x32_bf16 v[48:51], v[184:187], v[168:171], v[48:51]
	v_mfma_f32_16x16x32_bf16 v[52:55], v[188:191], v[168:171], v[52:55]
	v_mfma_f32_16x16x32_bf16 v[56:59], v[184:187], v[172:175], v[56:59]
	v_mfma_f32_16x16x32_bf16 v[60:63], v[188:191], v[172:175], v[60:63]
	s_setprio 0
	s_add_i32 s77, s77, 2
	s_add_u32 s58, s58, 0x100
	s_addc_u32 s59, s59, 0
	s_add_u32 s52, s52, 0x100
	s_addc_u32 s53, s53, 0
	s_add_u32 s4, s4, 0x100
	s_addc_u32 s5, s5, 0
	s_cmp_lt_u32 s77, 28
	s_barrier
	s_cbranch_scc1 .LBB0_423
	v_mov_b32_e32 v128, v223
	s_lshl_b32 s59, s34, 8
	s_add_i32 s59, s59, s70
	v_add_u32_e32 v128, s59, v128
	v_readlane_b32 s80, v254, 32
	v_ashrrev_i32_e32 v129, 31, v128
	v_readlane_b32 s94, v254, 46
	v_readlane_b32 s95, v254, 47
	s_add_i32 s75, s75, 1
	s_mul_i32 s4, s75, s57
	v_lshl_add_u64 v[128:129], v[128:129], 2, s[94:95]
	global_load_dword v214, v[128:129], off
	global_load_dword v243, v[128:129], off offset:64
	global_load_dword v242, v[128:129], off offset:128
	global_load_dword v241, v[128:129], off offset:192
	global_load_dword v240, v[128:129], off offset:512
	global_load_dword v239, v[128:129], off offset:576
	global_load_dword v238, v[128:129], off offset:640
	global_load_dword v237, v[128:129], off offset:704
	ds_read_b128 v[136:139], v224
	ds_read_b128 v[140:143], v224 offset:2048
	ds_read_b128 v[148:151], v225
	ds_read_b128 v[144:147], v225 offset:2048
	s_add_i32 s4, s4, s56
	v_readlane_b32 s81, v254, 33
	v_readlane_b32 s82, v254, 34
	v_readlane_b32 s83, v254, 35
	v_readlane_b32 s84, v254, 36
	v_readlane_b32 s85, v254, 37
	v_readlane_b32 s86, v254, 38
	v_readlane_b32 s87, v254, 39
	v_readlane_b32 s88, v254, 40
	v_readlane_b32 s89, v254, 41
	v_readlane_b32 s90, v254, 42
	v_readlane_b32 s91, v254, 43
	v_readlane_b32 s92, v254, 44
	v_readlane_b32 s93, v254, 45
	v_lshl_add_u64 v[128:129], s[0:1], 0, v[212:213]
	s_mov_b32 m0, s72
	v_lshl_add_u64 v[130:131], v[128:129], 0, s[48:49]
	ds_read_b128 v[152:155], v226
	ds_read_b128 v[156:159], v226 offset:2048
	ds_read_b128 v[180:183], v227
	ds_read_b128 v[172:175], v227 offset:2048
	ds_read_b128 v[160:163], v226 offset:4096
	ds_read_b128 v[164:167], v226 offset:6144
	ds_read_b128 v[176:179], v227 offset:4096
	ds_read_b128 v[168:171], v227 offset:6144
	global_load_lds_dwordx4 v[130:131], off
	v_lshl_add_u64 v[128:129], v[128:129], 0, s[50:51]
	s_mov_b32 m0, s73
	s_nop 0
	global_load_lds_dwordx4 v[128:129], off
	s_waitcnt lgkmcnt(8)
	s_barrier
	s_waitcnt lgkmcnt(0)
	s_setprio 1
	s_waitcnt lgkmcnt(0)
	v_mfma_f32_16x16x32_bf16 v[124:127], v[136:139], v[152:155], v[124:127]
	s_cmpk_lt_i32 s4, 0x2100
	s_cselect_b64 s[52:53], -1, 0
	s_cmpk_gt_i32 s4, 0x20ff
	v_mfma_f32_16x16x32_bf16 v[120:123], v[140:143], v[152:155], v[120:123]
	v_mfma_f32_16x16x32_bf16 v[116:119], v[136:139], v[156:159], v[116:119]
	v_mfma_f32_16x16x32_bf16 v[112:115], v[140:143], v[156:159], v[112:115]
	v_mfma_f32_16x16x32_bf16 v[108:111], v[136:139], v[160:163], v[108:111]
	v_mfma_f32_16x16x32_bf16 v[104:107], v[140:143], v[160:163], v[104:107]
	v_mfma_f32_16x16x32_bf16 v[100:103], v[136:139], v[164:167], v[100:103]
	v_mfma_f32_16x16x32_bf16 v[96:99], v[140:143], v[164:167], v[96:99]
	v_mfma_f32_16x16x32_bf16 v[124:127], v[148:151], v[180:183], v[124:127]
	v_mfma_f32_16x16x32_bf16 v[120:123], v[144:147], v[180:183], v[120:123]
	v_mfma_f32_16x16x32_bf16 v[116:119], v[148:151], v[172:175], v[116:119]
	v_mfma_f32_16x16x32_bf16 v[112:115], v[144:147], v[172:175], v[112:115]
	v_mfma_f32_16x16x32_bf16 v[108:111], v[148:151], v[176:179], v[108:111]
	v_mfma_f32_16x16x32_bf16 v[104:107], v[144:147], v[176:179], v[104:107]
	v_mfma_f32_16x16x32_bf16 v[128:131], v[148:151], v[168:171], v[100:103]
	v_mfma_f32_16x16x32_bf16 v[132:135], v[144:147], v[168:171], v[96:99]
	s_setprio 0
	s_barrier
	s_mov_b32 s58, s76
	s_cbranch_scc1 .LBB0_426
	s_mul_hi_i32 s0, s4, 0x2e8ba2e9
	s_lshr_b32 s1, s0, 31
	s_ashr_i32 s0, s0, 6
	s_add_i32 s0, s0, s1
	s_lshl_b32 s1, s0, 3
	s_mulk_i32 s0, 0xfea0
	s_add_i32 s0, s0, s4
	s_and_b32 s4, s4, 7
	s_or_b32 s34, s1, s4
	s_ashr_i32 s58, s0, 3
	s_lshl_b32 s0, s34, 8
	v_readlane_b32 s80, v254, 0
	s_ashr_i32 s1, s0, 31
	v_readlane_b32 s86, v254, 6
	v_readlane_b32 s87, v254, 7
	s_lshl_b64 s[0:1], s[0:1], 12
	s_mov_b64 s[10:11], s[86:87]
	v_readlane_b32 s81, v254, 1
	v_readlane_b32 s82, v254, 2
	v_readlane_b32 s83, v254, 3
	v_readlane_b32 s84, v254, 4
	v_readlane_b32 s85, v254, 5
	s_add_u32 s0, s10, s0
	s_addc_u32 s1, s11, s1
	s_lshl_b32 s4, s58, 7
	v_readlane_b32 s80, v254, 32
	s_ashr_i32 s5, s4, 31
	v_readlane_b32 s82, v254, 34
	v_readlane_b32 s83, v254, 35
	s_lshl_b64 s[4:5], s[4:5], 12
	s_mov_b64 s[78:79], s[82:83]
	s_add_u32 s8, s78, s4
	s_addc_u32 s9, s79, s5
	s_add_u32 s10, s8, 0x1600000
	s_addc_u32 s11, s9, 0
	v_readlane_b32 s81, v254, 33
	v_readlane_b32 s84, v254, 36
	v_readlane_b32 s85, v254, 37
	v_readlane_b32 s86, v254, 38
	v_readlane_b32 s87, v254, 39
	v_readlane_b32 s88, v254, 40
	v_readlane_b32 s89, v254, 41
	v_readlane_b32 s90, v254, 42
	v_readlane_b32 s91, v254, 43
	v_readlane_b32 s92, v254, 44
	v_readlane_b32 s93, v254, 45
	v_readlane_b32 s94, v254, 46
	v_readlane_b32 s95, v254, 47

; __global__ void __launch_bounds__(NTHR) fwd_megakernel(Params p) {
;     ...
;   run_phase<6>(p); grid.sync();
.LBB0_447:
	s_waitcnt vmcnt(0) lgkmcnt(0)
	s_barrier
	s_mov_b64 s[0:1], exec
	v_readlane_b32 s4, v255, 1
	v_readlane_b32 s5, v255, 2
	s_and_b64 s[4:5], s[0:1], s[4:5]
	s_mov_b64 exec, s[4:5]
	s_cbranch_execz .LBB0_457
	buffer_wbl2 sc1
	s_waitcnt vmcnt(0)
	v_readlane_b32 s4, v254, 24
	v_readlane_b32 s5, v254, 25
	v_readlane_b32 s6, v255, 3
	s_load_dword s7, s[72:73], 0x0
	s_nop 3
	s_add_u32 s4, s4, 0x10000000
	s_addc_u32 s5, s5, 0
	s_and_b32 s6, s6, 7
	s_lshl_b32 s6, s6, 8
	s_add_i32 s6, s6, 0x100
	v_mov_b32_e32 v2, 0
	v_mov_b32_e32 v3, 1
	v_mov_b32_e32 v0, s6
	s_nop 3
	global_atomic_add v3, v2, v3, s[4:5] sc0 sc1
	s_waitcnt lgkmcnt(0)
	s_mul_i32 s7, s7, 6
	s_add_i32 s7, s7, -1
	s_waitcnt vmcnt(0)
	v_readfirstlane_b32 s6, v3
	s_nop 3
	s_cmp_lg_u32 s6, s7
	s_cbranch_scc1 .Lfb6_poll0
	v_mov_b32_e32 v1, 1
	global_atomic_add v2, v1, s[4:5] offset:256 sc1
	global_atomic_add v2, v1, s[4:5] offset:512 sc1
	global_atomic_add v2, v1, s[4:5] offset:768 sc1
	global_atomic_add v2, v1, s[4:5] offset:1024 sc1
	global_atomic_add v2, v1, s[4:5] offset:1280 sc1
	global_atomic_add v2, v1, s[4:5] offset:1536 sc1
	global_atomic_add v2, v1, s[4:5] offset:1792 sc1
	global_atomic_add v2, v1, s[4:5] offset:2048 sc1
	s_branch .Lfb6_done

; __global__ void __launch_bounds__(NTHR) fwd_megakernel(Params p) {
;     ...
;   run_phase<6>(p); grid.sync();
.Lfb6_poll:
	global_load_dword v1, v0, s[4:5] sc1
	s_waitcnt vmcnt(0)
	v_readfirstlane_b32 s6, v1
	s_nop 3
	s_cmpk_ge_u32 s6, 6
	s_cbranch_scc1 .Lfb6_done
	s_sleep 1
	s_add_u32 s8, s8, 1
	s_cmpk_lt_u32 s8, 0x7fff
	s_cbranch_scc1 .Lfb6_poll

; #define WAIT_V(n) asm volatile("s_waitcnt vmcnt(" #n ")":::"memory")
; #define BAR __builtin_amdgcn_s_barrier()
; #define STAGE_A(b,h,kt) do{ unsigned char* _d = SA(b,h) + wbase; \
;     if constexpr (BLK) { const char* _s = baseA + ((size_t)(h)*(K/64) + (kt)) * 16384; GLDS(_s + voa, _d); GLDS(_s + 8192 + voa, _d + 8192); } \
;     else { const char* _s = baseA + ((size_t)(h)*128*K + (kt)*64) * 2; GLDS(_s + voa, _d); GLDS(_s + (size_t)128*K + voa, _d + 8192); } }while(0)
; #define STAGE_B(b,h,kt) do{ unsigned char* _d = SB(b,h) + wbase; \
;     if constexpr (BLK) { const char* _s = ((h)?baseB1:baseB0) + (size_t)(kt) * 16384; GLDS(_s + voa, _d); GLDS(_s + 8192 + voa, _d + 8192); } \
;     else { const char* _s = ((h)?baseB1:baseB0) + (kt)*128; GLDS(_s + voa, _d); GLDS(_s + (size_t)128*K + voa, _d + 8192); } }while(0)
; template <int K, int EPI, bool MIX = false>
; __device__ __forceinline__ void gemm_phase(const Params& p, const u16* __restrict__ A, const u16* __restrict__ Bt,
;                            const float* __restrict__ rs_in, float* __restrict__ ssq_out, float alpha, bool rev = false) {
;     ...
;   int tid = threadIdx.x;
;   asm volatile("" : "+v"(tid));
;   const int wid = __builtin_amdgcn_readfirstlane(tid >> 6);
;   const int lane = tid & 63, wr = wid >> 2, wc = wid & 3, fr = lane & 15, fq = lane >> 4;
;   const int wbase = wid * 1024;
;   int koff[2];
;   koff[0] = lds_off32(fr, fq); koff[1] = lds_off32(fr, 4 + fq);
;   int it = 0;
;   int id = item_id(0);
;   if (id >= ntiles) return;
;   if (rev) id = ntiles - 1 - id;
;   int pm, pn;
;   const char *baseA, *baseB0, *baseB1;
;   unsigned voa;
;   {
;     const int R = tid >> 3, C = ((tid & 7) ^ ((R >> 1) & 7)) * 8;
;     voa = (unsigned)(R * (BLK ? 64 : K) + C) * 2u;
;   }
;     ...
;   SETUP_TILE();
;   STAGE_B(0,0,0); STAGE_A(0,0,0); STAGE_B(0,1,0); STAGE_A(0,1,0);
;   if (wr == 1) BAR;
;   WAIT_V(4); BAR;
;   STAGE_B(1,0,1); STAGE_A(1,0,1); STAGE_B(1,1,1);
;   WAIT_V(6); BAR;
;   for (;;) {
.LBB0_460:
	s_add_i32 s55, s33, 0x18000
	s_mov_b64 s[14:15], 0x4000
	v_lshl_add_u64 v[8:9], v[0:1], 0, s[14:15]
	s_mov_b32 m0, s55
	s_mov_b64 s[16:17], 0x6000
	s_add_i32 s58, s33, 0x1a000
	s_waitcnt vmcnt(4)
	s_barrier
	global_load_lds_dwordx4 v[8:9], off
	v_lshl_add_u64 v[8:9], v[0:1], 0, s[16:17]
	s_mov_b32 m0, s58
	s_add_i32 s59, s33, 0x8000
	global_load_lds_dwordx4 v[8:9], off
	v_lshl_add_u64 v[8:9], v[2:3], 0, s[14:15]
	s_mov_b32 m0, s59
	s_add_i32 s60, s33, 0xa000
	global_load_lds_dwordx4 v[8:9], off
	v_lshl_add_u64 v[2:3], v[2:3], 0, s[16:17]
	s_mov_b32 m0, s60
	s_add_i32 s61, s33, 0x1c000
	s_mov_b64 s[18:19], 0x164000
	global_load_lds_dwordx4 v[2:3], off
	v_lshl_add_u64 v[2:3], v[0:1], 0, s[18:19]
	s_mov_b32 m0, s61
	s_mov_b64 s[20:21], 0x166000
	s_add_i32 s62, s33, 0x1e000
	global_load_lds_dwordx4 v[2:3], off
	v_lshl_add_u64 v[0:1], v[0:1], 0, s[20:21]
	s_mov_b32 m0, s62
	s_and_b32 s24, s22, 3
	global_load_lds_dwordx4 v[0:1], off
	s_lshl_b32 s22, s24, 12
	v_and_b32_e32 v0, 15, v6
	v_bfe_u32 v1, v6, 4, 2
	v_bfe_u32 v2, v6, 1, 3
	s_or_b32 s26, s22, 0x10000
	s_lshl_b32 s27, s3, 13
	s_or_b32 s28, s22, 0x14000
	s_or_b32 s30, s22, 0x18000
	s_or_b32 s38, s22, 0x1c000
	v_lshlrev_b32_e32 v0, 7, v0
	v_xor_b32_e32 v3, v1, v2
	v_bitop3_b32 v1, v1, v2, 4 bitop3:0x36
	s_waitcnt vmcnt(6)
	s_cmpk_lt_u32 s2, 0x100
	v_lshl_or_b32 v3, v3, 4, v0
	v_lshl_or_b32 v0, v1, 4, v0
	s_cselect_b64 s[22:23], -1, 0
	s_lshl_b32 s2, s24, 5
	s_mov_b32 s25, 0
	v_and_b32_e32 v224, 63, v6
	s_lshl_b32 s63, s3, 6
	v_add_u32_e32 v218, v5, v4
	v_mov_b32_e32 v219, v217
	v_add_u32_e32 v225, s26, v3
	v_add_u32_e32 v226, s26, v0
	v_add_u32_e32 v227, s27, v3
	v_add_u32_e32 v228, s27, v0
	s_add_i32 s64, s33, 0xc000
	s_add_i32 s65, s33, 0xe000
	v_add_u32_e32 v229, s28, v3
	v_add_u32_e32 v232, s28, v0
	s_mov_b64 s[26:27], 0x8000
	s_mov_b64 s[28:29], 0xa000
	v_add_u32_e32 v233, s30, v3
	v_add_u32_e32 v234, s30, v0
	s_mov_b64 s[30:31], 0x168000
	s_mov_b64 s[36:37], 0x16a000
	v_add_u32_e32 v235, s38, v3
	v_add_u32_e32 v236, s38, v0
	s_mov_b64 s[38:39], 0xc000
	s_mov_b64 s[40:41], 0xe000
	s_mov_b64 s[46:47], 0x2bc000
	s_mov_b64 s[48:49], 0x2be000
	v_mbcnt_hi_u32_b32 v231, -1, v231
	s_lshl_b32 s24, s2, 1
	s_mov_b32 s66, s25
	s_barrier
	s_mov_b64 vcc, exec
	s_branch .LBB0_462

; #define SCHED __builtin_amdgcn_sched_barrier(0)
; template <int K, int EPI, bool MIX = false>
; __device__ __forceinline__ void gemm_phase(const Params& p, const u16* __restrict__ A, const u16* __restrict__ Bt,
;                            const float* __restrict__ rs_in, float* __restrict__ ssq_out, float alpha, bool rev = false) {
;     ...
;     f32x4 acc[2][2][4][2];
; #pragma unroll
;     for (int a = 0; a < 2; ++a)
; #pragma unroll
;       for (int b = 0; b < 2; ++b)
; #pragma unroll
;         for (int m = 0; m < 4; ++m)
; #pragma unroll
;           for (int n = 0; n < 2; ++n) acc[a][b][m][n] = f32x4{0.f, 0.f, 0.f, 0.f};
;     bf16x8 At[4][2], B0[2][2], B1[2][2];
;     asm volatile("" ::: "memory");
;     SCHED;
.LBB0_462:
	s_mov_b32 s70, s68
	s_mov_b32 s69, s67
	v_mov_b32_e32 v0, 0
	s_mov_b32 s67, -2
	s_mov_b64 s[2:3], s[10:11]
	s_mov_b64 s[50:51], s[4:5]
	s_mov_b64 s[52:53], s[8:9]
	s_waitcnt lgkmcnt(0)
	v_mov_b32_e32 v1, v0
	v_mov_b32_e32 v2, v0
	v_mov_b32_e32 v3, v0
	v_mov_b32_e32 v4, v0
	v_mov_b32_e32 v5, v0
	v_mov_b32_e32 v6, v0
	v_mov_b32_e32 v7, v0
	v_mov_b32_e32 v8, v0
	v_mov_b32_e32 v9, v0
	v_mov_b32_e32 v10, v0
	v_mov_b32_e32 v11, v0
	v_mov_b32_e32 v12, v0
	v_mov_b32_e32 v13, v0
	v_mov_b32_e32 v14, v0
	v_mov_b32_e32 v15, v0
	v_mov_b32_e32 v16, v0
	v_mov_b32_e32 v17, v0
	v_mov_b32_e32 v18, v0
	v_mov_b32_e32 v19, v0
	v_mov_b32_e32 v20, v0
	v_mov_b32_e32 v21, v0
	v_mov_b32_e32 v22, v0
	v_mov_b32_e32 v23, v0
	v_mov_b32_e32 v24, v0
	v_mov_b32_e32 v25, v0
	v_mov_b32_e32 v26, v0
	v_mov_b32_e32 v27, v0
	v_mov_b32_e32 v28, v0
	v_mov_b32_e32 v29, v0
	v_mov_b32_e32 v30, v0
	v_mov_b32_e32 v31, v0
	v_mov_b32_e32 v32, v0
	v_mov_b32_e32 v33, v0
	v_mov_b32_e32 v34, v0
	v_mov_b32_e32 v35, v0
	v_mov_b32_e32 v36, v0
	v_mov_b32_e32 v37, v0
	v_mov_b32_e32 v38, v0
	v_mov_b32_e32 v39, v0
	v_mov_b32_e32 v40, v0
	v_mov_b32_e32 v41, v0
	v_mov_b32_e32 v42, v0
	v_mov_b32_e32 v43, v0
	v_mov_b32_e32 v44, v0
	v_mov_b32_e32 v45, v0
	v_mov_b32_e32 v46, v0
	v_mov_b32_e32 v47, v0
	v_mov_b32_e32 v48, v0
	v_mov_b32_e32 v49, v0
	v_mov_b32_e32 v50, v0
	v_mov_b32_e32 v51, v0
	v_mov_b32_e32 v52, v0
	v_mov_b32_e32 v53, v0
	v_mov_b32_e32 v54, v0
	v_mov_b32_e32 v55, v0
	v_mov_b32_e32 v56, v0
	v_mov_b32_e32 v57, v0
	v_mov_b32_e32 v58, v0
	v_mov_b32_e32 v59, v0
	v_mov_b32_e32 v60, v0
	v_mov_b32_e32 v61, v0
	v_mov_b32_e32 v62, v0
	v_mov_b32_e32 v63, v0
	v_mov_b32_e32 v64, v0
	v_mov_b32_e32 v65, v0
	v_mov_b32_e32 v66, v0
	v_mov_b32_e32 v67, v0
	v_mov_b32_e32 v68, v0
	v_mov_b32_e32 v69, v0
	v_mov_b32_e32 v70, v0
	v_mov_b32_e32 v71, v0
	v_mov_b32_e32 v72, v0
	v_mov_b32_e32 v73, v0
	v_mov_b32_e32 v74, v0
	v_mov_b32_e32 v75, v0
	v_mov_b32_e32 v76, v0
	v_mov_b32_e32 v77, v0
	v_mov_b32_e32 v78, v0
	v_mov_b32_e32 v79, v0
	v_mov_b32_e32 v80, v0
	v_mov_b32_e32 v81, v0
	v_mov_b32_e32 v82, v0
	v_mov_b32_e32 v83, v0
	v_mov_b32_e32 v84, v0
	v_mov_b32_e32 v85, v0
	v_mov_b32_e32 v86, v0
	v_mov_b32_e32 v87, v0
	v_mov_b32_e32 v88, v0
	v_mov_b32_e32 v89, v0
	v_mov_b32_e32 v90, v0
	v_mov_b32_e32 v91, v0
	v_mov_b32_e32 v92, v0
	v_mov_b32_e32 v93, v0
	v_mov_b32_e32 v94, v0
	v_mov_b32_e32 v95, v0
	v_mov_b32_e32 v96, v0
	v_mov_b32_e32 v97, v0
	v_mov_b32_e32 v98, v0
	v_mov_b32_e32 v99, v0
	v_mov_b32_e32 v100, v0
	v_mov_b32_e32 v101, v0
	v_mov_b32_e32 v102, v0
	v_mov_b32_e32 v103, v0
	v_mov_b32_e32 v104, v0
	v_mov_b32_e32 v105, v0
	v_mov_b32_e32 v106, v0
	v_mov_b32_e32 v107, v0
	v_mov_b32_e32 v108, v0
	v_mov_b32_e32 v109, v0
	v_mov_b32_e32 v110, v0
	v_mov_b32_e32 v111, v0
	v_mov_b32_e32 v112, v0
	v_mov_b32_e32 v113, v0
	v_mov_b32_e32 v114, v0
	v_mov_b32_e32 v115, v0
	v_mov_b32_e32 v116, v0
	v_mov_b32_e32 v117, v0
	v_mov_b32_e32 v118, v0
	v_mov_b32_e32 v119, v0
	v_mov_b32_e32 v120, v0
	v_mov_b32_e32 v121, v0
	v_mov_b32_e32 v122, v0
	v_mov_b32_e32 v123, v0
	v_mov_b32_e32 v124, v0
	v_mov_b32_e32 v125, v0
	v_mov_b32_e32 v126, v0
	v_mov_b32_e32 v127, v0
	s_cbranch_vccnz .Llate_p7_done
	s_barrier
.Llate_p7_done:
.LBB0_463:
	ds_read_b128 v[128:131], v225
	ds_read_b128 v[132:135], v225 offset:2048
	ds_read_b128 v[136:139], v226
	ds_read_b128 v[140:143], v226 offset:2048
	v_lshl_add_u64 v[192:193], s[50:51], 0, v[218:219]
	s_mov_b32 m0, s64
	v_lshl_add_u64 v[176:177], v[192:193], 0, s[18:19]
	ds_read_b128 v[144:147], v227
	ds_read_b128 v[148:151], v227 offset:2048
	ds_read_b128 v[152:155], v228
	ds_read_b128 v[156:159], v228 offset:2048
	ds_read_b128 v[160:163], v227 offset:4096
	ds_read_b128 v[164:167], v227 offset:6144
	ds_read_b128 v[168:171], v228 offset:4096
	ds_read_b128 v[172:175], v228 offset:6144
	global_load_lds_dwordx4 v[176:177], off
	v_lshl_add_u64 v[176:177], v[192:193], 0, s[20:21]
	s_mov_b32 m0, s65
	s_nop 0
	global_load_lds_dwordx4 v[176:177], off
	s_waitcnt lgkmcnt(8)
	s_barrier
	s_waitcnt lgkmcnt(0)
	s_setprio 1
	s_waitcnt lgkmcnt(0)
	v_mfma_f32_16x16x32_bf16 v[124:127], v[128:131], v[144:147], v[124:127]
	v_mfma_f32_16x16x32_bf16 v[120:123], v[132:135], v[144:147], v[120:123]
	v_mfma_f32_16x16x32_bf16 v[116:119], v[128:131], v[148:151], v[116:119]
	v_mfma_f32_16x16x32_bf16 v[112:115], v[132:135], v[148:151], v[112:115]
	v_mfma_f32_16x16x32_bf16 v[108:111], v[128:131], v[160:163], v[108:111]
	v_mfma_f32_16x16x32_bf16 v[104:107], v[132:135], v[160:163], v[104:107]
	v_mfma_f32_16x16x32_bf16 v[100:103], v[128:131], v[164:167], v[100:103]
	v_mfma_f32_16x16x32_bf16 v[96:99], v[132:135], v[164:167], v[96:99]
	v_mfma_f32_16x16x32_bf16 v[124:127], v[136:139], v[152:155], v[124:127]
	v_mfma_f32_16x16x32_bf16 v[120:123], v[140:143], v[152:155], v[120:123]
	v_mfma_f32_16x16x32_bf16 v[116:119], v[136:139], v[156:159], v[116:119]
	v_mfma_f32_16x16x32_bf16 v[112:115], v[140:143], v[156:159], v[112:115]
	v_mfma_f32_16x16x32_bf16 v[108:111], v[136:139], v[168:171], v[108:111]
	v_mfma_f32_16x16x32_bf16 v[104:107], v[140:143], v[168:171], v[104:107]
	v_mfma_f32_16x16x32_bf16 v[100:103], v[136:139], v[172:175], v[100:103]
	v_mfma_f32_16x16x32_bf16 v[96:99], v[140:143], v[172:175], v[96:99]
	s_setprio 0
	s_barrier
	v_lshl_add_u64 v[194:195], s[52:53], 0, v[218:219]
	s_mov_b32 m0, s34
	v_lshl_add_u64 v[196:197], v[194:195], 0, s[26:27]
	ds_read_b128 v[176:179], v229
	ds_read_b128 v[180:183], v229 offset:2048
	ds_read_b128 v[184:187], v232
	ds_read_b128 v[188:191], v232 offset:2048
	global_load_lds_dwordx4 v[196:197], off
	v_lshl_add_u64 v[196:197], v[194:195], 0, s[28:29]
	s_mov_b32 m0, s35
	s_nop 0
	global_load_lds_dwordx4 v[196:197], off
	s_barrier
	s_waitcnt lgkmcnt(0)
	s_setprio 1
	s_waitcnt lgkmcnt(0)
	v_mfma_f32_16x16x32_bf16 v[92:95], v[176:179], v[144:147], v[92:95]
	v_mfma_f32_16x16x32_bf16 v[88:91], v[180:183], v[144:147], v[88:91]
	v_mfma_f32_16x16x32_bf16 v[84:87], v[176:179], v[148:151], v[84:87]
	v_mfma_f32_16x16x32_bf16 v[80:83], v[180:183], v[148:151], v[80:83]
	v_mfma_f32_16x16x32_bf16 v[76:79], v[176:179], v[160:163], v[76:79]
	v_mfma_f32_16x16x32_bf16 v[72:75], v[180:183], v[160:163], v[72:75]
	v_mfma_f32_16x16x32_bf16 v[68:71], v[176:179], v[164:167], v[68:71]
	v_mfma_f32_16x16x32_bf16 v[64:67], v[180:183], v[164:167], v[64:67]
	v_mfma_f32_16x16x32_bf16 v[92:95], v[184:187], v[152:155], v[92:95]
	v_mfma_f32_16x16x32_bf16 v[88:91], v[188:191], v[152:155], v[88:91]
	v_mfma_f32_16x16x32_bf16 v[84:87], v[184:187], v[156:159], v[84:87]
	v_mfma_f32_16x16x32_bf16 v[80:83], v[188:191], v[156:159], v[80:83]
	v_mfma_f32_16x16x32_bf16 v[76:79], v[184:187], v[168:171], v[76:79]
	v_mfma_f32_16x16x32_bf16 v[72:75], v[188:191], v[168:171], v[72:75]
	v_mfma_f32_16x16x32_bf16 v[68:71], v[184:187], v[172:175], v[68:71]
	v_mfma_f32_16x16x32_bf16 v[64:67], v[188:191], v[172:175], v[64:67]
	s_setprio 0
	s_mov_b32 m0, s33
	v_lshl_add_u64 v[196:197], v[192:193], 0, s[26:27]
	s_barrier
	ds_read_b128 v[144:147], v227 offset:16384
	ds_read_b128 v[148:151], v227 offset:18432
	ds_read_b128 v[152:155], v228 offset:16384
	ds_read_b128 v[156:159], v228 offset:18432
	ds_read_b128 v[160:163], v227 offset:20480
	ds_read_b128 v[164:167], v227 offset:22528
	ds_read_b128 v[168:171], v228 offset:20480
	ds_read_b128 v[172:175], v228 offset:22528
	global_load_lds_dwordx4 v[196:197], off
	v_lshl_add_u64 v[196:197], v[192:193], 0, s[28:29]
	s_mov_b32 m0, s42
	s_nop 0
	global_load_lds_dwordx4 v[196:197], off
	s_barrier
	s_waitcnt lgkmcnt(0)
	s_setprio 1
	s_waitcnt lgkmcnt(0)
	v_mfma_f32_16x16x32_bf16 v[60:63], v[128:131], v[144:147], v[60:63]
	v_mfma_f32_16x16x32_bf16 v[56:59], v[132:135], v[144:147], v[56:59]
	v_mfma_f32_16x16x32_bf16 v[52:55], v[128:131], v[148:151], v[52:55]
	v_mfma_f32_16x16x32_bf16 v[48:51], v[132:135], v[148:151], v[48:51]
	v_mfma_f32_16x16x32_bf16 v[44:47], v[128:131], v[160:163], v[44:47]
	v_mfma_f32_16x16x32_bf16 v[40:43], v[132:135], v[160:163], v[40:43]
	v_mfma_f32_16x16x32_bf16 v[36:39], v[128:131], v[164:167], v[36:39]
	v_mfma_f32_16x16x32_bf16 v[32:35], v[132:135], v[164:167], v[32:35]
	v_mfma_f32_16x16x32_bf16 v[60:63], v[136:139], v[152:155], v[60:63]
	v_mfma_f32_16x16x32_bf16 v[56:59], v[140:143], v[152:155], v[56:59]
	v_mfma_f32_16x16x32_bf16 v[52:55], v[136:139], v[156:159], v[52:55]
	v_mfma_f32_16x16x32_bf16 v[48:51], v[140:143], v[156:159], v[48:51]
	v_mfma_f32_16x16x32_bf16 v[44:47], v[136:139], v[168:171], v[44:47]
	v_mfma_f32_16x16x32_bf16 v[40:43], v[140:143], v[168:171], v[40:43]
	v_mfma_f32_16x16x32_bf16 v[36:39], v[136:139], v[172:175], v[36:39]
	v_mfma_f32_16x16x32_bf16 v[32:35], v[140:143], v[172:175], v[32:35]
	s_setprio 0
	s_barrier
	v_lshl_add_u64 v[196:197], s[2:3], 0, v[218:219]
	s_mov_b32 m0, s43
	v_lshl_add_u64 v[128:129], v[196:197], 0, s[26:27]
	global_load_lds_dwordx4 v[128:129], off
	v_lshl_add_u64 v[128:129], v[196:197], 0, s[28:29]
	s_mov_b32 m0, s44
	s_nop 0
	global_load_lds_dwordx4 v[128:129], off
	s_waitcnt vmcnt(6)
	s_barrier
	s_setprio 1
	v_mfma_f32_16x16x32_bf16 v[28:31], v[176:179], v[144:147], v[28:31]
	v_mfma_f32_16x16x32_bf16 v[24:27], v[180:183], v[144:147], v[24:27]
	v_mfma_f32_16x16x32_bf16 v[20:23], v[176:179], v[148:151], v[20:23]
	v_mfma_f32_16x16x32_bf16 v[16:19], v[180:183], v[148:151], v[16:19]
	v_mfma_f32_16x16x32_bf16 v[12:15], v[176:179], v[160:163], v[12:15]
	v_mfma_f32_16x16x32_bf16 v[8:11], v[180:183], v[160:163], v[8:11]
	v_mfma_f32_16x16x32_bf16 v[4:7], v[176:179], v[164:167], v[4:7]
	v_mfma_f32_16x16x32_bf16 v[0:3], v[180:183], v[164:167], v[0:3]
	v_mfma_f32_16x16x32_bf16 v[28:31], v[184:187], v[152:155], v[28:31]
	v_mfma_f32_16x16x32_bf16 v[24:27], v[188:191], v[152:155], v[24:27]
	v_mfma_f32_16x16x32_bf16 v[20:23], v[184:187], v[156:159], v[20:23]
	v_mfma_f32_16x16x32_bf16 v[16:19], v[188:191], v[156:159], v[16:19]
	v_mfma_f32_16x16x32_bf16 v[12:15], v[184:187], v[168:171], v[12:15]
	v_mfma_f32_16x16x32_bf16 v[8:11], v[188:191], v[168:171], v[8:11]
	v_mfma_f32_16x16x32_bf16 v[4:7], v[184:187], v[172:175], v[4:7]
	v_mfma_f32_16x16x32_bf16 v[0:3], v[188:191], v[172:175], v[0:3]
	s_setprio 0
	s_barrier
	ds_read_b128 v[128:131], v233
	ds_read_b128 v[132:135], v233 offset:2048
	ds_read_b128 v[136:139], v234
	ds_read_b128 v[140:143], v234 offset:2048
	s_mov_b32 m0, s45
	v_lshl_add_u64 v[176:177], v[192:193], 0, s[30:31]
	ds_read_b128 v[144:147], v227 offset:32768
	ds_read_b128 v[148:151], v227 offset:34816
	ds_read_b128 v[152:155], v228 offset:32768
	ds_read_b128 v[156:159], v228 offset:34816
	ds_read_b128 v[160:163], v227 offset:36864
	ds_read_b128 v[164:167], v227 offset:38912
	ds_read_b128 v[168:171], v228 offset:36864
	ds_read_b128 v[172:175], v228 offset:38912
	global_load_lds_dwordx4 v[176:177], off
	v_lshl_add_u64 v[176:177], v[192:193], 0, s[36:37]
	s_mov_b32 m0, s54
	s_nop 0
	global_load_lds_dwordx4 v[176:177], off
	s_waitcnt lgkmcnt(8)
	s_barrier
	s_waitcnt lgkmcnt(0)
	s_setprio 1
	s_waitcnt lgkmcnt(0)
	v_mfma_f32_16x16x32_bf16 v[124:127], v[128:131], v[144:147], v[124:127]
	v_mfma_f32_16x16x32_bf16 v[120:123], v[132:135], v[144:147], v[120:123]
	v_mfma_f32_16x16x32_bf16 v[116:119], v[128:131], v[148:151], v[116:119]
	v_mfma_f32_16x16x32_bf16 v[112:115], v[132:135], v[148:151], v[112:115]
	v_mfma_f32_16x16x32_bf16 v[108:111], v[128:131], v[160:163], v[108:111]
	v_mfma_f32_16x16x32_bf16 v[104:107], v[132:135], v[160:163], v[104:107]
	v_mfma_f32_16x16x32_bf16 v[100:103], v[128:131], v[164:167], v[100:103]
	v_mfma_f32_16x16x32_bf16 v[96:99], v[132:135], v[164:167], v[96:99]
	v_mfma_f32_16x16x32_bf16 v[124:127], v[136:139], v[152:155], v[124:127]
	v_mfma_f32_16x16x32_bf16 v[120:123], v[140:143], v[152:155], v[120:123]
	v_mfma_f32_16x16x32_bf16 v[116:119], v[136:139], v[156:159], v[116:119]
	v_mfma_f32_16x16x32_bf16 v[112:115], v[140:143], v[156:159], v[112:115]
	v_mfma_f32_16x16x32_bf16 v[108:111], v[136:139], v[168:171], v[108:111]
	v_mfma_f32_16x16x32_bf16 v[104:107], v[140:143], v[168:171], v[104:107]
	v_mfma_f32_16x16x32_bf16 v[100:103], v[136:139], v[172:175], v[100:103]
	v_mfma_f32_16x16x32_bf16 v[96:99], v[140:143], v[172:175], v[96:99]
	s_setprio 0
	s_barrier
	s_mov_b32 m0, s55
	v_lshl_add_u64 v[198:199], v[194:195], 0, s[38:39]
	ds_read_b128 v[176:179], v235
	ds_read_b128 v[180:183], v235 offset:2048
	ds_read_b128 v[184:187], v236
	ds_read_b128 v[188:191], v236 offset:2048
	global_load_lds_dwordx4 v[198:199], off
	v_lshl_add_u64 v[194:195], v[194:195], 0, s[40:41]
	s_mov_b32 m0, s58
	s_nop 0
	global_load_lds_dwordx4 v[194:195], off
	s_barrier
	s_waitcnt lgkmcnt(0)
	s_setprio 1
	s_waitcnt lgkmcnt(0)
	v_mfma_f32_16x16x32_bf16 v[92:95], v[176:179], v[144:147], v[92:95]
	v_mfma_f32_16x16x32_bf16 v[88:91], v[180:183], v[144:147], v[88:91]
	v_mfma_f32_16x16x32_bf16 v[84:87], v[176:179], v[148:151], v[84:87]
	v_mfma_f32_16x16x32_bf16 v[80:83], v[180:183], v[148:151], v[80:83]
	v_mfma_f32_16x16x32_bf16 v[76:79], v[176:179], v[160:163], v[76:79]
	v_mfma_f32_16x16x32_bf16 v[72:75], v[180:183], v[160:163], v[72:75]
	v_mfma_f32_16x16x32_bf16 v[68:71], v[176:179], v[164:167], v[68:71]
	v_mfma_f32_16x16x32_bf16 v[64:67], v[180:183], v[164:167], v[64:67]
	v_mfma_f32_16x16x32_bf16 v[92:95], v[184:187], v[152:155], v[92:95]
	v_mfma_f32_16x16x32_bf16 v[88:91], v[188:191], v[152:155], v[88:91]
	v_mfma_f32_16x16x32_bf16 v[84:87], v[184:187], v[156:159], v[84:87]
	v_mfma_f32_16x16x32_bf16 v[80:83], v[188:191], v[156:159], v[80:83]
	v_mfma_f32_16x16x32_bf16 v[76:79], v[184:187], v[168:171], v[76:79]
	v_mfma_f32_16x16x32_bf16 v[72:75], v[188:191], v[168:171], v[72:75]
	v_mfma_f32_16x16x32_bf16 v[68:71], v[184:187], v[172:175], v[68:71]
	v_mfma_f32_16x16x32_bf16 v[64:67], v[188:191], v[172:175], v[64:67]
	s_setprio 0
	s_mov_b32 m0, s59
	v_lshl_add_u64 v[194:195], v[192:193], 0, s[38:39]
	s_barrier
	ds_read_b128 v[144:147], v227 offset:49152
	ds_read_b128 v[148:151], v227 offset:51200
	ds_read_b128 v[152:155], v228 offset:49152
	ds_read_b128 v[156:159], v228 offset:51200
	ds_read_b128 v[160:163], v227 offset:53248
	ds_read_b128 v[164:167], v227 offset:55296
	ds_read_b128 v[168:171], v228 offset:53248
	ds_read_b128 v[172:175], v228 offset:55296
	global_load_lds_dwordx4 v[194:195], off
	v_lshl_add_u64 v[192:193], v[192:193], 0, s[40:41]
	s_mov_b32 m0, s60
	s_nop 0
	global_load_lds_dwordx4 v[192:193], off
	s_barrier
	s_waitcnt lgkmcnt(0)
	s_setprio 1
	s_waitcnt lgkmcnt(0)
	v_mfma_f32_16x16x32_bf16 v[60:63], v[128:131], v[144:147], v[60:63]
	v_mfma_f32_16x16x32_bf16 v[56:59], v[132:135], v[144:147], v[56:59]
	v_mfma_f32_16x16x32_bf16 v[52:55], v[128:131], v[148:151], v[52:55]
	v_mfma_f32_16x16x32_bf16 v[48:51], v[132:135], v[148:151], v[48:51]
	v_mfma_f32_16x16x32_bf16 v[44:47], v[128:131], v[160:163], v[44:47]
	v_mfma_f32_16x16x32_bf16 v[40:43], v[132:135], v[160:163], v[40:43]
	v_mfma_f32_16x16x32_bf16 v[36:39], v[128:131], v[164:167], v[36:39]
	v_mfma_f32_16x16x32_bf16 v[32:35], v[132:135], v[164:167], v[32:35]
	v_mfma_f32_16x16x32_bf16 v[60:63], v[136:139], v[152:155], v[60:63]
	v_mfma_f32_16x16x32_bf16 v[56:59], v[140:143], v[152:155], v[56:59]
	v_mfma_f32_16x16x32_bf16 v[52:55], v[136:139], v[156:159], v[52:55]
	v_mfma_f32_16x16x32_bf16 v[48:51], v[140:143], v[156:159], v[48:51]
	v_mfma_f32_16x16x32_bf16 v[44:47], v[136:139], v[168:171], v[44:47]
	v_mfma_f32_16x16x32_bf16 v[40:43], v[140:143], v[168:171], v[40:43]
	v_mfma_f32_16x16x32_bf16 v[36:39], v[136:139], v[172:175], v[36:39]
	v_mfma_f32_16x16x32_bf16 v[32:35], v[140:143], v[172:175], v[32:35]
	s_setprio 0
	s_barrier
	s_mov_b32 m0, s61
	v_lshl_add_u64 v[128:129], v[196:197], 0, s[38:39]
	global_load_lds_dwordx4 v[128:129], off
	v_lshl_add_u64 v[128:129], v[196:197], 0, s[40:41]
	s_mov_b32 m0, s62
	s_nop 0
	global_load_lds_dwordx4 v[128:129], off
	s_waitcnt vmcnt(6)
	s_barrier
; #define LDA(dst,b,h) _Pragma("unroll") for(int m=0;m<4;++m) _Pragma("unroll") for(int k=0;k<2;++k) \
;     dst[m][k]=*reinterpret_cast<const bf16x8*>(SA(b,h)+(wr*64+m*16)*128+koff[k])
; #define LDB(dst,b,h) _Pragma("unroll") for(int n=0;n<2;++n) _Pragma("unroll") for(int k=0;k<2;++k) \
;     dst[n][k]=*reinterpret_cast<const bf16x8*>(SB(b,h)+(wc*32+n*16)*128+koff[k])
; #define MMA(ai,bj,Af,Bf) do{__builtin_amdgcn_s_setprio(1); \
;     _Pragma("unroll") for(int m=0;m<4;++m) _Pragma("unroll") for(int n=0;n<2;++n) _Pragma("unroll") for(int k=0;k<2;++k) \
;       acc[ai][bj][m][n]=__builtin_amdgcn_mfma_f32_16x16x32_bf16(Bf[n][k],Af[m][k],acc[ai][bj][m][n],0,0,0); \
;     __builtin_amdgcn_s_setprio(0);}while(0)
; #define WAIT_L(n) asm volatile("s_waitcnt lgkmcnt(" #n ")":::"memory")
; #define BAR __builtin_amdgcn_s_barrier()
; #define SCHED __builtin_amdgcn_sched_barrier(0)
; template <int K, int EPI, bool MIX = false>
; __device__ __forceinline__ void gemm_phase(const Params& p, const u16* __restrict__ A, const u16* __restrict__ Bt,
;                            const float* __restrict__ rs_in, float* __restrict__ ssq_out, float alpha, bool rev = false) {
;     ...
;       for (int t = 0; t < nt - 2; t += 2) KBODY(t);
;     }
;     ...
;     const int cpm = pm, cpn = pn;
;     float rsq[2][4];
;     if constexpr (EPI == EPI_SWIGLU || EPI == EPI_Z || MIX) {
;       const float* rsrc = MIX ? p.ssqb : rs_in;
;       int fr_p = fr;
;       asm volatile("" : "+v"(fr_p));
; #pragma unroll
;       for (int ai = 0; ai < 2; ++ai)
; #pragma unroll
;         for (int m = 0; m < 4; ++m) rsq[ai][m] = rsrc[cpm * 256 + ai * 128 + wr * 64 + m * 16 + fr_p];
;     }
;     ++it;
;     id = item_id(it);
;     const bool more = id < ntiles;
;     if (rev) id = ntiles - 1 - id;
;     {
;       LDB(B0,0,0); SCHED; LDA(At,0,0); STAGE_A(1,1,nt-1);
;       WAIT_L(8); BAR; WAIT_L(0); MMA(0,0,At,B0); BAR; SCHED;
;       if (more) SETUP_TILE();
;       LDB(B1,0,1); if (more) STAGE_B(0,0,0);
;       BAR; WAIT_L(0); MMA(0,1,At,B1); BAR;
;       LDA(At,0,1); if (more) STAGE_A(0,0,0);
	s_setprio 1
	v_mfma_f32_16x16x32_bf16 v[28:31], v[176:179], v[144:147], v[28:31]
	v_mfma_f32_16x16x32_bf16 v[24:27], v[180:183], v[144:147], v[24:27]
	v_mfma_f32_16x16x32_bf16 v[20:23], v[176:179], v[148:151], v[20:23]
	v_mfma_f32_16x16x32_bf16 v[16:19], v[180:183], v[148:151], v[16:19]
	v_mfma_f32_16x16x32_bf16 v[12:15], v[176:179], v[160:163], v[12:15]
	v_mfma_f32_16x16x32_bf16 v[8:11], v[180:183], v[160:163], v[8:11]
	v_mfma_f32_16x16x32_bf16 v[4:7], v[176:179], v[164:167], v[4:7]
	v_mfma_f32_16x16x32_bf16 v[0:3], v[180:183], v[164:167], v[0:3]
	v_mfma_f32_16x16x32_bf16 v[28:31], v[184:187], v[152:155], v[28:31]
	v_mfma_f32_16x16x32_bf16 v[24:27], v[188:191], v[152:155], v[24:27]
	v_mfma_f32_16x16x32_bf16 v[20:23], v[184:187], v[156:159], v[20:23]
	v_mfma_f32_16x16x32_bf16 v[16:19], v[188:191], v[156:159], v[16:19]
	v_mfma_f32_16x16x32_bf16 v[12:15], v[184:187], v[168:171], v[12:15]
	v_mfma_f32_16x16x32_bf16 v[8:11], v[188:191], v[168:171], v[8:11]
	v_mfma_f32_16x16x32_bf16 v[4:7], v[184:187], v[172:175], v[4:7]
	v_mfma_f32_16x16x32_bf16 v[0:3], v[188:191], v[172:175], v[0:3]
	s_setprio 0
	s_add_i32 s67, s67, 2
	s_add_u32 s52, s52, 0x8000
	s_addc_u32 s53, s53, 0
	s_add_u32 s50, s50, 0x8000
	s_addc_u32 s51, s51, 0
	s_add_u32 s2, s2, 0x8000
	s_addc_u32 s3, s3, 0
	s_cmpk_lt_u32 s67, 0x54
	s_barrier
	s_cbranch_scc1 .LBB0_463
	ds_read_b128 v[144:147], v225
	ds_read_b128 v[148:151], v225 offset:2048
	ds_read_b128 v[156:159], v226
	ds_read_b128 v[152:155], v226 offset:2048
	s_add_i32 s66, s66, 1
	s_mul_i32 s2, s66, s76
	s_add_i32 s2, s2, s77
	s_cmpk_lt_i32 s2, 0x600
	s_cselect_b64 s[50:51], -1, 0
	s_cmpk_gt_i32 s2, 0x5ff
	v_lshl_add_u64 v[128:129], s[4:5], 0, v[216:217]
	s_mov_b32 m0, s64
	v_lshl_add_u64 v[130:131], v[128:129], 0, s[46:47]
	ds_read_b128 v[160:163], v227
	ds_read_b128 v[164:167], v227 offset:2048
	ds_read_b128 v[188:191], v228
	ds_read_b128 v[180:183], v228 offset:2048
	ds_read_b128 v[168:171], v227 offset:4096
	ds_read_b128 v[172:175], v227 offset:6144
	ds_read_b128 v[184:187], v228 offset:4096
	ds_read_b128 v[176:179], v228 offset:6144
	global_load_lds_dwordx4 v[130:131], off
	v_lshl_add_u64 v[128:129], v[128:129], 0, s[48:49]
	s_mov_b32 m0, s65
	s_nop 0
	global_load_lds_dwordx4 v[128:129], off
	s_waitcnt lgkmcnt(8)
	s_barrier
	s_waitcnt lgkmcnt(0)
	s_setprio 1
	s_waitcnt lgkmcnt(0)
	v_mfma_f32_16x16x32_bf16 v[124:127], v[144:147], v[160:163], v[124:127]
	v_mfma_f32_16x16x32_bf16 v[120:123], v[148:151], v[160:163], v[120:123]
	v_mfma_f32_16x16x32_bf16 v[116:119], v[144:147], v[164:167], v[116:119]
	v_mfma_f32_16x16x32_bf16 v[112:115], v[148:151], v[164:167], v[112:115]
	v_mfma_f32_16x16x32_bf16 v[108:111], v[144:147], v[168:171], v[108:111]
	v_mfma_f32_16x16x32_bf16 v[104:107], v[148:151], v[168:171], v[104:107]
	v_mfma_f32_16x16x32_bf16 v[100:103], v[144:147], v[172:175], v[100:103]
	v_mfma_f32_16x16x32_bf16 v[96:99], v[148:151], v[172:175], v[96:99]
	v_mfma_f32_16x16x32_bf16 v[124:127], v[156:159], v[188:191], v[124:127]
	v_mfma_f32_16x16x32_bf16 v[120:123], v[152:155], v[188:191], v[120:123]
	v_mfma_f32_16x16x32_bf16 v[128:131], v[156:159], v[180:183], v[116:119]
	v_mfma_f32_16x16x32_bf16 v[132:135], v[152:155], v[180:183], v[112:115]
	v_mfma_f32_16x16x32_bf16 v[108:111], v[156:159], v[184:187], v[108:111]
	v_mfma_f32_16x16x32_bf16 v[104:107], v[152:155], v[184:187], v[104:107]
	v_mfma_f32_16x16x32_bf16 v[136:139], v[156:159], v[176:179], v[100:103]
	v_mfma_f32_16x16x32_bf16 v[140:143], v[152:155], v[176:179], v[96:99]
	s_setprio 0
	s_barrier
	s_mov_b32 s67, s69
	s_mov_b32 s68, s70
	s_cbranch_scc1 .LBB0_466
	s_sub_i32 s2, 0x5ff, s2
	s_lshr_b32 s3, s2, 3
	s_and_b32 s3, s3, 0x1ffffff8
	s_lshl_b32 s4, s3, 3
	s_sub_i32 s4, s2, s4
	s_and_b32 s2, s2, 7
	s_or_b32 s68, s3, s2
	s_ashr_i32 s67, s4, 3
	s_lshl_b32 s2, s68, 1
	s_mul_i32 s3, s68, 0x2c0000
	v_readlane_b32 s76, v254, 32
	s_mul_hi_u32 s2, s2, 0x160000
	s_add_u32 s4, s92, s3
	v_readlane_b32 s80, v254, 36
	v_readlane_b32 s81, v254, 37
	s_addc_u32 s5, s93, s2
	s_lshl_b32 s2, s67, 1
	s_mul_i32 s3, s67, 0x2c0000
	s_mov_b64 s[8:9], s[80:81]
	s_mul_hi_i32 s2, s2, 0x160000
	s_add_u32 s8, s8, s3
	v_readlane_b32 s84, v254, 40
	v_readlane_b32 s85, v254, 41
	v_readlane_b32 s86, v254, 42
	v_readlane_b32 s87, v254, 43
	v_readlane_b32 s88, v254, 44
	v_readlane_b32 s89, v254, 45
	v_readlane_b32 s90, v254, 46
	v_readlane_b32 s91, v254, 47
	s_addc_u32 s9, s9, s2
	v_readlane_b32 s77, v254, 33
	v_readlane_b32 s84, v254, 0
	s_add_u32 s10, s8, 0x160000
	s_mov_b32 s76, s57
	s_mov_b32 s77, s56
	v_readlane_b32 s85, v254, 1
	v_readlane_b32 s90, v254, 6
	v_readlane_b32 s91, v254, 7
	s_addc_u32 s11, s9, 0
	v_readlane_b32 s78, v254, 34
	v_readlane_b32 s79, v254, 35
	v_readlane_b32 s82, v254, 38
	v_readlane_b32 s83, v254, 39
	v_readlane_b32 s86, v254, 2
	v_readlane_b32 s87, v254, 3
	v_readlane_b32 s88, v254, 4
	v_readlane_b32 s89, v254, 5

; __global__ void __launch_bounds__(NTHR) fwd_megakernel(Params p) {
;     ...
;   run_phase<7>(p); grid.sync();
.LBB0_503:
	s_waitcnt vmcnt(0) lgkmcnt(0)
	s_barrier
	s_mov_b64 s[0:1], exec
	v_readlane_b32 s2, v255, 1
	v_readlane_b32 s3, v255, 2
	s_and_b64 s[2:3], s[0:1], s[2:3]
	s_mov_b64 exec, s[2:3]
	s_cbranch_execz .LBB0_513
	buffer_wbl2 sc1
	s_waitcnt vmcnt(0)
	s_load_dwordx2 s[2:3], s[72:73], 0x58
	v_mov_b32_e32 v2, 0
	s_mov_b64 s[4:5], exec
	v_mbcnt_lo_u32_b32 v1, s4, 0
	v_mbcnt_hi_u32_b32 v1, s5, v1
	s_waitcnt lgkmcnt(0)
	global_load_dword v0, v2, s[2:3] offset:40
	v_cmp_eq_u32_e32 vcc, 0, v1
	s_and_saveexec_b64 s[6:7], vcc
	s_cbranch_execz .LBB0_506
	s_bcnt1_i32_b64 s4, s[4:5]
	v_mov_b32_e32 v3, s4
	global_atomic_add v3, v2, v3, s[2:3] offset:32 sc0
